# K-loop segment-edge rotation: setprio raise before the opening barrier, drop after the closing barrier, half-unit skip test ahead of the barrier
# speedup vs baseline: 1.0010x; 1.0010x over previous
.LBB0_153:
	ds_read_b128 v[0:3], v145
	ds_read_b128 v[4:7], v145 offset:1024
	ds_read_b128 v[8:11], v145 offset:2048
	ds_read_b128 v[12:15], v145 offset:3072
	ds_read_b128 v[16:19], v146
	ds_read_b128 v[20:23], v146 offset:1024
	ds_read_b128 v[24:27], v146 offset:2048
	ds_read_b128 v[28:31], v146 offset:3072
	s_ashr_i32 s37, s36, 31
	s_lshl_b64 s[46:47], s[36:37], 17
	s_add_u32 s46, s44, s46
	s_addc_u32 s47, s45, s47
	s_and_b64 s[48:49], s[4:5], exec
	s_cselect_b32 s59, s47, s53
	s_cselect_b32 s58, s46, s52
	s_ashr_i32 s35, s34, 31
	s_lshl_b64 s[48:49], s[34:35], 17
	s_add_u32 s48, s60, s48
	s_addc_u32 s49, s61, s49
	s_and_b64 s[56:57], s[4:5], exec
	s_cselect_b32 s57, s49, s55
	s_cselect_b32 s56, s48, s54
	s_add_u32 s80, s52, 0x10080
	s_addc_u32 s81, s53, 0
	s_add_i32 s83, s51, 0xc000
	v_lshl_add_u64 v[64:65], s[80:81], 0, v[128:129]
	s_mov_b32 m0, s83
	s_add_i32 s35, s51, 0xe000
	ds_read_b128 v[32:35], v147
	ds_read_b128 v[36:39], v147 offset:1024
	ds_read_b128 v[40:43], v147 offset:2048
	ds_read_b128 v[44:47], v147 offset:3072
	ds_read_b128 v[48:51], v147 offset:4096
	ds_read_b128 v[52:55], v147 offset:5120
	ds_read_b128 v[56:59], v147 offset:6144
	ds_read_b128 v[60:63], v147 offset:7168
	global_load_lds_dwordx4 v[64:65], off
	v_lshl_add_u64 v[64:65], s[80:81], 0, v[132:133]
	s_mov_b32 m0, s35
	s_nop 0
	global_load_lds_dwordx4 v[64:65], off
	s_waitcnt vmcnt(8)
	s_waitcnt lgkmcnt(0)
	s_setprio 1
	s_barrier
	v_mfma_f32_16x16x32_bf16 v[64:67], v[0:3], v[32:35], 0
	v_mfma_f32_16x16x32_bf16 v[68:71], v[8:11], v[32:35], 0
	v_mfma_f32_16x16x32_bf16 v[72:75], v[0:3], v[40:43], 0
	v_mfma_f32_16x16x32_bf16 v[76:79], v[8:11], v[40:43], 0
	v_mfma_f32_16x16x32_bf16 v[80:83], v[0:3], v[48:51], 0
	v_mfma_f32_16x16x32_bf16 v[84:87], v[8:11], v[48:51], 0
	v_mfma_f32_16x16x32_bf16 v[88:91], v[0:3], v[56:59], 0
	v_mfma_f32_16x16x32_bf16 v[92:95], v[8:11], v[56:59], 0
	v_mfma_f32_16x16x32_bf16 v[64:67], v[4:7], v[36:39], v[64:67]
	v_mfma_f32_16x16x32_bf16 v[68:71], v[12:15], v[36:39], v[68:71]
	v_mfma_f32_16x16x32_bf16 v[72:75], v[4:7], v[44:47], v[72:75]
	v_mfma_f32_16x16x32_bf16 v[76:79], v[12:15], v[44:47], v[76:79]
	v_mfma_f32_16x16x32_bf16 v[80:83], v[4:7], v[52:55], v[80:83]
	v_mfma_f32_16x16x32_bf16 v[84:87], v[12:15], v[52:55], v[84:87]
	v_mfma_f32_16x16x32_bf16 v[88:91], v[4:7], v[60:63], v[88:91]
	v_mfma_f32_16x16x32_bf16 v[92:95], v[12:15], v[60:63], v[92:95]
	v_mfma_f32_16x16x32_bf16 v[96:99], v[16:19], v[32:35], 0
	v_mfma_f32_16x16x32_bf16 v[32:35], v[24:27], v[32:35], 0
	v_mfma_f32_16x16x32_bf16 v[96:99], v[20:23], v[36:39], v[96:99]
	v_mfma_f32_16x16x32_bf16 v[32:35], v[28:31], v[36:39], v[32:35]
	v_mfma_f32_16x16x32_bf16 v[36:39], v[16:19], v[40:43], 0
	v_mfma_f32_16x16x32_bf16 v[40:43], v[24:27], v[40:43], 0
	v_mfma_f32_16x16x32_bf16 v[36:39], v[20:23], v[44:47], v[36:39]
	v_mfma_f32_16x16x32_bf16 v[40:43], v[28:31], v[44:47], v[40:43]
	v_mfma_f32_16x16x32_bf16 v[44:47], v[16:19], v[48:51], 0
	v_mfma_f32_16x16x32_bf16 v[48:51], v[24:27], v[48:51], 0
	v_mfma_f32_16x16x32_bf16 v[44:47], v[20:23], v[52:55], v[44:47]
	v_mfma_f32_16x16x32_bf16 v[48:51], v[28:31], v[52:55], v[48:51]
	v_mfma_f32_16x16x32_bf16 v[52:55], v[16:19], v[56:59], 0
	v_mfma_f32_16x16x32_bf16 v[56:59], v[24:27], v[56:59], 0
	v_mfma_f32_16x16x32_bf16 v[52:55], v[20:23], v[60:63], v[52:55]
	v_mfma_f32_16x16x32_bf16 v[56:59], v[28:31], v[60:63], v[56:59]
	s_barrier
	s_setprio 0
	s_add_i32 s81, s72, s62
	v_lshl_add_u64 v[140:141], s[54:55], 0, v[130:131]
	s_add_i32 s37, s81, 0x2000
	v_lshl_add_u64 v[148:149], v[140:141], 0, s[18:19]
	s_mov_b32 m0, s81
	v_lshl_add_u64 v[212:213], s[54:55], 0, v[134:135]
	s_add_u32 s84, s54, 0x10100
	ds_read_b128 v[60:63], v147 offset:16384
	ds_read_b128 v[100:103], v147 offset:17408
	ds_read_b128 v[104:107], v147 offset:18432
	ds_read_b128 v[108:111], v147 offset:19456
	ds_read_b128 v[112:115], v147 offset:20480
	ds_read_b128 v[116:119], v147 offset:21504
	ds_read_b128 v[120:123], v147 offset:22528
	ds_read_b128 v[124:127], v147 offset:23552
	global_load_lds_dwordx4 v[148:149], off
	v_lshl_add_u64 v[148:149], v[212:213], 0, s[18:19]
	s_mov_b32 m0, s37
	s_addc_u32 s85, s55, 0
	s_add_i32 s79, s73, s62
	global_load_lds_dwordx4 v[148:149], off
	v_lshl_add_u64 v[148:149], s[84:85], 0, v[130:131]
	s_mov_b32 m0, s79
	s_add_i32 s80, s79, 0x2000
	global_load_lds_dwordx4 v[148:149], off
	v_lshl_add_u64 v[148:149], s[84:85], 0, v[134:135]
	s_mov_b32 m0, s80
	v_lshl_add_u64 v[214:215], s[52:53], 0, v[128:129]
	global_load_lds_dwordx4 v[148:149], off
	v_lshl_add_u64 v[148:149], v[214:215], 0, s[18:19]
	s_mov_b32 m0, s51
	v_lshl_add_u64 v[216:217], s[52:53], 0, v[132:133]
	global_load_lds_dwordx4 v[148:149], off
	v_lshl_add_u64 v[148:149], v[216:217], 0, s[18:19]
	s_mov_b32 m0, s63
	s_nop 0
	global_load_lds_dwordx4 v[148:149], off
	s_waitcnt vmcnt(8)
	s_waitcnt lgkmcnt(0)
	s_setprio 1
	s_barrier
	v_mfma_f32_16x16x32_bf16 v[148:151], v[0:3], v[60:63], 0
	v_mfma_f32_16x16x32_bf16 v[156:159], v[0:3], v[104:107], 0
	v_mfma_f32_16x16x32_bf16 v[164:167], v[0:3], v[112:115], 0
	v_mfma_f32_16x16x32_bf16 v[0:3], v[0:3], v[120:123], 0
	v_mfma_f32_16x16x32_bf16 v[148:151], v[4:7], v[100:103], v[148:151]
	v_mfma_f32_16x16x32_bf16 v[156:159], v[4:7], v[108:111], v[156:159]
	v_mfma_f32_16x16x32_bf16 v[164:167], v[4:7], v[116:119], v[164:167]
	v_mfma_f32_16x16x32_bf16 v[0:3], v[4:7], v[124:127], v[0:3]
	v_mfma_f32_16x16x32_bf16 v[4:7], v[8:11], v[120:123], 0
	v_mfma_f32_16x16x32_bf16 v[152:155], v[8:11], v[60:63], 0
	v_mfma_f32_16x16x32_bf16 v[160:163], v[8:11], v[104:107], 0
	v_mfma_f32_16x16x32_bf16 v[168:171], v[8:11], v[112:115], 0
	v_mfma_f32_16x16x32_bf16 v[4:7], v[12:15], v[124:127], v[4:7]
	v_mfma_f32_16x16x32_bf16 v[152:155], v[12:15], v[100:103], v[152:155]
	v_mfma_f32_16x16x32_bf16 v[160:163], v[12:15], v[108:111], v[160:163]
	v_mfma_f32_16x16x32_bf16 v[168:171], v[12:15], v[116:119], v[168:171]
	v_mfma_f32_16x16x32_bf16 v[8:11], v[16:19], v[60:63], 0
	v_mfma_f32_16x16x32_bf16 v[12:15], v[24:27], v[60:63], 0
	v_mfma_f32_16x16x32_bf16 v[8:11], v[20:23], v[100:103], v[8:11]
	v_mfma_f32_16x16x32_bf16 v[12:15], v[28:31], v[100:103], v[12:15]
	v_mfma_f32_16x16x32_bf16 v[60:63], v[16:19], v[104:107], 0
	v_mfma_f32_16x16x32_bf16 v[100:103], v[24:27], v[104:107], 0
	v_mfma_f32_16x16x32_bf16 v[104:107], v[16:19], v[112:115], 0
	v_mfma_f32_16x16x32_bf16 v[16:19], v[16:19], v[120:123], 0
	v_mfma_f32_16x16x32_bf16 v[60:63], v[20:23], v[108:111], v[60:63]
	v_mfma_f32_16x16x32_bf16 v[100:103], v[28:31], v[108:111], v[100:103]
	v_mfma_f32_16x16x32_bf16 v[104:107], v[20:23], v[116:119], v[104:107]
	v_mfma_f32_16x16x32_bf16 v[108:111], v[24:27], v[112:115], 0
	v_mfma_f32_16x16x32_bf16 v[16:19], v[20:23], v[124:127], v[16:19]
	v_mfma_f32_16x16x32_bf16 v[20:23], v[24:27], v[120:123], 0
	v_mfma_f32_16x16x32_bf16 v[108:111], v[28:31], v[116:119], v[108:111]
	v_mfma_f32_16x16x32_bf16 v[20:23], v[28:31], v[124:127], v[20:23]
	s_barrier
	s_setprio 0
	s_add_i32 s82, 0, 0x18000
	s_add_i32 s88, 0, 0x1c000
	v_add_u32_e32 v228, s82, v143
	v_add_u32_e32 v236, s88, v143
	ds_read_b128 v[24:27], v228
	ds_read_b128 v[28:31], v228 offset:1024
	ds_read_b128 v[112:115], v228 offset:2048
	ds_read_b128 v[116:119], v228 offset:3072
	ds_read_b128 v[120:123], v236
	ds_read_b128 v[124:127], v236 offset:1024
	ds_read_b128 v[172:175], v236 offset:2048
	ds_read_b128 v[176:179], v236 offset:3072
	s_add_u32 s84, s52, 0x10100
	s_addc_u32 s85, s53, 0
	s_mov_b32 m0, s64
	v_lshl_add_u64 v[218:219], s[84:85], 0, v[128:129]
	ds_read_b128 v[180:183], v147 offset:32768
	ds_read_b128 v[184:187], v147 offset:33792
	ds_read_b128 v[188:191], v147 offset:34816
	ds_read_b128 v[192:195], v147 offset:35840
	ds_read_b128 v[196:199], v147 offset:36864
	ds_read_b128 v[200:203], v147 offset:37888
	ds_read_b128 v[204:207], v147 offset:38912
	ds_read_b128 v[208:211], v147 offset:39936
	global_load_lds_dwordx4 v[218:219], off
	v_lshl_add_u64 v[218:219], s[84:85], 0, v[132:133]
	s_mov_b32 m0, s65
	s_nop 0
	global_load_lds_dwordx4 v[218:219], off
	s_waitcnt vmcnt(8)
	s_waitcnt lgkmcnt(0)
	s_setprio 1
	s_barrier
	v_mfma_f32_16x16x32_bf16 v[64:67], v[24:27], v[180:183], v[64:67]
	v_mfma_f32_16x16x32_bf16 v[68:71], v[112:115], v[180:183], v[68:71]
	v_mfma_f32_16x16x32_bf16 v[72:75], v[24:27], v[188:191], v[72:75]
	v_mfma_f32_16x16x32_bf16 v[76:79], v[112:115], v[188:191], v[76:79]
	v_mfma_f32_16x16x32_bf16 v[80:83], v[24:27], v[196:199], v[80:83]
	v_mfma_f32_16x16x32_bf16 v[84:87], v[112:115], v[196:199], v[84:87]
	v_mfma_f32_16x16x32_bf16 v[88:91], v[24:27], v[204:207], v[88:91]
	v_mfma_f32_16x16x32_bf16 v[92:95], v[112:115], v[204:207], v[92:95]
	v_mfma_f32_16x16x32_bf16 v[64:67], v[28:31], v[184:187], v[64:67]
	v_mfma_f32_16x16x32_bf16 v[68:71], v[116:119], v[184:187], v[68:71]
	v_mfma_f32_16x16x32_bf16 v[72:75], v[28:31], v[192:195], v[72:75]
	v_mfma_f32_16x16x32_bf16 v[76:79], v[116:119], v[192:195], v[76:79]
	v_mfma_f32_16x16x32_bf16 v[80:83], v[28:31], v[200:203], v[80:83]
	v_mfma_f32_16x16x32_bf16 v[84:87], v[116:119], v[200:203], v[84:87]
	v_mfma_f32_16x16x32_bf16 v[88:91], v[28:31], v[208:211], v[88:91]
	v_mfma_f32_16x16x32_bf16 v[92:95], v[116:119], v[208:211], v[92:95]
	v_mfma_f32_16x16x32_bf16 v[96:99], v[120:123], v[180:183], v[96:99]
	v_mfma_f32_16x16x32_bf16 v[32:35], v[172:175], v[180:183], v[32:35]
	v_mfma_f32_16x16x32_bf16 v[36:39], v[120:123], v[188:191], v[36:39]
	v_mfma_f32_16x16x32_bf16 v[40:43], v[172:175], v[188:191], v[40:43]
	v_mfma_f32_16x16x32_bf16 v[44:47], v[120:123], v[196:199], v[44:47]
	v_mfma_f32_16x16x32_bf16 v[48:51], v[172:175], v[196:199], v[48:51]
	v_mfma_f32_16x16x32_bf16 v[52:55], v[120:123], v[204:207], v[52:55]
	v_mfma_f32_16x16x32_bf16 v[56:59], v[172:175], v[204:207], v[56:59]
	v_mfma_f32_16x16x32_bf16 v[96:99], v[124:127], v[184:187], v[96:99]
	v_mfma_f32_16x16x32_bf16 v[32:35], v[176:179], v[184:187], v[32:35]
	v_mfma_f32_16x16x32_bf16 v[36:39], v[124:127], v[192:195], v[36:39]
	v_mfma_f32_16x16x32_bf16 v[40:43], v[176:179], v[192:195], v[40:43]
	v_mfma_f32_16x16x32_bf16 v[44:47], v[124:127], v[200:203], v[44:47]
	v_mfma_f32_16x16x32_bf16 v[48:51], v[176:179], v[200:203], v[48:51]
	v_mfma_f32_16x16x32_bf16 v[52:55], v[124:127], v[208:211], v[52:55]
	v_mfma_f32_16x16x32_bf16 v[56:59], v[176:179], v[208:211], v[56:59]
	s_barrier
	s_setprio 0
	s_add_i32 s84, s82, s62
	s_add_i32 s82, s84, 0x2000
	v_lshl_add_u64 v[140:141], v[140:141], 0, s[20:21]
	s_mov_b32 m0, s84
	s_add_u32 s86, s54, 0x10180
	ds_read_b128 v[180:183], v147 offset:49152
	ds_read_b128 v[184:187], v147 offset:50176
	ds_read_b128 v[188:191], v147 offset:51200
	ds_read_b128 v[192:195], v147 offset:52224
	ds_read_b128 v[196:199], v147 offset:53248
	ds_read_b128 v[200:203], v147 offset:54272
	ds_read_b128 v[204:207], v147 offset:55296
	ds_read_b128 v[208:211], v147 offset:56320
	global_load_lds_dwordx4 v[140:141], off
	v_lshl_add_u64 v[140:141], v[212:213], 0, s[20:21]
	s_mov_b32 m0, s82
	s_addc_u32 s87, s55, 0
	s_add_i32 s54, s88, s62
	global_load_lds_dwordx4 v[140:141], off
	v_lshl_add_u64 v[140:141], s[86:87], 0, v[130:131]
	s_mov_b32 m0, s54
	s_add_i32 s55, s54, 0x2000
	global_load_lds_dwordx4 v[140:141], off
	v_lshl_add_u64 v[140:141], s[86:87], 0, v[134:135]
	s_mov_b32 m0, s55
	s_nop 0
	global_load_lds_dwordx4 v[140:141], off
	v_lshl_add_u64 v[140:141], v[214:215], 0, s[20:21]
	s_mov_b32 m0, s66
	s_nop 0
	global_load_lds_dwordx4 v[140:141], off
	v_lshl_add_u64 v[140:141], v[216:217], 0, s[20:21]
	s_mov_b32 m0, s67
	s_nop 0
	global_load_lds_dwordx4 v[140:141], off
	s_waitcnt vmcnt(8)
	s_waitcnt lgkmcnt(0)
	s_setprio 1
	s_barrier
	v_mfma_f32_16x16x32_bf16 v[0:3], v[24:27], v[204:207], v[0:3]
	v_mfma_f32_16x16x32_bf16 v[4:7], v[112:115], v[204:207], v[4:7]
	v_mfma_f32_16x16x32_bf16 v[148:151], v[24:27], v[180:183], v[148:151]
	v_mfma_f32_16x16x32_bf16 v[152:155], v[112:115], v[180:183], v[152:155]
	v_mfma_f32_16x16x32_bf16 v[156:159], v[24:27], v[188:191], v[156:159]
	v_mfma_f32_16x16x32_bf16 v[160:163], v[112:115], v[188:191], v[160:163]
	v_mfma_f32_16x16x32_bf16 v[164:167], v[24:27], v[196:199], v[164:167]
	v_mfma_f32_16x16x32_bf16 v[168:171], v[112:115], v[196:199], v[168:171]
	v_mfma_f32_16x16x32_bf16 v[0:3], v[28:31], v[208:211], v[0:3]
	v_mfma_f32_16x16x32_bf16 v[4:7], v[116:119], v[208:211], v[4:7]
	v_mfma_f32_16x16x32_bf16 v[148:151], v[28:31], v[184:187], v[148:151]
	v_mfma_f32_16x16x32_bf16 v[152:155], v[116:119], v[184:187], v[152:155]
	v_mfma_f32_16x16x32_bf16 v[156:159], v[28:31], v[192:195], v[156:159]
	v_mfma_f32_16x16x32_bf16 v[160:163], v[116:119], v[192:195], v[160:163]
	v_mfma_f32_16x16x32_bf16 v[164:167], v[28:31], v[200:203], v[164:167]
	v_mfma_f32_16x16x32_bf16 v[168:171], v[116:119], v[200:203], v[168:171]
	v_mfma_f32_16x16x32_bf16 v[8:11], v[120:123], v[180:183], v[8:11]
	v_mfma_f32_16x16x32_bf16 v[12:15], v[172:175], v[180:183], v[12:15]
	v_mfma_f32_16x16x32_bf16 v[24:27], v[120:123], v[188:191], v[60:63]
	v_mfma_f32_16x16x32_bf16 v[28:31], v[172:175], v[188:191], v[100:103]
	v_mfma_f32_16x16x32_bf16 v[60:63], v[120:123], v[196:199], v[104:107]
	v_mfma_f32_16x16x32_bf16 v[100:103], v[172:175], v[196:199], v[108:111]
	v_mfma_f32_16x16x32_bf16 v[16:19], v[120:123], v[204:207], v[16:19]
	v_mfma_f32_16x16x32_bf16 v[20:23], v[172:175], v[204:207], v[20:23]
	v_mfma_f32_16x16x32_bf16 v[8:11], v[124:127], v[184:187], v[8:11]
	v_mfma_f32_16x16x32_bf16 v[12:15], v[176:179], v[184:187], v[12:15]
	v_mfma_f32_16x16x32_bf16 v[24:27], v[124:127], v[192:195], v[24:27]
	v_mfma_f32_16x16x32_bf16 v[28:31], v[176:179], v[192:195], v[28:31]
	v_mfma_f32_16x16x32_bf16 v[60:63], v[124:127], v[200:203], v[60:63]
	v_mfma_f32_16x16x32_bf16 v[100:103], v[176:179], v[200:203], v[100:103]
	v_mfma_f32_16x16x32_bf16 v[16:19], v[124:127], v[208:211], v[16:19]
	v_mfma_f32_16x16x32_bf16 v[20:23], v[176:179], v[208:211], v[20:23]
	s_barrier
	s_setprio 0
	ds_read_b128 v[104:107], v145
	ds_read_b128 v[108:111], v145 offset:1024
	ds_read_b128 v[112:115], v145 offset:2048
	ds_read_b128 v[116:119], v145 offset:3072
	ds_read_b128 v[120:123], v146
	ds_read_b128 v[124:127], v146 offset:1024
	ds_read_b128 v[172:175], v146 offset:2048
	ds_read_b128 v[176:179], v146 offset:3072
	s_add_u32 s52, s52, 0x10180
	s_addc_u32 s53, s53, 0
	s_mov_b32 m0, s83
	v_lshl_add_u64 v[140:141], s[52:53], 0, v[128:129]
	ds_read_b128 v[180:183], v147
	ds_read_b128 v[184:187], v147 offset:1024
	ds_read_b128 v[188:191], v147 offset:2048
	ds_read_b128 v[192:195], v147 offset:3072
	ds_read_b128 v[196:199], v147 offset:4096
	ds_read_b128 v[200:203], v147 offset:5120
	ds_read_b128 v[204:207], v147 offset:6144
	ds_read_b128 v[208:211], v147 offset:7168
	global_load_lds_dwordx4 v[140:141], off
	v_lshl_add_u64 v[140:141], s[52:53], 0, v[132:133]
	s_mov_b32 m0, s35
	s_nop 0
	global_load_lds_dwordx4 v[140:141], off
	s_waitcnt vmcnt(8)
	s_waitcnt lgkmcnt(0)
	s_setprio 1
	s_barrier
	v_mfma_f32_16x16x32_bf16 v[88:91], v[104:107], v[204:207], v[88:91]
	v_mfma_f32_16x16x32_bf16 v[64:67], v[104:107], v[180:183], v[64:67]
	v_mfma_f32_16x16x32_bf16 v[68:71], v[112:115], v[180:183], v[68:71]
	v_mfma_f32_16x16x32_bf16 v[72:75], v[104:107], v[188:191], v[72:75]
	v_mfma_f32_16x16x32_bf16 v[76:79], v[112:115], v[188:191], v[76:79]
	v_mfma_f32_16x16x32_bf16 v[80:83], v[104:107], v[196:199], v[80:83]
	v_mfma_f32_16x16x32_bf16 v[84:87], v[112:115], v[196:199], v[84:87]
	v_mfma_f32_16x16x32_bf16 v[212:215], v[108:111], v[208:211], v[88:91]
	v_mfma_f32_16x16x32_bf16 v[88:91], v[112:115], v[204:207], v[92:95]
	v_mfma_f32_16x16x32_bf16 v[64:67], v[108:111], v[184:187], v[64:67]
	v_mfma_f32_16x16x32_bf16 v[68:71], v[116:119], v[184:187], v[68:71]
	v_mfma_f32_16x16x32_bf16 v[72:75], v[108:111], v[192:195], v[72:75]
	v_mfma_f32_16x16x32_bf16 v[76:79], v[116:119], v[192:195], v[76:79]
	v_mfma_f32_16x16x32_bf16 v[80:83], v[108:111], v[200:203], v[80:83]
	v_mfma_f32_16x16x32_bf16 v[84:87], v[116:119], v[200:203], v[84:87]
	v_mfma_f32_16x16x32_bf16 v[92:95], v[116:119], v[208:211], v[88:91]
	v_mfma_f32_16x16x32_bf16 v[48:51], v[172:175], v[196:199], v[48:51]
	v_mfma_f32_16x16x32_bf16 v[88:91], v[120:123], v[180:183], v[96:99]
	v_mfma_f32_16x16x32_bf16 v[32:35], v[172:175], v[180:183], v[32:35]
	v_mfma_f32_16x16x32_bf16 v[36:39], v[120:123], v[188:191], v[36:39]
	v_mfma_f32_16x16x32_bf16 v[40:43], v[172:175], v[188:191], v[40:43]
	v_mfma_f32_16x16x32_bf16 v[44:47], v[120:123], v[196:199], v[44:47]
	v_mfma_f32_16x16x32_bf16 v[180:183], v[176:179], v[200:203], v[48:51]
	v_mfma_f32_16x16x32_bf16 v[48:51], v[120:123], v[204:207], v[52:55]
	v_mfma_f32_16x16x32_bf16 v[32:35], v[176:179], v[184:187], v[32:35]
	v_mfma_f32_16x16x32_bf16 v[36:39], v[124:127], v[192:195], v[36:39]
	v_mfma_f32_16x16x32_bf16 v[40:43], v[176:179], v[192:195], v[40:43]
	v_mfma_f32_16x16x32_bf16 v[44:47], v[124:127], v[200:203], v[44:47]
	v_mfma_f32_16x16x32_bf16 v[52:55], v[124:127], v[208:211], v[48:51]
	v_mfma_f32_16x16x32_bf16 v[48:51], v[172:175], v[204:207], v[56:59]
	v_mfma_f32_16x16x32_bf16 v[220:223], v[124:127], v[184:187], v[88:91]
	v_mfma_f32_16x16x32_bf16 v[184:187], v[176:179], v[208:211], v[48:51]
	s_barrier
	s_setprio 0
	s_mov_b32 m0, s81
	v_lshl_add_u64 v[140:141], s[56:57], 0, v[130:131]
	s_add_u32 s52, s56, 0x10000
	s_nop 0
	ds_read_b128 v[48:51], v147 offset:16384
	ds_read_b128 v[56:59], v147 offset:17408
	ds_read_b128 v[88:91], v147 offset:18432
	ds_read_b128 v[96:99], v147 offset:19456
	ds_read_b128 v[188:191], v147 offset:20480
	ds_read_b128 v[192:195], v147 offset:21504
	ds_read_b128 v[196:199], v147 offset:22528
	ds_read_b128 v[200:203], v147 offset:23552
	global_load_lds_dwordx4 v[140:141], off
	v_lshl_add_u64 v[252:253], s[56:57], 0, v[134:135]
	s_mov_b32 m0, s37
	s_addc_u32 s53, s57, 0
	global_load_lds_dwordx4 v[252:253], off
	v_lshl_add_u64 v[204:205], s[52:53], 0, v[130:131]
	s_mov_b32 m0, s79
	v_lshl_add_u64 v[136:137], s[58:59], 0, v[128:129]
	global_load_lds_dwordx4 v[204:205], off
	v_lshl_add_u64 v[204:205], s[52:53], 0, v[134:135]
	s_mov_b32 m0, s80
	v_lshl_add_u64 v[138:139], s[58:59], 0, v[132:133]
	global_load_lds_dwordx4 v[204:205], off
	s_mov_b32 m0, s51
	s_nop 0
	global_load_lds_dwordx4 v[136:137], off
	s_mov_b32 m0, s63
	s_nop 0
	global_load_lds_dwordx4 v[138:139], off
	s_waitcnt vmcnt(8)
	s_waitcnt lgkmcnt(0)
	s_setprio 1
	s_barrier
	v_mfma_f32_16x16x32_bf16 v[0:3], v[104:107], v[196:199], v[0:3]
	v_mfma_f32_16x16x32_bf16 v[4:7], v[112:115], v[196:199], v[4:7]
	v_mfma_f32_16x16x32_bf16 v[148:151], v[104:107], v[48:51], v[148:151]
	v_mfma_f32_16x16x32_bf16 v[152:155], v[112:115], v[48:51], v[152:155]
	v_mfma_f32_16x16x32_bf16 v[156:159], v[104:107], v[88:91], v[156:159]
	v_mfma_f32_16x16x32_bf16 v[160:163], v[112:115], v[88:91], v[160:163]
	v_mfma_f32_16x16x32_bf16 v[164:167], v[104:107], v[188:191], v[164:167]
	v_mfma_f32_16x16x32_bf16 v[168:171], v[112:115], v[188:191], v[168:171]
	v_mfma_f32_16x16x32_bf16 v[0:3], v[108:111], v[200:203], v[0:3]
	v_mfma_f32_16x16x32_bf16 v[4:7], v[116:119], v[200:203], v[4:7]
	v_mfma_f32_16x16x32_bf16 v[148:151], v[108:111], v[56:59], v[148:151]
	v_mfma_f32_16x16x32_bf16 v[152:155], v[116:119], v[56:59], v[152:155]
	v_mfma_f32_16x16x32_bf16 v[156:159], v[108:111], v[96:99], v[156:159]
	v_mfma_f32_16x16x32_bf16 v[160:163], v[116:119], v[96:99], v[160:163]
	v_mfma_f32_16x16x32_bf16 v[164:167], v[108:111], v[192:195], v[164:167]
	v_mfma_f32_16x16x32_bf16 v[168:171], v[116:119], v[192:195], v[168:171]
	v_mfma_f32_16x16x32_bf16 v[12:15], v[172:175], v[48:51], v[12:15]
	v_mfma_f32_16x16x32_bf16 v[204:207], v[176:179], v[56:59], v[12:15]
	v_mfma_f32_16x16x32_bf16 v[12:15], v[120:123], v[88:91], v[24:27]
	v_mfma_f32_16x16x32_bf16 v[24:27], v[124:127], v[96:99], v[12:15]
	v_mfma_f32_16x16x32_bf16 v[12:15], v[172:175], v[88:91], v[28:31]
	v_mfma_f32_16x16x32_bf16 v[208:211], v[176:179], v[96:99], v[12:15]
	v_mfma_f32_16x16x32_bf16 v[12:15], v[120:123], v[188:191], v[60:63]
	v_mfma_f32_16x16x32_bf16 v[224:227], v[124:127], v[192:195], v[12:15]
	v_mfma_f32_16x16x32_bf16 v[12:15], v[172:175], v[188:191], v[100:103]
	v_mfma_f32_16x16x32_bf16 v[8:11], v[120:123], v[48:51], v[8:11]
	v_mfma_f32_16x16x32_bf16 v[188:191], v[176:179], v[192:195], v[12:15]
	v_mfma_f32_16x16x32_bf16 v[12:15], v[120:123], v[196:199], v[16:19]
	v_mfma_f32_16x16x32_bf16 v[8:11], v[124:127], v[56:59], v[8:11]
	v_mfma_f32_16x16x32_bf16 v[192:195], v[124:127], v[200:203], v[12:15]
	v_mfma_f32_16x16x32_bf16 v[12:15], v[172:175], v[196:199], v[20:23]
	v_mfma_f32_16x16x32_bf16 v[172:175], v[176:179], v[200:203], v[12:15]
	s_barrier
	s_setprio 0
	s_nop 4
	ds_read_b128 v[12:15], v228
	ds_read_b128 v[16:19], v228 offset:1024
	ds_read_b128 v[176:179], v228 offset:2048
	ds_read_b128 v[196:199], v228 offset:3072
	ds_read_b128 v[200:203], v236
	ds_read_b128 v[228:231], v236 offset:1024
	ds_read_b128 v[232:235], v236 offset:2048
	ds_read_b128 v[236:239], v236 offset:3072
	s_add_u32 s52, s58, 0x10000
	s_addc_u32 s53, s59, 0
	s_mov_b32 m0, s64
	v_lshl_add_u64 v[48:49], s[52:53], 0, v[128:129]
	ds_read_b128 v[20:23], v147 offset:32768
	ds_read_b128 v[28:31], v147 offset:33792
	ds_read_b128 v[60:63], v147 offset:34816
	ds_read_b128 v[100:103], v147 offset:35840
	ds_read_b128 v[240:243], v147 offset:36864
	ds_read_b128 v[244:247], v147 offset:37888
	ds_read_b128 v[248:251], v147 offset:38912
	ds_read_b128 v[216:219], v147 offset:39936
	global_load_lds_dwordx4 v[48:49], off
	v_lshl_add_u64 v[48:49], s[52:53], 0, v[132:133]
	s_mov_b32 m0, s65
	s_nop 0
	global_load_lds_dwordx4 v[48:49], off
	s_waitcnt vmcnt(8)
	s_waitcnt lgkmcnt(0)
	s_setprio 1
	s_barrier
	v_mfma_f32_16x16x32_bf16 v[48:51], v[12:15], v[20:23], v[64:67]
	v_mfma_f32_16x16x32_bf16 v[120:123], v[16:19], v[28:31], v[48:51]
	v_mfma_f32_16x16x32_bf16 v[48:51], v[176:179], v[20:23], v[68:71]
	v_mfma_f32_16x16x32_bf16 v[112:115], v[196:199], v[28:31], v[48:51]
	v_mfma_f32_16x16x32_bf16 v[48:51], v[12:15], v[60:63], v[72:75]
	v_mfma_f32_16x16x32_bf16 v[104:107], v[16:19], v[100:103], v[48:51]
	v_mfma_f32_16x16x32_bf16 v[48:51], v[176:179], v[60:63], v[76:79]
	v_mfma_f32_16x16x32_bf16 v[96:99], v[196:199], v[100:103], v[48:51]
	v_mfma_f32_16x16x32_bf16 v[48:51], v[12:15], v[240:243], v[80:83]
	v_mfma_f32_16x16x32_bf16 v[88:91], v[16:19], v[244:247], v[48:51]
	v_mfma_f32_16x16x32_bf16 v[48:51], v[176:179], v[240:243], v[84:87]
	v_mfma_f32_16x16x32_bf16 v[80:83], v[196:199], v[244:247], v[48:51]
	v_mfma_f32_16x16x32_bf16 v[48:51], v[12:15], v[248:251], v[212:215]
	v_mfma_f32_16x16x32_bf16 v[56:59], v[16:19], v[216:219], v[48:51]
	v_mfma_f32_16x16x32_bf16 v[48:51], v[176:179], v[248:251], v[92:95]
	v_mfma_f32_16x16x32_bf16 v[48:51], v[196:199], v[216:219], v[48:51]
	v_mfma_f32_16x16x32_bf16 v[64:67], v[200:203], v[20:23], v[220:223]
	v_mfma_f32_16x16x32_bf16 v[20:23], v[232:235], v[20:23], v[32:35]
	v_mfma_f32_16x16x32_bf16 v[116:119], v[236:239], v[28:31], v[20:23]
	v_mfma_f32_16x16x32_bf16 v[20:23], v[200:203], v[60:63], v[36:39]
	v_mfma_f32_16x16x32_bf16 v[108:111], v[228:231], v[100:103], v[20:23]
	v_mfma_f32_16x16x32_bf16 v[20:23], v[232:235], v[60:63], v[40:43]
	v_mfma_f32_16x16x32_bf16 v[100:103], v[236:239], v[100:103], v[20:23]
	v_mfma_f32_16x16x32_bf16 v[20:23], v[200:203], v[240:243], v[44:47]
	v_mfma_f32_16x16x32_bf16 v[92:95], v[228:231], v[244:247], v[20:23]
	v_mfma_f32_16x16x32_bf16 v[20:23], v[232:235], v[240:243], v[180:183]
	v_mfma_f32_16x16x32_bf16 v[84:87], v[236:239], v[244:247], v[20:23]
	v_mfma_f32_16x16x32_bf16 v[20:23], v[200:203], v[248:251], v[52:55]
	v_mfma_f32_16x16x32_bf16 v[60:63], v[228:231], v[216:219], v[20:23]
	v_mfma_f32_16x16x32_bf16 v[20:23], v[232:235], v[248:251], v[184:187]
	v_mfma_f32_16x16x32_bf16 v[124:127], v[228:231], v[28:31], v[64:67]
	v_mfma_f32_16x16x32_bf16 v[52:55], v[236:239], v[216:219], v[20:23]
	s_barrier
	s_setprio 0
	s_mov_b32 m0, s84
	s_nop 2
	v_lshl_add_u64 v[20:21], v[140:141], 0, s[12:13]
	s_add_u32 s52, s56, 0x10080
	ds_read_b128 v[32:35], v147 offset:49152
	ds_read_b128 v[40:43], v147 offset:50176
	ds_read_b128 v[180:183], v147 offset:51200
	ds_read_b128 v[184:187], v147 offset:52224
	ds_read_b128 v[212:215], v147 offset:53248
	ds_read_b128 v[216:219], v147 offset:54272
	ds_read_b128 v[220:223], v147 offset:55296
	ds_read_b128 v[240:243], v147 offset:56320
	global_load_lds_dwordx4 v[20:21], off
	v_lshl_add_u64 v[20:21], v[252:253], 0, s[12:13]
	s_mov_b32 m0, s82
	s_addc_u32 s53, s57, 0
	global_load_lds_dwordx4 v[20:21], off
	v_lshl_add_u64 v[20:21], s[52:53], 0, v[130:131]
	s_mov_b32 m0, s54
	s_nop 0
	global_load_lds_dwordx4 v[20:21], off
	v_lshl_add_u64 v[20:21], s[52:53], 0, v[134:135]
	s_mov_b32 m0, s55
	s_nop 0
	global_load_lds_dwordx4 v[20:21], off
	v_lshl_add_u64 v[20:21], v[136:137], 0, s[12:13]
	s_mov_b32 m0, s66
	s_nop 0
	global_load_lds_dwordx4 v[20:21], off
	v_lshl_add_u64 v[20:21], v[138:139], 0, s[12:13]
	s_mov_b32 m0, s67
	s_nop 0
	global_load_lds_dwordx4 v[20:21], off
	s_waitcnt vmcnt(8)
	s_waitcnt lgkmcnt(0)
	s_setprio 1
	s_barrier
	v_mfma_f32_16x16x32_bf16 v[20:23], v[12:15], v[32:35], v[148:151]
	v_mfma_f32_16x16x32_bf16 v[76:79], v[16:19], v[40:43], v[20:23]
	v_mfma_f32_16x16x32_bf16 v[20:23], v[176:179], v[32:35], v[152:155]
	v_mfma_f32_16x16x32_bf16 v[68:71], v[196:199], v[40:43], v[20:23]
	v_mfma_f32_16x16x32_bf16 v[20:23], v[12:15], v[180:183], v[156:159]
	v_mfma_f32_16x16x32_bf16 v[44:47], v[16:19], v[184:187], v[20:23]
	v_mfma_f32_16x16x32_bf16 v[20:23], v[176:179], v[180:183], v[160:163]
	v_mfma_f32_16x16x32_bf16 v[36:39], v[196:199], v[184:187], v[20:23]
	v_mfma_f32_16x16x32_bf16 v[20:23], v[12:15], v[212:215], v[164:167]
	v_mfma_f32_16x16x32_bf16 v[0:3], v[12:15], v[220:223], v[0:3]
	v_mfma_f32_16x16x32_bf16 v[28:31], v[16:19], v[216:219], v[20:23]
	v_mfma_f32_16x16x32_bf16 v[20:23], v[176:179], v[212:215], v[168:171]
	v_mfma_f32_16x16x32_bf16 v[12:15], v[16:19], v[240:243], v[0:3]
	v_mfma_f32_16x16x32_bf16 v[0:3], v[176:179], v[220:223], v[4:7]
	v_mfma_f32_16x16x32_bf16 v[20:23], v[196:199], v[216:219], v[20:23]
	v_mfma_f32_16x16x32_bf16 v[4:7], v[196:199], v[240:243], v[0:3]
	v_mfma_f32_16x16x32_bf16 v[0:3], v[200:203], v[32:35], v[8:11]
	v_mfma_f32_16x16x32_bf16 v[72:75], v[228:231], v[40:43], v[0:3]
	v_mfma_f32_16x16x32_bf16 v[0:3], v[232:235], v[32:35], v[204:207]
	v_mfma_f32_16x16x32_bf16 v[64:67], v[236:239], v[40:43], v[0:3]
	v_mfma_f32_16x16x32_bf16 v[0:3], v[200:203], v[180:183], v[24:27]
	v_mfma_f32_16x16x32_bf16 v[40:43], v[228:231], v[184:187], v[0:3]
	v_mfma_f32_16x16x32_bf16 v[0:3], v[232:235], v[180:183], v[208:211]
	v_mfma_f32_16x16x32_bf16 v[32:35], v[236:239], v[184:187], v[0:3]
	v_mfma_f32_16x16x32_bf16 v[0:3], v[200:203], v[212:215], v[224:227]
	v_mfma_f32_16x16x32_bf16 v[24:27], v[228:231], v[216:219], v[0:3]
	v_mfma_f32_16x16x32_bf16 v[0:3], v[232:235], v[212:215], v[188:191]
	v_mfma_f32_16x16x32_bf16 v[16:19], v[236:239], v[216:219], v[0:3]
	v_mfma_f32_16x16x32_bf16 v[0:3], v[200:203], v[220:223], v[192:195]
	v_mfma_f32_16x16x32_bf16 v[8:11], v[228:231], v[240:243], v[0:3]
	v_mfma_f32_16x16x32_bf16 v[0:3], v[232:235], v[220:223], v[172:175]
	v_mfma_f32_16x16x32_bf16 v[0:3], v[236:239], v[240:243], v[0:3]
	s_barrier
	s_setprio 0
	s_andn2_b64 vcc, exec, s[14:15]
	s_cbranch_vccnz .LBB0_155
	s_barrier

.LBB0_178:
	ds_read_b128 v[148:151], v157
	ds_read_b128 v[162:165], v157 offset:1024
	ds_read_b128 v[166:169], v157 offset:2048
	ds_read_b128 v[170:173], v157 offset:3072
	ds_read_b128 v[174:177], v158
	ds_read_b128 v[178:181], v158 offset:1024
	ds_read_b128 v[182:185], v158 offset:2048
	ds_read_b128 v[186:189], v158 offset:3072
	s_add_u32 s48, s46, 0xfff80080
	s_addc_u32 s49, s47, -1
	s_cmp_eq_u32 s72, 28
	s_cselect_b32 s51, s31, s49
	s_cselect_b32 s50, s66, s48
	s_cselect_b32 s49, s27, s71
	s_cselect_b32 s48, s67, s70
	v_lshl_add_u64 v[152:153], s[46:47], 0, v[142:143]
	s_add_i32 m0, s13, 0xc000
	ds_read_b128 v[190:193], v159
	ds_read_b128 v[194:197], v159 offset:1024
	ds_read_b128 v[198:201], v159 offset:2048
	ds_read_b128 v[202:205], v159 offset:3072
	ds_read_b128 v[206:209], v159 offset:4096
	ds_read_b128 v[210:213], v159 offset:5120
	ds_read_b128 v[214:217], v159 offset:6144
	ds_read_b128 v[218:221], v159 offset:7168
	global_load_lds_dwordx4 v[152:153], off
	v_lshl_add_u64 v[152:153], s[46:47], 0, v[140:141]
	s_add_i32 m0, s13, 0xe000
	s_nop 0
	global_load_lds_dwordx4 v[152:153], off
	s_waitcnt vmcnt(8)
	s_waitcnt lgkmcnt(0)
	s_setprio 1
	s_barrier
	v_mfma_f32_16x16x32_bf16 v[124:127], v[148:151], v[190:193], v[124:127]
	v_mfma_f32_16x16x32_bf16 v[120:123], v[166:169], v[190:193], v[120:123]
	v_mfma_f32_16x16x32_bf16 v[108:111], v[148:151], v[198:201], v[108:111]
	v_mfma_f32_16x16x32_bf16 v[104:107], v[166:169], v[198:201], v[104:107]
	v_mfma_f32_16x16x32_bf16 v[92:95], v[148:151], v[206:209], v[92:95]
	v_mfma_f32_16x16x32_bf16 v[88:91], v[166:169], v[206:209], v[88:91]
	v_mfma_f32_16x16x32_bf16 v[76:79], v[148:151], v[214:217], v[76:79]
	v_mfma_f32_16x16x32_bf16 v[72:75], v[166:169], v[214:217], v[72:75]
	v_mfma_f32_16x16x32_bf16 v[124:127], v[162:165], v[194:197], v[124:127]
	v_mfma_f32_16x16x32_bf16 v[120:123], v[170:173], v[194:197], v[120:123]
	v_mfma_f32_16x16x32_bf16 v[108:111], v[162:165], v[202:205], v[108:111]
	v_mfma_f32_16x16x32_bf16 v[104:107], v[170:173], v[202:205], v[104:107]
	v_mfma_f32_16x16x32_bf16 v[92:95], v[162:165], v[210:213], v[92:95]
	v_mfma_f32_16x16x32_bf16 v[88:91], v[170:173], v[210:213], v[88:91]
	v_mfma_f32_16x16x32_bf16 v[76:79], v[162:165], v[218:221], v[76:79]
	v_mfma_f32_16x16x32_bf16 v[72:75], v[170:173], v[218:221], v[72:75]
	v_mfma_f32_16x16x32_bf16 v[116:119], v[174:177], v[190:193], v[116:119]
	v_mfma_f32_16x16x32_bf16 v[112:115], v[182:185], v[190:193], v[112:115]
	v_mfma_f32_16x16x32_bf16 v[100:103], v[174:177], v[198:201], v[100:103]
	v_mfma_f32_16x16x32_bf16 v[96:99], v[182:185], v[198:201], v[96:99]
	v_mfma_f32_16x16x32_bf16 v[84:87], v[174:177], v[206:209], v[84:87]
	v_mfma_f32_16x16x32_bf16 v[80:83], v[182:185], v[206:209], v[80:83]
	v_mfma_f32_16x16x32_bf16 v[68:71], v[174:177], v[214:217], v[68:71]
	v_mfma_f32_16x16x32_bf16 v[64:67], v[182:185], v[214:217], v[64:67]
	v_mfma_f32_16x16x32_bf16 v[116:119], v[178:181], v[194:197], v[116:119]
	v_mfma_f32_16x16x32_bf16 v[112:115], v[186:189], v[194:197], v[112:115]
	v_mfma_f32_16x16x32_bf16 v[100:103], v[178:181], v[202:205], v[100:103]
	v_mfma_f32_16x16x32_bf16 v[96:99], v[186:189], v[202:205], v[96:99]
	v_mfma_f32_16x16x32_bf16 v[84:87], v[178:181], v[210:213], v[84:87]
	v_mfma_f32_16x16x32_bf16 v[80:83], v[186:189], v[210:213], v[80:83]
	v_mfma_f32_16x16x32_bf16 v[68:71], v[178:181], v[218:221], v[68:71]
	v_mfma_f32_16x16x32_bf16 v[64:67], v[186:189], v[218:221], v[64:67]
	s_barrier
	s_setprio 0
	s_add_i32 s73, s62, s52
	v_lshl_add_u64 v[152:153], s[48:49], 0, v[130:131]
	s_mov_b32 m0, s73
	ds_read_b128 v[190:193], v159 offset:16384
	ds_read_b128 v[194:197], v159 offset:17408
	ds_read_b128 v[198:201], v159 offset:18432
	ds_read_b128 v[202:205], v159 offset:19456
	ds_read_b128 v[206:209], v159 offset:20480
	ds_read_b128 v[210:213], v159 offset:21504
	ds_read_b128 v[214:217], v159 offset:22528
	ds_read_b128 v[218:221], v159 offset:23552
	global_load_lds_dwordx4 v[152:153], off
	s_add_i32 m0, s73, 0x2000
	s_add_u32 s74, s48, 0x80000
	v_lshl_add_u64 v[222:223], s[48:49], 0, v[134:135]
	s_addc_u32 s75, s49, 0
	s_add_i32 s73, s63, s52
	global_load_lds_dwordx4 v[222:223], off
	v_lshl_add_u64 v[224:225], s[74:75], 0, v[130:131]
	s_mov_b32 m0, s73
	v_lshl_add_u64 v[226:227], s[50:51], 0, v[132:133]
	global_load_lds_dwordx4 v[224:225], off
	v_lshl_add_u64 v[224:225], s[74:75], 0, v[134:135]
	s_add_i32 m0, s73, 0x2000
	s_nop 0
	global_load_lds_dwordx4 v[224:225], off
	v_lshl_add_u64 v[224:225], s[50:51], 0, v[128:129]
	s_mov_b32 m0, s13
	s_nop 0
	global_load_lds_dwordx4 v[224:225], off
	s_mov_b32 m0, s53
	s_nop 0
	global_load_lds_dwordx4 v[226:227], off
	s_waitcnt vmcnt(8)
	s_waitcnt lgkmcnt(0)
	s_setprio 1
	s_barrier
	v_mfma_f32_16x16x32_bf16 v[60:63], v[148:151], v[190:193], v[60:63]
	v_mfma_f32_16x16x32_bf16 v[56:59], v[166:169], v[190:193], v[56:59]
	v_mfma_f32_16x16x32_bf16 v[44:47], v[148:151], v[198:201], v[44:47]
	v_mfma_f32_16x16x32_bf16 v[40:43], v[166:169], v[198:201], v[40:43]
	v_mfma_f32_16x16x32_bf16 v[28:31], v[148:151], v[206:209], v[28:31]
	v_mfma_f32_16x16x32_bf16 v[24:27], v[166:169], v[206:209], v[24:27]
	v_mfma_f32_16x16x32_bf16 v[12:15], v[148:151], v[214:217], v[12:15]
	v_mfma_f32_16x16x32_bf16 v[8:11], v[166:169], v[214:217], v[8:11]
	v_mfma_f32_16x16x32_bf16 v[60:63], v[162:165], v[194:197], v[60:63]
	v_mfma_f32_16x16x32_bf16 v[56:59], v[170:173], v[194:197], v[56:59]
	v_mfma_f32_16x16x32_bf16 v[44:47], v[162:165], v[202:205], v[44:47]
	v_mfma_f32_16x16x32_bf16 v[40:43], v[170:173], v[202:205], v[40:43]
	v_mfma_f32_16x16x32_bf16 v[28:31], v[162:165], v[210:213], v[28:31]
	v_mfma_f32_16x16x32_bf16 v[24:27], v[170:173], v[210:213], v[24:27]
	v_mfma_f32_16x16x32_bf16 v[12:15], v[162:165], v[218:221], v[12:15]
	v_mfma_f32_16x16x32_bf16 v[8:11], v[170:173], v[218:221], v[8:11]
	v_mfma_f32_16x16x32_bf16 v[52:55], v[174:177], v[190:193], v[52:55]
	v_mfma_f32_16x16x32_bf16 v[48:51], v[182:185], v[190:193], v[48:51]
	v_mfma_f32_16x16x32_bf16 v[36:39], v[174:177], v[198:201], v[36:39]
	v_mfma_f32_16x16x32_bf16 v[32:35], v[182:185], v[198:201], v[32:35]
	v_mfma_f32_16x16x32_bf16 v[20:23], v[174:177], v[206:209], v[20:23]
	v_mfma_f32_16x16x32_bf16 v[16:19], v[182:185], v[206:209], v[16:19]
	v_mfma_f32_16x16x32_bf16 v[4:7], v[174:177], v[214:217], v[4:7]
	v_mfma_f32_16x16x32_bf16 v[0:3], v[182:185], v[214:217], v[0:3]
	v_mfma_f32_16x16x32_bf16 v[52:55], v[178:181], v[194:197], v[52:55]
	v_mfma_f32_16x16x32_bf16 v[48:51], v[186:189], v[194:197], v[48:51]
	v_mfma_f32_16x16x32_bf16 v[36:39], v[178:181], v[202:205], v[36:39]
	v_mfma_f32_16x16x32_bf16 v[32:35], v[186:189], v[202:205], v[32:35]
	v_mfma_f32_16x16x32_bf16 v[20:23], v[178:181], v[210:213], v[20:23]
	v_mfma_f32_16x16x32_bf16 v[16:19], v[186:189], v[210:213], v[16:19]
	v_mfma_f32_16x16x32_bf16 v[4:7], v[178:181], v[218:221], v[4:7]
	v_mfma_f32_16x16x32_bf16 v[0:3], v[186:189], v[218:221], v[0:3]
	s_barrier
	s_setprio 0
	s_add_i32 s73, 0, 0x18000
	v_add_u32_e32 v137, s73, v155
	s_add_i32 s74, 0, 0x1c000
	ds_read_b128 v[148:151], v137
	ds_read_b128 v[162:165], v137 offset:1024
	ds_read_b128 v[166:169], v137 offset:2048
	ds_read_b128 v[170:173], v137 offset:3072
	v_add_u32_e32 v137, s74, v155
	ds_read_b128 v[174:177], v137
	ds_read_b128 v[178:181], v137 offset:1024
	ds_read_b128 v[182:185], v137 offset:2048
	ds_read_b128 v[186:189], v137 offset:3072
	s_add_u32 s50, s50, 0x80000
	s_addc_u32 s51, s51, 0
	s_mov_b32 m0, s54
	v_lshl_add_u64 v[228:229], s[50:51], 0, v[128:129]
	ds_read_b128 v[190:193], v159 offset:32768
	ds_read_b128 v[194:197], v159 offset:33792
	ds_read_b128 v[198:201], v159 offset:34816
	ds_read_b128 v[202:205], v159 offset:35840
	ds_read_b128 v[206:209], v159 offset:36864
	ds_read_b128 v[210:213], v159 offset:37888
	ds_read_b128 v[214:217], v159 offset:38912
	ds_read_b128 v[218:221], v159 offset:39936
	global_load_lds_dwordx4 v[228:229], off
	v_lshl_add_u64 v[228:229], s[50:51], 0, v[132:133]
	s_mov_b32 m0, s55
	s_nop 0
	global_load_lds_dwordx4 v[228:229], off
	s_waitcnt vmcnt(8)
	s_waitcnt lgkmcnt(0)
	s_setprio 1
	s_barrier
	v_mfma_f32_16x16x32_bf16 v[124:127], v[148:151], v[190:193], v[124:127]
	v_mfma_f32_16x16x32_bf16 v[120:123], v[166:169], v[190:193], v[120:123]
	v_mfma_f32_16x16x32_bf16 v[108:111], v[148:151], v[198:201], v[108:111]
	v_mfma_f32_16x16x32_bf16 v[104:107], v[166:169], v[198:201], v[104:107]
	v_mfma_f32_16x16x32_bf16 v[92:95], v[148:151], v[206:209], v[92:95]
	v_mfma_f32_16x16x32_bf16 v[88:91], v[166:169], v[206:209], v[88:91]
	v_mfma_f32_16x16x32_bf16 v[76:79], v[148:151], v[214:217], v[76:79]
	v_mfma_f32_16x16x32_bf16 v[72:75], v[166:169], v[214:217], v[72:75]
	v_mfma_f32_16x16x32_bf16 v[124:127], v[162:165], v[194:197], v[124:127]
	v_mfma_f32_16x16x32_bf16 v[120:123], v[170:173], v[194:197], v[120:123]
	v_mfma_f32_16x16x32_bf16 v[108:111], v[162:165], v[202:205], v[108:111]
	v_mfma_f32_16x16x32_bf16 v[104:107], v[170:173], v[202:205], v[104:107]
	v_mfma_f32_16x16x32_bf16 v[92:95], v[162:165], v[210:213], v[92:95]
	v_mfma_f32_16x16x32_bf16 v[88:91], v[170:173], v[210:213], v[88:91]
	v_mfma_f32_16x16x32_bf16 v[76:79], v[162:165], v[218:221], v[76:79]
	v_mfma_f32_16x16x32_bf16 v[72:75], v[170:173], v[218:221], v[72:75]
	v_mfma_f32_16x16x32_bf16 v[116:119], v[174:177], v[190:193], v[116:119]
	v_mfma_f32_16x16x32_bf16 v[112:115], v[182:185], v[190:193], v[112:115]
	v_mfma_f32_16x16x32_bf16 v[100:103], v[174:177], v[198:201], v[100:103]
	v_mfma_f32_16x16x32_bf16 v[96:99], v[182:185], v[198:201], v[96:99]
	v_mfma_f32_16x16x32_bf16 v[84:87], v[174:177], v[206:209], v[84:87]
	v_mfma_f32_16x16x32_bf16 v[80:83], v[182:185], v[206:209], v[80:83]
	v_mfma_f32_16x16x32_bf16 v[68:71], v[174:177], v[214:217], v[68:71]
	v_mfma_f32_16x16x32_bf16 v[64:67], v[182:185], v[214:217], v[64:67]
	v_mfma_f32_16x16x32_bf16 v[116:119], v[178:181], v[194:197], v[116:119]
	v_mfma_f32_16x16x32_bf16 v[112:115], v[186:189], v[194:197], v[112:115]
	v_mfma_f32_16x16x32_bf16 v[100:103], v[178:181], v[202:205], v[100:103]
	v_mfma_f32_16x16x32_bf16 v[96:99], v[186:189], v[202:205], v[96:99]
	v_mfma_f32_16x16x32_bf16 v[84:87], v[178:181], v[210:213], v[84:87]
	v_mfma_f32_16x16x32_bf16 v[80:83], v[186:189], v[210:213], v[80:83]
	v_mfma_f32_16x16x32_bf16 v[68:71], v[178:181], v[218:221], v[68:71]
	v_mfma_f32_16x16x32_bf16 v[64:67], v[186:189], v[218:221], v[64:67]
	s_barrier
	s_setprio 0
	s_add_i32 s50, s73, s52
	v_lshl_add_u64 v[152:153], v[152:153], 0, s[22:23]
	s_mov_b32 m0, s50
	ds_read_b128 v[190:193], v159 offset:49152
	ds_read_b128 v[194:197], v159 offset:50176
	ds_read_b128 v[198:201], v159 offset:51200
	ds_read_b128 v[202:205], v159 offset:52224
	ds_read_b128 v[206:209], v159 offset:53248
	ds_read_b128 v[210:213], v159 offset:54272
	ds_read_b128 v[214:217], v159 offset:55296
	ds_read_b128 v[218:221], v159 offset:56320
	global_load_lds_dwordx4 v[152:153], off
	s_add_i32 m0, s50, 0x2000
	s_add_u32 s48, s48, 0x80080
	v_lshl_add_u64 v[152:153], v[222:223], 0, s[22:23]
	s_addc_u32 s49, s49, 0
	s_add_i32 s50, s74, s52
	global_load_lds_dwordx4 v[152:153], off
	v_lshl_add_u64 v[152:153], s[48:49], 0, v[130:131]
	s_mov_b32 m0, s50
	s_nop 0
	global_load_lds_dwordx4 v[152:153], off
	v_lshl_add_u64 v[152:153], s[48:49], 0, v[134:135]
	s_add_i32 m0, s50, 0x2000
	s_nop 0
	global_load_lds_dwordx4 v[152:153], off
	v_lshl_add_u64 v[152:153], v[224:225], 0, s[22:23]
	s_mov_b32 m0, s57
	s_nop 0
	global_load_lds_dwordx4 v[152:153], off
	v_lshl_add_u64 v[152:153], v[226:227], 0, s[22:23]
	s_mov_b32 m0, s58
	s_nop 0
	global_load_lds_dwordx4 v[152:153], off
	s_waitcnt vmcnt(8)
	s_waitcnt lgkmcnt(0)
	s_setprio 1
	s_barrier
	v_mfma_f32_16x16x32_bf16 v[60:63], v[148:151], v[190:193], v[60:63]
	v_mfma_f32_16x16x32_bf16 v[56:59], v[166:169], v[190:193], v[56:59]
	v_mfma_f32_16x16x32_bf16 v[44:47], v[148:151], v[198:201], v[44:47]
	v_mfma_f32_16x16x32_bf16 v[40:43], v[166:169], v[198:201], v[40:43]
	v_mfma_f32_16x16x32_bf16 v[28:31], v[148:151], v[206:209], v[28:31]
	v_mfma_f32_16x16x32_bf16 v[24:27], v[166:169], v[206:209], v[24:27]
	v_mfma_f32_16x16x32_bf16 v[12:15], v[148:151], v[214:217], v[12:15]
	v_mfma_f32_16x16x32_bf16 v[8:11], v[166:169], v[214:217], v[8:11]
	v_mfma_f32_16x16x32_bf16 v[60:63], v[162:165], v[194:197], v[60:63]
	v_mfma_f32_16x16x32_bf16 v[56:59], v[170:173], v[194:197], v[56:59]
	v_mfma_f32_16x16x32_bf16 v[44:47], v[162:165], v[202:205], v[44:47]
	v_mfma_f32_16x16x32_bf16 v[40:43], v[170:173], v[202:205], v[40:43]
	v_mfma_f32_16x16x32_bf16 v[28:31], v[162:165], v[210:213], v[28:31]
	v_mfma_f32_16x16x32_bf16 v[24:27], v[170:173], v[210:213], v[24:27]
	v_mfma_f32_16x16x32_bf16 v[12:15], v[162:165], v[218:221], v[12:15]
	v_mfma_f32_16x16x32_bf16 v[8:11], v[170:173], v[218:221], v[8:11]
	v_mfma_f32_16x16x32_bf16 v[52:55], v[174:177], v[190:193], v[52:55]
	v_mfma_f32_16x16x32_bf16 v[48:51], v[182:185], v[190:193], v[48:51]
	v_mfma_f32_16x16x32_bf16 v[36:39], v[174:177], v[198:201], v[36:39]
	v_mfma_f32_16x16x32_bf16 v[32:35], v[182:185], v[198:201], v[32:35]
	v_mfma_f32_16x16x32_bf16 v[20:23], v[174:177], v[206:209], v[20:23]
	v_mfma_f32_16x16x32_bf16 v[16:19], v[182:185], v[206:209], v[16:19]
	v_mfma_f32_16x16x32_bf16 v[4:7], v[174:177], v[214:217], v[4:7]
	v_mfma_f32_16x16x32_bf16 v[0:3], v[182:185], v[214:217], v[0:3]
	v_mfma_f32_16x16x32_bf16 v[52:55], v[178:181], v[194:197], v[52:55]
	v_mfma_f32_16x16x32_bf16 v[48:51], v[186:189], v[194:197], v[48:51]
	v_mfma_f32_16x16x32_bf16 v[36:39], v[178:181], v[202:205], v[36:39]
	v_mfma_f32_16x16x32_bf16 v[32:35], v[186:189], v[202:205], v[32:35]
	v_mfma_f32_16x16x32_bf16 v[20:23], v[178:181], v[210:213], v[20:23]
	v_mfma_f32_16x16x32_bf16 v[16:19], v[186:189], v[210:213], v[16:19]
	v_mfma_f32_16x16x32_bf16 v[4:7], v[178:181], v[218:221], v[4:7]
	v_mfma_f32_16x16x32_bf16 v[0:3], v[186:189], v[218:221], v[0:3]
	s_barrier
	s_setprio 0
	s_add_i32 s72, s72, 2
	s_add_u32 s70, s70, 0x100
	s_addc_u32 s71, s71, 0
	s_add_u32 s46, s46, 0x100
	s_addc_u32 s47, s47, 0
	s_cmp_gt_u32 s72, 29
	s_cbranch_scc0 .LBB0_178
	s_and_b64 vcc, exec, s[24:25]
	s_cbranch_vccz .LBB0_181
	s_barrier

.LBB0_337:
	ds_read_b128 v[144:147], v151
	ds_read_b128 v[156:159], v151 offset:1024
	ds_read_b128 v[160:163], v151 offset:2048
	ds_read_b128 v[164:167], v151 offset:3072
	ds_read_b128 v[168:171], v152
	ds_read_b128 v[172:175], v152 offset:1024
	ds_read_b128 v[176:179], v152 offset:2048
	ds_read_b128 v[180:183], v152 offset:3072
	s_add_u32 s50, s48, 0xfff80080
	s_addc_u32 s51, s49, -1
	s_cmp_eq_u32 s75, 28
	s_cselect_b32 s53, s31, s51
	s_cselect_b32 s52, s47, s50
	s_cselect_b32 s51, s27, s74
	s_cselect_b32 s50, s71, s72
	v_lshl_add_u64 v[216:217], s[48:49], 0, v[138:139]
	s_add_i32 m0, s57, 0xc000
	ds_read_b128 v[184:187], v153
	ds_read_b128 v[188:191], v153 offset:1024
	ds_read_b128 v[192:195], v153 offset:2048
	ds_read_b128 v[196:199], v153 offset:3072
	ds_read_b128 v[200:203], v153 offset:4096
	ds_read_b128 v[204:207], v153 offset:5120
	ds_read_b128 v[208:211], v153 offset:6144
	ds_read_b128 v[212:215], v153 offset:7168
	global_load_lds_dwordx4 v[216:217], off
	v_lshl_add_u64 v[216:217], s[48:49], 0, v[136:137]
	s_add_i32 m0, s57, 0xe000
	s_nop 0
	global_load_lds_dwordx4 v[216:217], off
	s_waitcnt vmcnt(8)
	s_waitcnt lgkmcnt(0)
	s_setprio 1
	s_barrier
	v_mfma_f32_16x16x32_bf16 v[124:127], v[144:147], v[184:187], v[124:127]
	v_mfma_f32_16x16x32_bf16 v[120:123], v[160:163], v[184:187], v[120:123]
	v_mfma_f32_16x16x32_bf16 v[108:111], v[144:147], v[192:195], v[108:111]
	v_mfma_f32_16x16x32_bf16 v[104:107], v[160:163], v[192:195], v[104:107]
	v_mfma_f32_16x16x32_bf16 v[92:95], v[144:147], v[200:203], v[92:95]
	v_mfma_f32_16x16x32_bf16 v[88:91], v[160:163], v[200:203], v[88:91]
	v_mfma_f32_16x16x32_bf16 v[76:79], v[144:147], v[208:211], v[76:79]
	v_mfma_f32_16x16x32_bf16 v[72:75], v[160:163], v[208:211], v[72:75]
	v_mfma_f32_16x16x32_bf16 v[124:127], v[156:159], v[188:191], v[124:127]
	v_mfma_f32_16x16x32_bf16 v[120:123], v[164:167], v[188:191], v[120:123]
	v_mfma_f32_16x16x32_bf16 v[108:111], v[156:159], v[196:199], v[108:111]
	v_mfma_f32_16x16x32_bf16 v[104:107], v[164:167], v[196:199], v[104:107]
	v_mfma_f32_16x16x32_bf16 v[92:95], v[156:159], v[204:207], v[92:95]
	v_mfma_f32_16x16x32_bf16 v[88:91], v[164:167], v[204:207], v[88:91]
	v_mfma_f32_16x16x32_bf16 v[76:79], v[156:159], v[212:215], v[76:79]
	v_mfma_f32_16x16x32_bf16 v[72:75], v[164:167], v[212:215], v[72:75]
	v_mfma_f32_16x16x32_bf16 v[116:119], v[168:171], v[184:187], v[116:119]
	v_mfma_f32_16x16x32_bf16 v[112:115], v[176:179], v[184:187], v[112:115]
	v_mfma_f32_16x16x32_bf16 v[100:103], v[168:171], v[192:195], v[100:103]
	v_mfma_f32_16x16x32_bf16 v[96:99], v[176:179], v[192:195], v[96:99]
	v_mfma_f32_16x16x32_bf16 v[84:87], v[168:171], v[200:203], v[84:87]
	v_mfma_f32_16x16x32_bf16 v[80:83], v[176:179], v[200:203], v[80:83]
	v_mfma_f32_16x16x32_bf16 v[68:71], v[168:171], v[208:211], v[68:71]
	v_mfma_f32_16x16x32_bf16 v[64:67], v[176:179], v[208:211], v[64:67]
	v_mfma_f32_16x16x32_bf16 v[116:119], v[172:175], v[188:191], v[116:119]
	v_mfma_f32_16x16x32_bf16 v[112:115], v[180:183], v[188:191], v[112:115]
	v_mfma_f32_16x16x32_bf16 v[100:103], v[172:175], v[196:199], v[100:103]
	v_mfma_f32_16x16x32_bf16 v[96:99], v[180:183], v[196:199], v[96:99]
	v_mfma_f32_16x16x32_bf16 v[84:87], v[172:175], v[204:207], v[84:87]
	v_mfma_f32_16x16x32_bf16 v[80:83], v[180:183], v[204:207], v[80:83]
	v_mfma_f32_16x16x32_bf16 v[68:71], v[172:175], v[212:215], v[68:71]
	v_mfma_f32_16x16x32_bf16 v[64:67], v[180:183], v[212:215], v[64:67]
	s_barrier
	s_setprio 0
	s_add_i32 s76, s66, s56
	v_lshl_add_u64 v[216:217], s[50:51], 0, v[130:131]
	s_mov_b32 m0, s76
	ds_read_b128 v[184:187], v153 offset:16384
	ds_read_b128 v[188:191], v153 offset:17408
	ds_read_b128 v[192:195], v153 offset:18432
	ds_read_b128 v[196:199], v153 offset:19456
	ds_read_b128 v[200:203], v153 offset:20480
	ds_read_b128 v[204:207], v153 offset:21504
	ds_read_b128 v[208:211], v153 offset:22528
	ds_read_b128 v[212:215], v153 offset:23552
	global_load_lds_dwordx4 v[216:217], off
	s_add_i32 m0, s76, 0x2000
	s_add_u32 s76, s50, 0x80000
	v_lshl_add_u64 v[218:219], s[50:51], 0, v[134:135]
	s_addc_u32 s77, s51, 0
	s_add_i32 s78, s67, s56
	global_load_lds_dwordx4 v[218:219], off
	v_lshl_add_u64 v[220:221], s[76:77], 0, v[130:131]
	s_mov_b32 m0, s78
	v_lshl_add_u64 v[222:223], s[52:53], 0, v[132:133]
	global_load_lds_dwordx4 v[220:221], off
	v_lshl_add_u64 v[220:221], s[76:77], 0, v[134:135]
	s_add_i32 m0, s78, 0x2000
	s_nop 0
	global_load_lds_dwordx4 v[220:221], off
	v_lshl_add_u64 v[220:221], s[52:53], 0, v[128:129]
	s_mov_b32 m0, s57
	s_nop 0
	global_load_lds_dwordx4 v[220:221], off
	s_mov_b32 m0, s58
	s_nop 0
	global_load_lds_dwordx4 v[222:223], off
	s_waitcnt vmcnt(8)
	s_waitcnt lgkmcnt(0)
	s_setprio 1
	s_barrier
	v_mfma_f32_16x16x32_bf16 v[60:63], v[144:147], v[184:187], v[60:63]
	v_mfma_f32_16x16x32_bf16 v[56:59], v[160:163], v[184:187], v[56:59]
	v_mfma_f32_16x16x32_bf16 v[44:47], v[144:147], v[192:195], v[44:47]
	v_mfma_f32_16x16x32_bf16 v[40:43], v[160:163], v[192:195], v[40:43]
	v_mfma_f32_16x16x32_bf16 v[28:31], v[144:147], v[200:203], v[28:31]
	v_mfma_f32_16x16x32_bf16 v[24:27], v[160:163], v[200:203], v[24:27]
	v_mfma_f32_16x16x32_bf16 v[12:15], v[144:147], v[208:211], v[12:15]
	v_mfma_f32_16x16x32_bf16 v[8:11], v[160:163], v[208:211], v[8:11]
	v_mfma_f32_16x16x32_bf16 v[60:63], v[156:159], v[188:191], v[60:63]
	v_mfma_f32_16x16x32_bf16 v[56:59], v[164:167], v[188:191], v[56:59]
	v_mfma_f32_16x16x32_bf16 v[44:47], v[156:159], v[196:199], v[44:47]
	v_mfma_f32_16x16x32_bf16 v[40:43], v[164:167], v[196:199], v[40:43]
	v_mfma_f32_16x16x32_bf16 v[28:31], v[156:159], v[204:207], v[28:31]
	v_mfma_f32_16x16x32_bf16 v[24:27], v[164:167], v[204:207], v[24:27]
	v_mfma_f32_16x16x32_bf16 v[12:15], v[156:159], v[212:215], v[12:15]
	v_mfma_f32_16x16x32_bf16 v[8:11], v[164:167], v[212:215], v[8:11]
	v_mfma_f32_16x16x32_bf16 v[52:55], v[168:171], v[184:187], v[52:55]
	v_mfma_f32_16x16x32_bf16 v[48:51], v[176:179], v[184:187], v[48:51]
	v_mfma_f32_16x16x32_bf16 v[36:39], v[168:171], v[192:195], v[36:39]
	v_mfma_f32_16x16x32_bf16 v[32:35], v[176:179], v[192:195], v[32:35]
	v_mfma_f32_16x16x32_bf16 v[20:23], v[168:171], v[200:203], v[20:23]
	v_mfma_f32_16x16x32_bf16 v[16:19], v[176:179], v[200:203], v[16:19]
	v_mfma_f32_16x16x32_bf16 v[4:7], v[168:171], v[208:211], v[4:7]
	v_mfma_f32_16x16x32_bf16 v[0:3], v[176:179], v[208:211], v[0:3]
	v_mfma_f32_16x16x32_bf16 v[52:55], v[172:175], v[188:191], v[52:55]
	v_mfma_f32_16x16x32_bf16 v[48:51], v[180:183], v[188:191], v[48:51]
	v_mfma_f32_16x16x32_bf16 v[36:39], v[172:175], v[196:199], v[36:39]
	v_mfma_f32_16x16x32_bf16 v[32:35], v[180:183], v[196:199], v[32:35]
	v_mfma_f32_16x16x32_bf16 v[20:23], v[172:175], v[204:207], v[20:23]
	v_mfma_f32_16x16x32_bf16 v[16:19], v[180:183], v[204:207], v[16:19]
	v_mfma_f32_16x16x32_bf16 v[4:7], v[172:175], v[212:215], v[4:7]
	v_mfma_f32_16x16x32_bf16 v[0:3], v[180:183], v[212:215], v[0:3]
	s_barrier
	s_setprio 0
	s_add_i32 s76, 0, 0x18000
	v_add_u32_e32 v155, s76, v149
	s_add_i32 s77, 0, 0x1c000
	ds_read_b128 v[144:147], v155
	ds_read_b128 v[156:159], v155 offset:1024
	ds_read_b128 v[160:163], v155 offset:2048
	ds_read_b128 v[164:167], v155 offset:3072
	v_add_u32_e32 v155, s77, v149
	ds_read_b128 v[168:171], v155
	ds_read_b128 v[172:175], v155 offset:1024
	ds_read_b128 v[176:179], v155 offset:2048
	ds_read_b128 v[180:183], v155 offset:3072
	s_add_u32 s52, s52, 0x80000
	s_addc_u32 s53, s53, 0
	s_mov_b32 m0, s59
	v_lshl_add_u64 v[224:225], s[52:53], 0, v[128:129]
	ds_read_b128 v[184:187], v153 offset:32768
	ds_read_b128 v[188:191], v153 offset:33792
	ds_read_b128 v[192:195], v153 offset:34816
	ds_read_b128 v[196:199], v153 offset:35840
	ds_read_b128 v[200:203], v153 offset:36864
	ds_read_b128 v[204:207], v153 offset:37888
	ds_read_b128 v[208:211], v153 offset:38912
	ds_read_b128 v[212:215], v153 offset:39936
	global_load_lds_dwordx4 v[224:225], off
	v_lshl_add_u64 v[224:225], s[52:53], 0, v[132:133]
	s_mov_b32 m0, s60
	s_nop 0
	global_load_lds_dwordx4 v[224:225], off
	s_waitcnt vmcnt(8)
	s_waitcnt lgkmcnt(0)
	s_setprio 1
	s_barrier
	v_mfma_f32_16x16x32_bf16 v[124:127], v[144:147], v[184:187], v[124:127]
	v_mfma_f32_16x16x32_bf16 v[120:123], v[160:163], v[184:187], v[120:123]
	v_mfma_f32_16x16x32_bf16 v[108:111], v[144:147], v[192:195], v[108:111]
	v_mfma_f32_16x16x32_bf16 v[104:107], v[160:163], v[192:195], v[104:107]
	v_mfma_f32_16x16x32_bf16 v[92:95], v[144:147], v[200:203], v[92:95]
	v_mfma_f32_16x16x32_bf16 v[88:91], v[160:163], v[200:203], v[88:91]
	v_mfma_f32_16x16x32_bf16 v[76:79], v[144:147], v[208:211], v[76:79]
	v_mfma_f32_16x16x32_bf16 v[72:75], v[160:163], v[208:211], v[72:75]
	v_mfma_f32_16x16x32_bf16 v[124:127], v[156:159], v[188:191], v[124:127]
	v_mfma_f32_16x16x32_bf16 v[120:123], v[164:167], v[188:191], v[120:123]
	v_mfma_f32_16x16x32_bf16 v[108:111], v[156:159], v[196:199], v[108:111]
	v_mfma_f32_16x16x32_bf16 v[104:107], v[164:167], v[196:199], v[104:107]
	v_mfma_f32_16x16x32_bf16 v[92:95], v[156:159], v[204:207], v[92:95]
	v_mfma_f32_16x16x32_bf16 v[88:91], v[164:167], v[204:207], v[88:91]
	v_mfma_f32_16x16x32_bf16 v[76:79], v[156:159], v[212:215], v[76:79]
	v_mfma_f32_16x16x32_bf16 v[72:75], v[164:167], v[212:215], v[72:75]
	v_mfma_f32_16x16x32_bf16 v[116:119], v[168:171], v[184:187], v[116:119]
	v_mfma_f32_16x16x32_bf16 v[112:115], v[176:179], v[184:187], v[112:115]
	v_mfma_f32_16x16x32_bf16 v[100:103], v[168:171], v[192:195], v[100:103]
	v_mfma_f32_16x16x32_bf16 v[96:99], v[176:179], v[192:195], v[96:99]
	v_mfma_f32_16x16x32_bf16 v[84:87], v[168:171], v[200:203], v[84:87]
	v_mfma_f32_16x16x32_bf16 v[80:83], v[176:179], v[200:203], v[80:83]
	v_mfma_f32_16x16x32_bf16 v[68:71], v[168:171], v[208:211], v[68:71]
	v_mfma_f32_16x16x32_bf16 v[64:67], v[176:179], v[208:211], v[64:67]
	v_mfma_f32_16x16x32_bf16 v[116:119], v[172:175], v[188:191], v[116:119]
	v_mfma_f32_16x16x32_bf16 v[112:115], v[180:183], v[188:191], v[112:115]
	v_mfma_f32_16x16x32_bf16 v[100:103], v[172:175], v[196:199], v[100:103]
	v_mfma_f32_16x16x32_bf16 v[96:99], v[180:183], v[196:199], v[96:99]
	v_mfma_f32_16x16x32_bf16 v[84:87], v[172:175], v[204:207], v[84:87]
	v_mfma_f32_16x16x32_bf16 v[80:83], v[180:183], v[204:207], v[80:83]
	v_mfma_f32_16x16x32_bf16 v[68:71], v[172:175], v[212:215], v[68:71]
	v_mfma_f32_16x16x32_bf16 v[64:67], v[180:183], v[212:215], v[64:67]
	s_barrier
	s_setprio 0
	s_add_i32 s52, s76, s56
	v_lshl_add_u64 v[216:217], v[216:217], 0, s[22:23]
	s_mov_b32 m0, s52
	ds_read_b128 v[184:187], v153 offset:49152
	ds_read_b128 v[188:191], v153 offset:50176
	ds_read_b128 v[192:195], v153 offset:51200
	ds_read_b128 v[196:199], v153 offset:52224
	ds_read_b128 v[200:203], v153 offset:53248
	ds_read_b128 v[204:207], v153 offset:54272
	ds_read_b128 v[208:211], v153 offset:55296
	ds_read_b128 v[212:215], v153 offset:56320
	global_load_lds_dwordx4 v[216:217], off
	s_add_i32 m0, s52, 0x2000
	s_add_u32 s50, s50, 0x80080
	v_lshl_add_u64 v[216:217], v[218:219], 0, s[22:23]
	s_addc_u32 s51, s51, 0
	s_add_i32 s52, s77, s56
	global_load_lds_dwordx4 v[216:217], off
	v_lshl_add_u64 v[216:217], s[50:51], 0, v[130:131]
	s_mov_b32 m0, s52
	s_nop 0
	global_load_lds_dwordx4 v[216:217], off
	v_lshl_add_u64 v[216:217], s[50:51], 0, v[134:135]
	s_add_i32 m0, s52, 0x2000
	s_nop 0
	global_load_lds_dwordx4 v[216:217], off
	v_lshl_add_u64 v[216:217], v[220:221], 0, s[22:23]
	s_mov_b32 m0, s62
	s_nop 0
	global_load_lds_dwordx4 v[216:217], off
	v_lshl_add_u64 v[216:217], v[222:223], 0, s[22:23]
	s_mov_b32 m0, s63
	s_nop 0
	global_load_lds_dwordx4 v[216:217], off
	s_waitcnt vmcnt(8)
	s_waitcnt lgkmcnt(0)
	s_setprio 1
	s_barrier
	v_mfma_f32_16x16x32_bf16 v[60:63], v[144:147], v[184:187], v[60:63]
	v_mfma_f32_16x16x32_bf16 v[56:59], v[160:163], v[184:187], v[56:59]
	v_mfma_f32_16x16x32_bf16 v[44:47], v[144:147], v[192:195], v[44:47]
	v_mfma_f32_16x16x32_bf16 v[40:43], v[160:163], v[192:195], v[40:43]
	v_mfma_f32_16x16x32_bf16 v[28:31], v[144:147], v[200:203], v[28:31]
	v_mfma_f32_16x16x32_bf16 v[24:27], v[160:163], v[200:203], v[24:27]
	v_mfma_f32_16x16x32_bf16 v[12:15], v[144:147], v[208:211], v[12:15]
	v_mfma_f32_16x16x32_bf16 v[8:11], v[160:163], v[208:211], v[8:11]
	v_mfma_f32_16x16x32_bf16 v[60:63], v[156:159], v[188:191], v[60:63]
	v_mfma_f32_16x16x32_bf16 v[56:59], v[164:167], v[188:191], v[56:59]
	v_mfma_f32_16x16x32_bf16 v[44:47], v[156:159], v[196:199], v[44:47]
	v_mfma_f32_16x16x32_bf16 v[40:43], v[164:167], v[196:199], v[40:43]
	v_mfma_f32_16x16x32_bf16 v[28:31], v[156:159], v[204:207], v[28:31]
	v_mfma_f32_16x16x32_bf16 v[24:27], v[164:167], v[204:207], v[24:27]
	v_mfma_f32_16x16x32_bf16 v[12:15], v[156:159], v[212:215], v[12:15]
	v_mfma_f32_16x16x32_bf16 v[8:11], v[164:167], v[212:215], v[8:11]
	v_mfma_f32_16x16x32_bf16 v[52:55], v[168:171], v[184:187], v[52:55]
	v_mfma_f32_16x16x32_bf16 v[48:51], v[176:179], v[184:187], v[48:51]
	v_mfma_f32_16x16x32_bf16 v[36:39], v[168:171], v[192:195], v[36:39]
	v_mfma_f32_16x16x32_bf16 v[32:35], v[176:179], v[192:195], v[32:35]
	v_mfma_f32_16x16x32_bf16 v[20:23], v[168:171], v[200:203], v[20:23]
	v_mfma_f32_16x16x32_bf16 v[16:19], v[176:179], v[200:203], v[16:19]
	v_mfma_f32_16x16x32_bf16 v[4:7], v[168:171], v[208:211], v[4:7]
	v_mfma_f32_16x16x32_bf16 v[0:3], v[176:179], v[208:211], v[0:3]
	v_mfma_f32_16x16x32_bf16 v[52:55], v[172:175], v[188:191], v[52:55]
	v_mfma_f32_16x16x32_bf16 v[48:51], v[180:183], v[188:191], v[48:51]
	v_mfma_f32_16x16x32_bf16 v[36:39], v[172:175], v[196:199], v[36:39]
	v_mfma_f32_16x16x32_bf16 v[32:35], v[180:183], v[196:199], v[32:35]
	v_mfma_f32_16x16x32_bf16 v[20:23], v[172:175], v[204:207], v[20:23]
	v_mfma_f32_16x16x32_bf16 v[16:19], v[180:183], v[204:207], v[16:19]
	v_mfma_f32_16x16x32_bf16 v[4:7], v[172:175], v[212:215], v[4:7]
	v_mfma_f32_16x16x32_bf16 v[0:3], v[180:183], v[212:215], v[0:3]
	s_barrier
	s_setprio 0
	s_add_i32 s75, s75, 2
	s_add_u32 s72, s72, 0x100
	s_addc_u32 s74, s74, 0
	s_add_u32 s48, s48, 0x100
	s_addc_u32 s49, s49, 0
	s_cmp_gt_u32 s75, 29
	s_cbranch_scc0 .LBB0_337
	s_and_b64 vcc, exec, s[24:25]
	s_cbranch_vccz .LBB0_340
	s_barrier

.Lsegback_1:
	s_add_i32 s84, s84, 2
	s_add_u32 s82, s82, 0x100
	s_addc_u32 s83, s83, 0
	s_add_u32 s54, s54, 0x100
	s_addc_u32 s55, s55, 0
	s_cmp_gt_u32 s84, 29
	s_cbranch_scc1 .LBB0_439
.LBB0_435:
	ds_read_b128 v[148:151], v222
	ds_read_b128 v[152:155], v222 offset:1024
	ds_read_b128 v[156:159], v222 offset:2048
	ds_read_b128 v[160:163], v222 offset:3072
	ds_read_b128 v[132:135], v223
	ds_read_b128 v[136:139], v223 offset:1024
	ds_read_b128 v[140:143], v223 offset:2048
	ds_read_b128 v[144:147], v223 offset:3072
	s_add_u32 s10, s54, 0xfff80080
	s_addc_u32 s11, s55, -1
	s_cmp_eq_u32 s84, 28
	s_cselect_b32 s59, s25, s11
	s_cselect_b32 s58, s46, s10
	s_cselect_b32 s57, s23, s83
	s_cselect_b32 s56, s47, s82
	v_lshl_add_u64 v[2:3], s[54:55], 0, v[208:209]
	s_add_i32 m0, s37, 0xc000
	s_waitcnt lgkmcnt(0)
	ds_read_b128 v[164:167], v224
	ds_read_b128 v[168:171], v224 offset:1024
	ds_read_b128 v[172:175], v224 offset:2048
	ds_read_b128 v[176:179], v224 offset:3072
	ds_read_b128 v[180:183], v224 offset:4096
	ds_read_b128 v[184:187], v224 offset:5120
	ds_read_b128 v[188:191], v224 offset:6144
	ds_read_b128 v[192:195], v224 offset:7168
	global_load_lds_dwordx4 v[2:3], off
	v_lshl_add_u64 v[2:3], s[54:55], 0, v[206:207]
	s_add_i32 m0, s37, 0xe000
	s_nop 0
	global_load_lds_dwordx4 v[2:3], off
	s_waitcnt vmcnt(8)
	s_waitcnt lgkmcnt(0)
	s_setprio 1
	s_barrier
	v_mfma_f32_16x16x32_bf16 v[120:123], v[148:151], v[164:167], v[120:123]
	v_mfma_f32_16x16x32_bf16 v[116:119], v[156:159], v[164:167], v[116:119]
	v_mfma_f32_16x16x32_bf16 v[104:107], v[148:151], v[172:175], v[104:107]
	v_mfma_f32_16x16x32_bf16 v[100:103], v[156:159], v[172:175], v[100:103]
	v_mfma_f32_16x16x32_bf16 v[88:91], v[148:151], v[180:183], v[88:91]
	v_mfma_f32_16x16x32_bf16 v[84:87], v[156:159], v[180:183], v[84:87]
	v_mfma_f32_16x16x32_bf16 v[76:79], v[148:151], v[188:191], v[76:79]
	v_mfma_f32_16x16x32_bf16 v[72:75], v[156:159], v[188:191], v[72:75]
	v_mfma_f32_16x16x32_bf16 v[120:123], v[152:155], v[168:171], v[120:123]
	v_mfma_f32_16x16x32_bf16 v[116:119], v[160:163], v[168:171], v[116:119]
	v_mfma_f32_16x16x32_bf16 v[104:107], v[152:155], v[176:179], v[104:107]
	v_mfma_f32_16x16x32_bf16 v[100:103], v[160:163], v[176:179], v[100:103]
	v_mfma_f32_16x16x32_bf16 v[88:91], v[152:155], v[184:187], v[88:91]
	v_mfma_f32_16x16x32_bf16 v[84:87], v[160:163], v[184:187], v[84:87]
	v_mfma_f32_16x16x32_bf16 v[76:79], v[152:155], v[192:195], v[76:79]
	v_mfma_f32_16x16x32_bf16 v[72:75], v[160:163], v[192:195], v[72:75]
	v_mfma_f32_16x16x32_bf16 v[128:131], v[132:135], v[164:167], v[128:131]
	v_mfma_f32_16x16x32_bf16 v[124:127], v[140:143], v[164:167], v[124:127]
	v_mfma_f32_16x16x32_bf16 v[112:115], v[132:135], v[172:175], v[112:115]
	v_mfma_f32_16x16x32_bf16 v[108:111], v[140:143], v[172:175], v[108:111]
	v_mfma_f32_16x16x32_bf16 v[96:99], v[132:135], v[180:183], v[96:99]
	v_mfma_f32_16x16x32_bf16 v[92:95], v[140:143], v[180:183], v[92:95]
	v_mfma_f32_16x16x32_bf16 v[80:83], v[132:135], v[188:191], v[80:83]
	v_mfma_f32_16x16x32_bf16 v[68:71], v[140:143], v[188:191], v[68:71]
	v_mfma_f32_16x16x32_bf16 v[128:131], v[136:139], v[168:171], v[128:131]
	v_mfma_f32_16x16x32_bf16 v[124:127], v[144:147], v[168:171], v[124:127]
	v_mfma_f32_16x16x32_bf16 v[112:115], v[136:139], v[176:179], v[112:115]
	v_mfma_f32_16x16x32_bf16 v[108:111], v[144:147], v[176:179], v[108:111]
	v_mfma_f32_16x16x32_bf16 v[96:99], v[136:139], v[184:187], v[96:99]
	v_mfma_f32_16x16x32_bf16 v[92:95], v[144:147], v[184:187], v[92:95]
	v_mfma_f32_16x16x32_bf16 v[80:83], v[136:139], v[192:195], v[80:83]
	v_mfma_f32_16x16x32_bf16 v[68:71], v[144:147], v[192:195], v[68:71]
	s_barrier
	s_setprio 0
	s_add_i32 s10, s67, s48
	v_lshl_add_u64 v[2:3], s[56:57], 0, v[198:199]
	s_mov_b32 m0, s10
	ds_read_b128 v[188:191], v224 offset:16384
	ds_read_b128 v[192:195], v224 offset:17408
	ds_read_b128 v[180:183], v224 offset:18432
	ds_read_b128 v[184:187], v224 offset:19456
	ds_read_b128 v[172:175], v224 offset:20480
	ds_read_b128 v[176:179], v224 offset:21504
	ds_read_b128 v[164:167], v224 offset:22528
	ds_read_b128 v[168:171], v224 offset:23552
	global_load_lds_dwordx4 v[2:3], off
	s_add_i32 m0, s10, 0x2000
	s_add_u32 s10, s56, 0x80000
	v_lshl_add_u64 v[212:213], s[56:57], 0, v[202:203]
	s_addc_u32 s11, s57, 0
	s_add_i32 s78, s70, s48
	global_load_lds_dwordx4 v[212:213], off
	v_lshl_add_u64 v[214:215], s[10:11], 0, v[198:199]
	s_mov_b32 m0, s78
	v_lshl_add_u64 v[216:217], s[58:59], 0, v[200:201]
	global_load_lds_dwordx4 v[214:215], off
	v_lshl_add_u64 v[214:215], s[10:11], 0, v[202:203]
	s_add_i32 m0, s78, 0x2000
	v_cmp_ne_u32_e64 s[10:11], 1, v227
	global_load_lds_dwordx4 v[214:215], off
	v_lshl_add_u64 v[214:215], s[58:59], 0, v[196:197]
	s_mov_b32 m0, s37
	s_andn2_b64 vcc, exec, s[52:53]
	global_load_lds_dwordx4 v[214:215], off
	s_mov_b32 m0, s60
	s_nop 0
	global_load_lds_dwordx4 v[216:217], off
	s_waitcnt vmcnt(8)
	s_waitcnt lgkmcnt(0)
	s_cbranch_vccnz .Lsegskip_0
	s_setprio 1
	s_barrier
	v_mfma_f32_16x16x32_bf16 v[56:59], v[148:151], v[188:191], v[56:59]
	v_mfma_f32_16x16x32_bf16 v[52:55], v[156:159], v[188:191], v[52:55]
	v_mfma_f32_16x16x32_bf16 v[40:43], v[148:151], v[180:183], v[40:43]
	v_mfma_f32_16x16x32_bf16 v[36:39], v[156:159], v[180:183], v[36:39]
	v_mfma_f32_16x16x32_bf16 v[24:27], v[148:151], v[172:175], v[24:27]
	v_mfma_f32_16x16x32_bf16 v[20:23], v[156:159], v[172:175], v[20:23]
	v_mfma_f32_16x16x32_bf16 v[8:11], v[148:151], v[164:167], v[8:11]
	v_mfma_f32_16x16x32_bf16 v[4:7], v[156:159], v[164:167], v[4:7]
	v_mfma_f32_16x16x32_bf16 v[56:59], v[152:155], v[192:195], v[56:59]
	v_mfma_f32_16x16x32_bf16 v[52:55], v[160:163], v[192:195], v[52:55]
	v_mfma_f32_16x16x32_bf16 v[40:43], v[152:155], v[184:187], v[40:43]
	v_mfma_f32_16x16x32_bf16 v[36:39], v[160:163], v[184:187], v[36:39]
	v_mfma_f32_16x16x32_bf16 v[24:27], v[152:155], v[176:179], v[24:27]
	v_mfma_f32_16x16x32_bf16 v[20:23], v[160:163], v[176:179], v[20:23]
	v_mfma_f32_16x16x32_bf16 v[8:11], v[152:155], v[168:171], v[8:11]
	v_mfma_f32_16x16x32_bf16 v[4:7], v[160:163], v[168:171], v[4:7]
	v_mfma_f32_16x16x32_bf16 v[64:67], v[132:135], v[188:191], v[64:67]
	v_mfma_f32_16x16x32_bf16 v[60:63], v[140:143], v[188:191], v[60:63]
	v_mfma_f32_16x16x32_bf16 v[48:51], v[132:135], v[180:183], v[48:51]
	v_mfma_f32_16x16x32_bf16 v[44:47], v[140:143], v[180:183], v[44:47]
	v_mfma_f32_16x16x32_bf16 v[32:35], v[132:135], v[172:175], v[32:35]
	v_mfma_f32_16x16x32_bf16 v[28:31], v[140:143], v[172:175], v[28:31]
	v_mfma_f32_16x16x32_bf16 v[16:19], v[132:135], v[164:167], v[16:19]
	v_mfma_f32_16x16x32_bf16 v[12:15], v[140:143], v[164:167], v[12:15]
	v_mfma_f32_16x16x32_bf16 v[64:67], v[136:139], v[192:195], v[64:67]
	v_mfma_f32_16x16x32_bf16 v[60:63], v[144:147], v[192:195], v[60:63]
	v_mfma_f32_16x16x32_bf16 v[48:51], v[136:139], v[184:187], v[48:51]
	v_mfma_f32_16x16x32_bf16 v[44:47], v[144:147], v[184:187], v[44:47]
	v_mfma_f32_16x16x32_bf16 v[32:35], v[136:139], v[176:179], v[32:35]
	v_mfma_f32_16x16x32_bf16 v[28:31], v[144:147], v[176:179], v[28:31]
	v_mfma_f32_16x16x32_bf16 v[16:19], v[136:139], v[168:171], v[16:19]
	v_mfma_f32_16x16x32_bf16 v[12:15], v[144:147], v[168:171], v[12:15]
.LBB0_437:
	s_barrier
	s_setprio 0
	s_add_i32 s78, 0, 0x18000
	v_add_u32_e32 v1, s78, v220
	s_add_i32 s79, 0, 0x1c000
	ds_read_b128 v[148:151], v1
	ds_read_b128 v[152:155], v1 offset:1024
	ds_read_b128 v[156:159], v1 offset:2048
	ds_read_b128 v[160:163], v1 offset:3072
	v_add_u32_e32 v1, s79, v220
	ds_read_b128 v[132:135], v1
	ds_read_b128 v[136:139], v1 offset:1024
	ds_read_b128 v[140:143], v1 offset:2048
	ds_read_b128 v[144:147], v1 offset:3072
	s_add_u32 s58, s58, 0x80000
	s_addc_u32 s59, s59, 0
	s_mov_b32 m0, s61
	v_lshl_add_u64 v[228:229], s[58:59], 0, v[196:197]
	s_waitcnt lgkmcnt(0)
	ds_read_b128 v[164:167], v224 offset:32768
	ds_read_b128 v[168:171], v224 offset:33792
	ds_read_b128 v[172:175], v224 offset:34816
	ds_read_b128 v[176:179], v224 offset:35840
	ds_read_b128 v[180:183], v224 offset:36864
	ds_read_b128 v[184:187], v224 offset:37888
	ds_read_b128 v[188:191], v224 offset:38912
	ds_read_b128 v[192:195], v224 offset:39936
	global_load_lds_dwordx4 v[228:229], off
	v_lshl_add_u64 v[228:229], s[58:59], 0, v[200:201]
	s_mov_b32 m0, s62
	s_nop 0
	global_load_lds_dwordx4 v[228:229], off
	s_waitcnt vmcnt(8)
	s_waitcnt lgkmcnt(0)
	s_setprio 1
	s_barrier
	v_mfma_f32_16x16x32_bf16 v[120:123], v[148:151], v[164:167], v[120:123]
	v_mfma_f32_16x16x32_bf16 v[116:119], v[156:159], v[164:167], v[116:119]
	v_mfma_f32_16x16x32_bf16 v[104:107], v[148:151], v[172:175], v[104:107]
	v_mfma_f32_16x16x32_bf16 v[100:103], v[156:159], v[172:175], v[100:103]
	v_mfma_f32_16x16x32_bf16 v[88:91], v[148:151], v[180:183], v[88:91]
	v_mfma_f32_16x16x32_bf16 v[84:87], v[156:159], v[180:183], v[84:87]
	v_mfma_f32_16x16x32_bf16 v[76:79], v[148:151], v[188:191], v[76:79]
	v_mfma_f32_16x16x32_bf16 v[72:75], v[156:159], v[188:191], v[72:75]
	v_mfma_f32_16x16x32_bf16 v[120:123], v[152:155], v[168:171], v[120:123]
	v_mfma_f32_16x16x32_bf16 v[116:119], v[160:163], v[168:171], v[116:119]
	v_mfma_f32_16x16x32_bf16 v[104:107], v[152:155], v[176:179], v[104:107]
	v_mfma_f32_16x16x32_bf16 v[100:103], v[160:163], v[176:179], v[100:103]
	v_mfma_f32_16x16x32_bf16 v[88:91], v[152:155], v[184:187], v[88:91]
	v_mfma_f32_16x16x32_bf16 v[84:87], v[160:163], v[184:187], v[84:87]
	v_mfma_f32_16x16x32_bf16 v[76:79], v[152:155], v[192:195], v[76:79]
	v_mfma_f32_16x16x32_bf16 v[72:75], v[160:163], v[192:195], v[72:75]
	v_mfma_f32_16x16x32_bf16 v[128:131], v[132:135], v[164:167], v[128:131]
	v_mfma_f32_16x16x32_bf16 v[124:127], v[140:143], v[164:167], v[124:127]
	v_mfma_f32_16x16x32_bf16 v[112:115], v[132:135], v[172:175], v[112:115]
	v_mfma_f32_16x16x32_bf16 v[108:111], v[140:143], v[172:175], v[108:111]
	v_mfma_f32_16x16x32_bf16 v[96:99], v[132:135], v[180:183], v[96:99]
	v_mfma_f32_16x16x32_bf16 v[92:95], v[140:143], v[180:183], v[92:95]
	v_mfma_f32_16x16x32_bf16 v[80:83], v[132:135], v[188:191], v[80:83]
	v_mfma_f32_16x16x32_bf16 v[68:71], v[140:143], v[188:191], v[68:71]
	v_mfma_f32_16x16x32_bf16 v[128:131], v[136:139], v[168:171], v[128:131]
	v_mfma_f32_16x16x32_bf16 v[124:127], v[144:147], v[168:171], v[124:127]
	v_mfma_f32_16x16x32_bf16 v[112:115], v[136:139], v[176:179], v[112:115]
	v_mfma_f32_16x16x32_bf16 v[108:111], v[144:147], v[176:179], v[108:111]
	v_mfma_f32_16x16x32_bf16 v[96:99], v[136:139], v[184:187], v[96:99]
	v_mfma_f32_16x16x32_bf16 v[92:95], v[144:147], v[184:187], v[92:95]
	v_mfma_f32_16x16x32_bf16 v[80:83], v[136:139], v[192:195], v[80:83]
	v_mfma_f32_16x16x32_bf16 v[68:71], v[144:147], v[192:195], v[68:71]
	s_barrier
	s_setprio 0
	s_add_i32 s58, s78, s48
	v_lshl_add_u64 v[2:3], v[2:3], 0, s[16:17]
	s_mov_b32 m0, s58
	ds_read_b128 v[188:191], v224 offset:49152
	ds_read_b128 v[192:195], v224 offset:50176
	ds_read_b128 v[180:183], v224 offset:51200
	ds_read_b128 v[184:187], v224 offset:52224
	ds_read_b128 v[172:175], v224 offset:53248
	ds_read_b128 v[176:179], v224 offset:54272
	ds_read_b128 v[164:167], v224 offset:55296
	ds_read_b128 v[168:171], v224 offset:56320
	global_load_lds_dwordx4 v[2:3], off
	s_add_i32 m0, s58, 0x2000
	s_add_u32 s56, s56, 0x80080
	v_lshl_add_u64 v[2:3], v[212:213], 0, s[16:17]
	s_addc_u32 s57, s57, 0
	s_add_i32 s58, s79, s48
	global_load_lds_dwordx4 v[2:3], off
	v_lshl_add_u64 v[2:3], s[56:57], 0, v[198:199]
	s_mov_b32 m0, s58
	s_and_b64 vcc, exec, s[10:11]
	global_load_lds_dwordx4 v[2:3], off
	v_lshl_add_u64 v[2:3], s[56:57], 0, v[202:203]
	s_add_i32 m0, s58, 0x2000
	s_nop 0
	global_load_lds_dwordx4 v[2:3], off
	v_lshl_add_u64 v[2:3], v[214:215], 0, s[16:17]
	s_mov_b32 m0, s63
	s_nop 0
	global_load_lds_dwordx4 v[2:3], off
	v_lshl_add_u64 v[2:3], v[216:217], 0, s[16:17]
	s_mov_b32 m0, s64
	s_nop 0
	global_load_lds_dwordx4 v[2:3], off
	s_waitcnt vmcnt(8)
	s_waitcnt lgkmcnt(0)
	s_cbranch_vccnz .Lsegskip_1
	s_setprio 1
	s_barrier
	v_mfma_f32_16x16x32_bf16 v[56:59], v[148:151], v[188:191], v[56:59]
	v_mfma_f32_16x16x32_bf16 v[52:55], v[156:159], v[188:191], v[52:55]
	v_mfma_f32_16x16x32_bf16 v[40:43], v[148:151], v[180:183], v[40:43]
	v_mfma_f32_16x16x32_bf16 v[36:39], v[156:159], v[180:183], v[36:39]
	v_mfma_f32_16x16x32_bf16 v[24:27], v[148:151], v[172:175], v[24:27]
	v_mfma_f32_16x16x32_bf16 v[20:23], v[156:159], v[172:175], v[20:23]
	v_mfma_f32_16x16x32_bf16 v[8:11], v[148:151], v[164:167], v[8:11]
	v_mfma_f32_16x16x32_bf16 v[2:5], v[156:159], v[164:167], v[4:7]
	v_mfma_f32_16x16x32_bf16 v[56:59], v[152:155], v[192:195], v[56:59]
	v_mfma_f32_16x16x32_bf16 v[52:55], v[160:163], v[192:195], v[52:55]
	v_mfma_f32_16x16x32_bf16 v[40:43], v[152:155], v[184:187], v[40:43]
	v_mfma_f32_16x16x32_bf16 v[36:39], v[160:163], v[184:187], v[36:39]
	v_mfma_f32_16x16x32_bf16 v[24:27], v[152:155], v[176:179], v[24:27]
	v_mfma_f32_16x16x32_bf16 v[20:23], v[160:163], v[176:179], v[20:23]
	v_mfma_f32_16x16x32_bf16 v[8:11], v[152:155], v[168:171], v[8:11]
	v_mfma_f32_16x16x32_bf16 v[4:7], v[160:163], v[168:171], v[2:5]
	v_mfma_f32_16x16x32_bf16 v[64:67], v[132:135], v[188:191], v[64:67]
	v_mfma_f32_16x16x32_bf16 v[60:63], v[140:143], v[188:191], v[60:63]
	v_mfma_f32_16x16x32_bf16 v[48:51], v[132:135], v[180:183], v[48:51]
	v_mfma_f32_16x16x32_bf16 v[44:47], v[140:143], v[180:183], v[44:47]
	v_mfma_f32_16x16x32_bf16 v[32:35], v[132:135], v[172:175], v[32:35]
	v_mfma_f32_16x16x32_bf16 v[28:31], v[140:143], v[172:175], v[28:31]
	v_mfma_f32_16x16x32_bf16 v[16:19], v[132:135], v[164:167], v[16:19]
	v_mfma_f32_16x16x32_bf16 v[12:15], v[140:143], v[164:167], v[12:15]
	v_mfma_f32_16x16x32_bf16 v[64:67], v[136:139], v[192:195], v[64:67]
	v_mfma_f32_16x16x32_bf16 v[60:63], v[144:147], v[192:195], v[60:63]
	v_mfma_f32_16x16x32_bf16 v[48:51], v[136:139], v[184:187], v[48:51]
	v_mfma_f32_16x16x32_bf16 v[44:47], v[144:147], v[184:187], v[44:47]
	v_mfma_f32_16x16x32_bf16 v[32:35], v[136:139], v[176:179], v[32:35]
	v_mfma_f32_16x16x32_bf16 v[28:31], v[144:147], v[176:179], v[28:31]
	v_mfma_f32_16x16x32_bf16 v[16:19], v[136:139], v[168:171], v[16:19]
	v_mfma_f32_16x16x32_bf16 v[12:15], v[144:147], v[168:171], v[12:15]
	s_barrier
	s_setprio 0
	s_branch .Lsegback_1
.Lsegskip_1:
	s_barrier
	s_branch .LBB0_434

.LBB0_523:
	ds_read_b128 v[144:147], v151
	ds_read_b128 v[156:159], v151 offset:1024
	ds_read_b128 v[160:163], v151 offset:2048
	ds_read_b128 v[164:167], v151 offset:3072
	ds_read_b128 v[168:171], v152
	ds_read_b128 v[172:175], v152 offset:1024
	ds_read_b128 v[176:179], v152 offset:2048
	ds_read_b128 v[180:183], v152 offset:3072
	s_add_u32 s36, s34, 0x100
	s_addc_u32 s37, s35, 0
	s_cmpk_eq_i32 s66, 0x54
	s_cselect_b32 s55, s13, s37
	s_cselect_b32 s54, s12, s36
	s_cselect_b32 s53, s31, s47
	s_cselect_b32 s52, s30, s46
	v_lshl_add_u64 v[216:217], s[34:35], 0, v[138:139]
	s_add_i32 m0, s49, 0xc000
	ds_read_b128 v[184:187], v153
	ds_read_b128 v[188:191], v153 offset:1024
	ds_read_b128 v[192:195], v153 offset:2048
	ds_read_b128 v[196:199], v153 offset:3072
	ds_read_b128 v[200:203], v153 offset:4096
	ds_read_b128 v[204:207], v153 offset:5120
	ds_read_b128 v[208:211], v153 offset:6144
	ds_read_b128 v[212:215], v153 offset:7168
	global_load_lds_dwordx4 v[216:217], off
	v_lshl_add_u64 v[216:217], s[34:35], 0, v[136:137]
	s_add_i32 m0, s49, 0xe000
	s_nop 0
	global_load_lds_dwordx4 v[216:217], off
	s_waitcnt vmcnt(8)
	s_waitcnt lgkmcnt(0)
	s_setprio 1
	s_barrier
	v_mfma_f32_16x16x32_bf16 v[124:127], v[144:147], v[184:187], v[124:127]
	v_mfma_f32_16x16x32_bf16 v[120:123], v[160:163], v[184:187], v[120:123]
	v_mfma_f32_16x16x32_bf16 v[108:111], v[144:147], v[192:195], v[108:111]
	v_mfma_f32_16x16x32_bf16 v[104:107], v[160:163], v[192:195], v[104:107]
	v_mfma_f32_16x16x32_bf16 v[92:95], v[144:147], v[200:203], v[92:95]
	v_mfma_f32_16x16x32_bf16 v[88:91], v[160:163], v[200:203], v[88:91]
	v_mfma_f32_16x16x32_bf16 v[76:79], v[144:147], v[208:211], v[76:79]
	v_mfma_f32_16x16x32_bf16 v[72:75], v[160:163], v[208:211], v[72:75]
	v_mfma_f32_16x16x32_bf16 v[124:127], v[156:159], v[188:191], v[124:127]
	v_mfma_f32_16x16x32_bf16 v[120:123], v[164:167], v[188:191], v[120:123]
	v_mfma_f32_16x16x32_bf16 v[108:111], v[156:159], v[196:199], v[108:111]
	v_mfma_f32_16x16x32_bf16 v[104:107], v[164:167], v[196:199], v[104:107]
	v_mfma_f32_16x16x32_bf16 v[92:95], v[156:159], v[204:207], v[92:95]
	v_mfma_f32_16x16x32_bf16 v[88:91], v[164:167], v[204:207], v[88:91]
	v_mfma_f32_16x16x32_bf16 v[76:79], v[156:159], v[212:215], v[76:79]
	v_mfma_f32_16x16x32_bf16 v[72:75], v[164:167], v[212:215], v[72:75]
	v_mfma_f32_16x16x32_bf16 v[116:119], v[168:171], v[184:187], v[116:119]
	v_mfma_f32_16x16x32_bf16 v[112:115], v[176:179], v[184:187], v[112:115]
	v_mfma_f32_16x16x32_bf16 v[100:103], v[168:171], v[192:195], v[100:103]
	v_mfma_f32_16x16x32_bf16 v[96:99], v[176:179], v[192:195], v[96:99]
	v_mfma_f32_16x16x32_bf16 v[84:87], v[168:171], v[200:203], v[84:87]
	v_mfma_f32_16x16x32_bf16 v[80:83], v[176:179], v[200:203], v[80:83]
	v_mfma_f32_16x16x32_bf16 v[68:71], v[168:171], v[208:211], v[68:71]
	v_mfma_f32_16x16x32_bf16 v[64:67], v[176:179], v[208:211], v[64:67]
	v_mfma_f32_16x16x32_bf16 v[116:119], v[172:175], v[188:191], v[116:119]
	v_mfma_f32_16x16x32_bf16 v[112:115], v[180:183], v[188:191], v[112:115]
	v_mfma_f32_16x16x32_bf16 v[100:103], v[172:175], v[196:199], v[100:103]
	v_mfma_f32_16x16x32_bf16 v[96:99], v[180:183], v[196:199], v[96:99]
	v_mfma_f32_16x16x32_bf16 v[84:87], v[172:175], v[204:207], v[84:87]
	v_mfma_f32_16x16x32_bf16 v[80:83], v[180:183], v[204:207], v[80:83]
	v_mfma_f32_16x16x32_bf16 v[68:71], v[172:175], v[212:215], v[68:71]
	v_mfma_f32_16x16x32_bf16 v[64:67], v[180:183], v[212:215], v[64:67]
	s_barrier
	s_setprio 0
	s_add_i32 s34, s62, s48
	v_lshl_add_u64 v[216:217], s[52:53], 0, v[130:131]
	s_mov_b32 m0, s34
	ds_read_b128 v[184:187], v153 offset:16384
	ds_read_b128 v[188:191], v153 offset:17408
	ds_read_b128 v[192:195], v153 offset:18432
	ds_read_b128 v[196:199], v153 offset:19456
	ds_read_b128 v[200:203], v153 offset:20480
	ds_read_b128 v[204:207], v153 offset:21504
	ds_read_b128 v[208:211], v153 offset:22528
	ds_read_b128 v[212:215], v153 offset:23552
	global_load_lds_dwordx4 v[216:217], off
	s_add_i32 m0, s34, 0x2000
	s_add_u32 s34, s52, 0x160000
	v_lshl_add_u64 v[218:219], s[52:53], 0, v[134:135]
	s_addc_u32 s35, s53, 0
	s_add_i32 s67, s63, s48
	global_load_lds_dwordx4 v[218:219], off
	v_lshl_add_u64 v[220:221], s[34:35], 0, v[130:131]
	s_mov_b32 m0, s67
	v_lshl_add_u64 v[222:223], s[54:55], 0, v[132:133]
	global_load_lds_dwordx4 v[220:221], off
	v_lshl_add_u64 v[220:221], s[34:35], 0, v[134:135]
	s_add_i32 m0, s67, 0x2000
	s_nop 0
	global_load_lds_dwordx4 v[220:221], off
	v_lshl_add_u64 v[220:221], s[54:55], 0, v[128:129]
	s_mov_b32 m0, s49
	s_nop 0
	global_load_lds_dwordx4 v[220:221], off
	s_mov_b32 m0, s56
	s_nop 0
	global_load_lds_dwordx4 v[222:223], off
	s_waitcnt vmcnt(8)
	s_waitcnt lgkmcnt(0)
	s_setprio 1
	s_barrier
	v_mfma_f32_16x16x32_bf16 v[60:63], v[144:147], v[184:187], v[60:63]
	v_mfma_f32_16x16x32_bf16 v[56:59], v[160:163], v[184:187], v[56:59]
	v_mfma_f32_16x16x32_bf16 v[44:47], v[144:147], v[192:195], v[44:47]
	v_mfma_f32_16x16x32_bf16 v[40:43], v[160:163], v[192:195], v[40:43]
	v_mfma_f32_16x16x32_bf16 v[28:31], v[144:147], v[200:203], v[28:31]
	v_mfma_f32_16x16x32_bf16 v[24:27], v[160:163], v[200:203], v[24:27]
	v_mfma_f32_16x16x32_bf16 v[12:15], v[144:147], v[208:211], v[12:15]
	v_mfma_f32_16x16x32_bf16 v[8:11], v[160:163], v[208:211], v[8:11]
	v_mfma_f32_16x16x32_bf16 v[60:63], v[156:159], v[188:191], v[60:63]
	v_mfma_f32_16x16x32_bf16 v[56:59], v[164:167], v[188:191], v[56:59]
	v_mfma_f32_16x16x32_bf16 v[44:47], v[156:159], v[196:199], v[44:47]
	v_mfma_f32_16x16x32_bf16 v[40:43], v[164:167], v[196:199], v[40:43]
	v_mfma_f32_16x16x32_bf16 v[28:31], v[156:159], v[204:207], v[28:31]
	v_mfma_f32_16x16x32_bf16 v[24:27], v[164:167], v[204:207], v[24:27]
	v_mfma_f32_16x16x32_bf16 v[12:15], v[156:159], v[212:215], v[12:15]
	v_mfma_f32_16x16x32_bf16 v[8:11], v[164:167], v[212:215], v[8:11]
	v_mfma_f32_16x16x32_bf16 v[52:55], v[168:171], v[184:187], v[52:55]
	v_mfma_f32_16x16x32_bf16 v[48:51], v[176:179], v[184:187], v[48:51]
	v_mfma_f32_16x16x32_bf16 v[36:39], v[168:171], v[192:195], v[36:39]
	v_mfma_f32_16x16x32_bf16 v[32:35], v[176:179], v[192:195], v[32:35]
	v_mfma_f32_16x16x32_bf16 v[20:23], v[168:171], v[200:203], v[20:23]
	v_mfma_f32_16x16x32_bf16 v[16:19], v[176:179], v[200:203], v[16:19]
	v_mfma_f32_16x16x32_bf16 v[4:7], v[168:171], v[208:211], v[4:7]
	v_mfma_f32_16x16x32_bf16 v[0:3], v[176:179], v[208:211], v[0:3]
	v_mfma_f32_16x16x32_bf16 v[52:55], v[172:175], v[188:191], v[52:55]
	v_mfma_f32_16x16x32_bf16 v[48:51], v[180:183], v[188:191], v[48:51]
	v_mfma_f32_16x16x32_bf16 v[36:39], v[172:175], v[196:199], v[36:39]
	v_mfma_f32_16x16x32_bf16 v[32:35], v[180:183], v[196:199], v[32:35]
	v_mfma_f32_16x16x32_bf16 v[20:23], v[172:175], v[204:207], v[20:23]
	v_mfma_f32_16x16x32_bf16 v[16:19], v[180:183], v[204:207], v[16:19]
	v_mfma_f32_16x16x32_bf16 v[4:7], v[172:175], v[212:215], v[4:7]
	v_mfma_f32_16x16x32_bf16 v[0:3], v[180:183], v[212:215], v[0:3]
	s_barrier
	s_setprio 0
	s_add_i32 s67, 0, 0x18000
	v_add_u32_e32 v155, s67, v149
	s_add_i32 s70, 0, 0x1c000
	ds_read_b128 v[144:147], v155
	ds_read_b128 v[156:159], v155 offset:1024
	ds_read_b128 v[160:163], v155 offset:2048
	ds_read_b128 v[164:167], v155 offset:3072
	v_add_u32_e32 v155, s70, v149
	ds_read_b128 v[168:171], v155
	ds_read_b128 v[172:175], v155 offset:1024
	ds_read_b128 v[176:179], v155 offset:2048
	ds_read_b128 v[180:183], v155 offset:3072
	s_add_u32 s34, s54, 0x160000
	s_addc_u32 s35, s55, 0
	s_mov_b32 m0, s57
	v_lshl_add_u64 v[224:225], s[34:35], 0, v[128:129]
	ds_read_b128 v[184:187], v153 offset:32768
	ds_read_b128 v[188:191], v153 offset:33792
	ds_read_b128 v[192:195], v153 offset:34816
	ds_read_b128 v[196:199], v153 offset:35840
	ds_read_b128 v[200:203], v153 offset:36864
	ds_read_b128 v[204:207], v153 offset:37888
	ds_read_b128 v[208:211], v153 offset:38912
	ds_read_b128 v[212:215], v153 offset:39936
	global_load_lds_dwordx4 v[224:225], off
	v_lshl_add_u64 v[224:225], s[34:35], 0, v[132:133]
	s_mov_b32 m0, s58
	s_nop 0
	global_load_lds_dwordx4 v[224:225], off
	s_waitcnt vmcnt(8)
	s_waitcnt lgkmcnt(0)
	s_setprio 1
	s_barrier
	v_mfma_f32_16x16x32_bf16 v[124:127], v[144:147], v[184:187], v[124:127]
	v_mfma_f32_16x16x32_bf16 v[120:123], v[160:163], v[184:187], v[120:123]
	v_mfma_f32_16x16x32_bf16 v[108:111], v[144:147], v[192:195], v[108:111]
	v_mfma_f32_16x16x32_bf16 v[104:107], v[160:163], v[192:195], v[104:107]
	v_mfma_f32_16x16x32_bf16 v[92:95], v[144:147], v[200:203], v[92:95]
	v_mfma_f32_16x16x32_bf16 v[88:91], v[160:163], v[200:203], v[88:91]
	v_mfma_f32_16x16x32_bf16 v[76:79], v[144:147], v[208:211], v[76:79]
	v_mfma_f32_16x16x32_bf16 v[72:75], v[160:163], v[208:211], v[72:75]
	v_mfma_f32_16x16x32_bf16 v[124:127], v[156:159], v[188:191], v[124:127]
	v_mfma_f32_16x16x32_bf16 v[120:123], v[164:167], v[188:191], v[120:123]
	v_mfma_f32_16x16x32_bf16 v[108:111], v[156:159], v[196:199], v[108:111]
	v_mfma_f32_16x16x32_bf16 v[104:107], v[164:167], v[196:199], v[104:107]
	v_mfma_f32_16x16x32_bf16 v[92:95], v[156:159], v[204:207], v[92:95]
	v_mfma_f32_16x16x32_bf16 v[88:91], v[164:167], v[204:207], v[88:91]
	v_mfma_f32_16x16x32_bf16 v[76:79], v[156:159], v[212:215], v[76:79]
	v_mfma_f32_16x16x32_bf16 v[72:75], v[164:167], v[212:215], v[72:75]
	v_mfma_f32_16x16x32_bf16 v[116:119], v[168:171], v[184:187], v[116:119]
	v_mfma_f32_16x16x32_bf16 v[112:115], v[176:179], v[184:187], v[112:115]
	v_mfma_f32_16x16x32_bf16 v[100:103], v[168:171], v[192:195], v[100:103]
	v_mfma_f32_16x16x32_bf16 v[96:99], v[176:179], v[192:195], v[96:99]
	v_mfma_f32_16x16x32_bf16 v[84:87], v[168:171], v[200:203], v[84:87]
	v_mfma_f32_16x16x32_bf16 v[80:83], v[176:179], v[200:203], v[80:83]
	v_mfma_f32_16x16x32_bf16 v[68:71], v[168:171], v[208:211], v[68:71]
	v_mfma_f32_16x16x32_bf16 v[64:67], v[176:179], v[208:211], v[64:67]
	v_mfma_f32_16x16x32_bf16 v[116:119], v[172:175], v[188:191], v[116:119]
	v_mfma_f32_16x16x32_bf16 v[112:115], v[180:183], v[188:191], v[112:115]
	v_mfma_f32_16x16x32_bf16 v[100:103], v[172:175], v[196:199], v[100:103]
	v_mfma_f32_16x16x32_bf16 v[96:99], v[180:183], v[196:199], v[96:99]
	v_mfma_f32_16x16x32_bf16 v[84:87], v[172:175], v[204:207], v[84:87]
	v_mfma_f32_16x16x32_bf16 v[80:83], v[180:183], v[204:207], v[80:83]
	v_mfma_f32_16x16x32_bf16 v[68:71], v[172:175], v[212:215], v[68:71]
	v_mfma_f32_16x16x32_bf16 v[64:67], v[180:183], v[212:215], v[64:67]
	s_barrier
	s_setprio 0
	s_add_i32 s34, s67, s48
	v_lshl_add_u64 v[216:217], v[216:217], 0, s[24:25]
	s_mov_b32 m0, s34
	ds_read_b128 v[184:187], v153 offset:49152
	ds_read_b128 v[188:191], v153 offset:50176
	ds_read_b128 v[192:195], v153 offset:51200
	ds_read_b128 v[196:199], v153 offset:52224
	ds_read_b128 v[200:203], v153 offset:53248
	ds_read_b128 v[204:207], v153 offset:54272
	ds_read_b128 v[208:211], v153 offset:55296
	ds_read_b128 v[212:215], v153 offset:56320
	global_load_lds_dwordx4 v[216:217], off
	s_add_i32 m0, s34, 0x2000
	s_add_u32 s34, s52, 0x160080
	v_lshl_add_u64 v[216:217], v[218:219], 0, s[24:25]
	s_addc_u32 s35, s53, 0
	s_add_i32 s52, s70, s48
	global_load_lds_dwordx4 v[216:217], off
	v_lshl_add_u64 v[216:217], s[34:35], 0, v[130:131]
	s_mov_b32 m0, s52
	s_nop 0
	global_load_lds_dwordx4 v[216:217], off
	v_lshl_add_u64 v[216:217], s[34:35], 0, v[134:135]
	s_add_i32 m0, s52, 0x2000
	s_nop 0
	global_load_lds_dwordx4 v[216:217], off
	v_lshl_add_u64 v[216:217], v[220:221], 0, s[24:25]
	s_mov_b32 m0, s60
	s_nop 0
	global_load_lds_dwordx4 v[216:217], off
	v_lshl_add_u64 v[216:217], v[222:223], 0, s[24:25]
	s_mov_b32 m0, s61
	s_nop 0
	global_load_lds_dwordx4 v[216:217], off
	s_waitcnt vmcnt(8)
	s_waitcnt lgkmcnt(0)
	s_setprio 1
	s_barrier
	v_mfma_f32_16x16x32_bf16 v[60:63], v[144:147], v[184:187], v[60:63]
	v_mfma_f32_16x16x32_bf16 v[56:59], v[160:163], v[184:187], v[56:59]
	v_mfma_f32_16x16x32_bf16 v[44:47], v[144:147], v[192:195], v[44:47]
	v_mfma_f32_16x16x32_bf16 v[40:43], v[160:163], v[192:195], v[40:43]
	v_mfma_f32_16x16x32_bf16 v[28:31], v[144:147], v[200:203], v[28:31]
	v_mfma_f32_16x16x32_bf16 v[24:27], v[160:163], v[200:203], v[24:27]
	v_mfma_f32_16x16x32_bf16 v[12:15], v[144:147], v[208:211], v[12:15]
	v_mfma_f32_16x16x32_bf16 v[8:11], v[160:163], v[208:211], v[8:11]
	v_mfma_f32_16x16x32_bf16 v[60:63], v[156:159], v[188:191], v[60:63]
	v_mfma_f32_16x16x32_bf16 v[56:59], v[164:167], v[188:191], v[56:59]
	v_mfma_f32_16x16x32_bf16 v[44:47], v[156:159], v[196:199], v[44:47]
	v_mfma_f32_16x16x32_bf16 v[40:43], v[164:167], v[196:199], v[40:43]
	v_mfma_f32_16x16x32_bf16 v[28:31], v[156:159], v[204:207], v[28:31]
	v_mfma_f32_16x16x32_bf16 v[24:27], v[164:167], v[204:207], v[24:27]
	v_mfma_f32_16x16x32_bf16 v[12:15], v[156:159], v[212:215], v[12:15]
	v_mfma_f32_16x16x32_bf16 v[8:11], v[164:167], v[212:215], v[8:11]
	v_mfma_f32_16x16x32_bf16 v[52:55], v[168:171], v[184:187], v[52:55]
	v_mfma_f32_16x16x32_bf16 v[48:51], v[176:179], v[184:187], v[48:51]
	v_mfma_f32_16x16x32_bf16 v[36:39], v[168:171], v[192:195], v[36:39]
	v_mfma_f32_16x16x32_bf16 v[32:35], v[176:179], v[192:195], v[32:35]
	v_mfma_f32_16x16x32_bf16 v[20:23], v[168:171], v[200:203], v[20:23]
	v_mfma_f32_16x16x32_bf16 v[16:19], v[176:179], v[200:203], v[16:19]
	v_mfma_f32_16x16x32_bf16 v[4:7], v[168:171], v[208:211], v[4:7]
	v_mfma_f32_16x16x32_bf16 v[0:3], v[176:179], v[208:211], v[0:3]
	v_mfma_f32_16x16x32_bf16 v[52:55], v[172:175], v[188:191], v[52:55]
	v_mfma_f32_16x16x32_bf16 v[48:51], v[180:183], v[188:191], v[48:51]
	v_mfma_f32_16x16x32_bf16 v[36:39], v[172:175], v[196:199], v[36:39]
	v_mfma_f32_16x16x32_bf16 v[32:35], v[180:183], v[196:199], v[32:35]
	v_mfma_f32_16x16x32_bf16 v[20:23], v[172:175], v[204:207], v[20:23]
	v_mfma_f32_16x16x32_bf16 v[16:19], v[180:183], v[204:207], v[16:19]
	v_mfma_f32_16x16x32_bf16 v[4:7], v[172:175], v[212:215], v[4:7]
	v_mfma_f32_16x16x32_bf16 v[0:3], v[180:183], v[212:215], v[0:3]
	s_barrier
	s_setprio 0
	s_add_i32 s66, s66, 2
	s_add_u32 s46, s46, 0x100
	s_addc_u32 s47, s47, 0
	s_cmpk_gt_u32 s66, 0x55
	s_mov_b64 s[34:35], s[36:37]
	s_cbranch_scc0 .LBB0_523
	s_and_b64 vcc, exec, s[26:27]
	s_cbranch_vccz .LBB0_526
	s_barrier

.LBB0_617:
	ds_read_b128 v[146:149], v159
	ds_read_b128 v[150:153], v159 offset:1024
	ds_read_b128 v[164:167], v159 offset:2048
	ds_read_b128 v[168:171], v159 offset:3072
	ds_read_b128 v[172:175], v160
	ds_read_b128 v[176:179], v160 offset:1024
	ds_read_b128 v[180:183], v160 offset:2048
	ds_read_b128 v[184:187], v160 offset:3072
	s_add_u32 s58, s56, 0xfff80080
	s_addc_u32 s59, s57, -1
	s_cmp_eq_u32 s55, 28
	s_cselect_b32 s61, s35, s59
	s_cselect_b32 s60, s46, s58
	s_cselect_b32 s59, s31, s51
	s_cselect_b32 s58, s47, s50
	v_lshl_add_u64 v[154:155], s[56:57], 0, v[140:141]
	s_add_i32 m0, s45, 0xc000
	ds_read_b128 v[188:191], v161
	ds_read_b128 v[192:195], v161 offset:1024
	ds_read_b128 v[196:199], v161 offset:2048
	ds_read_b128 v[200:203], v161 offset:3072
	ds_read_b128 v[204:207], v161 offset:4096
	ds_read_b128 v[208:211], v161 offset:5120
	ds_read_b128 v[212:215], v161 offset:6144
	ds_read_b128 v[216:219], v161 offset:7168
	global_load_lds_dwordx4 v[154:155], off
	v_lshl_add_u64 v[154:155], s[56:57], 0, v[138:139]
	s_add_i32 m0, s45, 0xe000
	s_nop 0
	global_load_lds_dwordx4 v[154:155], off
	s_waitcnt vmcnt(8)
	s_waitcnt lgkmcnt(0)
	s_setprio 1
	s_barrier
	v_mfma_f32_16x16x32_bf16 v[124:127], v[146:149], v[188:191], v[124:127]
	v_mfma_f32_16x16x32_bf16 v[120:123], v[164:167], v[188:191], v[120:123]
	v_mfma_f32_16x16x32_bf16 v[108:111], v[146:149], v[196:199], v[108:111]
	v_mfma_f32_16x16x32_bf16 v[104:107], v[164:167], v[196:199], v[104:107]
	v_mfma_f32_16x16x32_bf16 v[92:95], v[146:149], v[204:207], v[92:95]
	v_mfma_f32_16x16x32_bf16 v[88:91], v[164:167], v[204:207], v[88:91]
	v_mfma_f32_16x16x32_bf16 v[76:79], v[146:149], v[212:215], v[76:79]
	v_mfma_f32_16x16x32_bf16 v[72:75], v[164:167], v[212:215], v[72:75]
	v_mfma_f32_16x16x32_bf16 v[124:127], v[150:153], v[192:195], v[124:127]
	v_mfma_f32_16x16x32_bf16 v[120:123], v[168:171], v[192:195], v[120:123]
	v_mfma_f32_16x16x32_bf16 v[108:111], v[150:153], v[200:203], v[108:111]
	v_mfma_f32_16x16x32_bf16 v[104:107], v[168:171], v[200:203], v[104:107]
	v_mfma_f32_16x16x32_bf16 v[92:95], v[150:153], v[208:211], v[92:95]
	v_mfma_f32_16x16x32_bf16 v[88:91], v[168:171], v[208:211], v[88:91]
	v_mfma_f32_16x16x32_bf16 v[76:79], v[150:153], v[216:219], v[76:79]
	v_mfma_f32_16x16x32_bf16 v[72:75], v[168:171], v[216:219], v[72:75]
	v_mfma_f32_16x16x32_bf16 v[116:119], v[172:175], v[188:191], v[116:119]
	v_mfma_f32_16x16x32_bf16 v[112:115], v[180:183], v[188:191], v[112:115]
	v_mfma_f32_16x16x32_bf16 v[100:103], v[172:175], v[196:199], v[100:103]
	v_mfma_f32_16x16x32_bf16 v[96:99], v[180:183], v[196:199], v[96:99]
	v_mfma_f32_16x16x32_bf16 v[84:87], v[172:175], v[204:207], v[84:87]
	v_mfma_f32_16x16x32_bf16 v[80:83], v[180:183], v[204:207], v[80:83]
	v_mfma_f32_16x16x32_bf16 v[68:71], v[172:175], v[212:215], v[68:71]
	v_mfma_f32_16x16x32_bf16 v[64:67], v[180:183], v[212:215], v[64:67]
	v_mfma_f32_16x16x32_bf16 v[116:119], v[176:179], v[192:195], v[116:119]
	v_mfma_f32_16x16x32_bf16 v[112:115], v[184:187], v[192:195], v[112:115]
	v_mfma_f32_16x16x32_bf16 v[100:103], v[176:179], v[200:203], v[100:103]
	v_mfma_f32_16x16x32_bf16 v[96:99], v[184:187], v[200:203], v[96:99]
	v_mfma_f32_16x16x32_bf16 v[84:87], v[176:179], v[208:211], v[84:87]
	v_mfma_f32_16x16x32_bf16 v[80:83], v[184:187], v[208:211], v[80:83]
	v_mfma_f32_16x16x32_bf16 v[68:71], v[176:179], v[216:219], v[68:71]
	v_mfma_f32_16x16x32_bf16 v[64:67], v[184:187], v[216:219], v[64:67]
	s_barrier
	s_setprio 0
	s_add_i32 s72, s66, s44
	v_lshl_add_u64 v[154:155], s[58:59], 0, v[130:131]
	s_mov_b32 m0, s72
	ds_read_b128 v[188:191], v161 offset:16384
	ds_read_b128 v[192:195], v161 offset:17408
	ds_read_b128 v[196:199], v161 offset:18432
	ds_read_b128 v[200:203], v161 offset:19456
	ds_read_b128 v[204:207], v161 offset:20480
	ds_read_b128 v[208:211], v161 offset:21504
	ds_read_b128 v[212:215], v161 offset:22528
	ds_read_b128 v[216:219], v161 offset:23552
	global_load_lds_dwordx4 v[154:155], off
	s_add_i32 m0, s72, 0x2000
	s_add_u32 s80, s58, 0x80000
	v_lshl_add_u64 v[220:221], s[58:59], 0, v[134:135]
	s_addc_u32 s81, s59, 0
	s_add_i32 s72, s67, s44
	global_load_lds_dwordx4 v[220:221], off
	v_lshl_add_u64 v[222:223], s[80:81], 0, v[130:131]
	s_mov_b32 m0, s72
	v_lshl_add_u64 v[224:225], s[60:61], 0, v[132:133]
	global_load_lds_dwordx4 v[222:223], off
	v_lshl_add_u64 v[222:223], s[80:81], 0, v[134:135]
	s_add_i32 m0, s72, 0x2000
	s_nop 0
	global_load_lds_dwordx4 v[222:223], off
	v_lshl_add_u64 v[222:223], s[60:61], 0, v[128:129]
	s_mov_b32 m0, s45
	s_nop 0
	global_load_lds_dwordx4 v[222:223], off
	s_mov_b32 m0, s48
	s_nop 0
	global_load_lds_dwordx4 v[224:225], off
	s_waitcnt vmcnt(8)
	s_waitcnt lgkmcnt(0)
	s_setprio 1
	s_barrier
	v_mfma_f32_16x16x32_bf16 v[60:63], v[146:149], v[188:191], v[60:63]
	v_mfma_f32_16x16x32_bf16 v[56:59], v[164:167], v[188:191], v[56:59]
	v_mfma_f32_16x16x32_bf16 v[44:47], v[146:149], v[196:199], v[44:47]
	v_mfma_f32_16x16x32_bf16 v[40:43], v[164:167], v[196:199], v[40:43]
	v_mfma_f32_16x16x32_bf16 v[28:31], v[146:149], v[204:207], v[28:31]
	v_mfma_f32_16x16x32_bf16 v[24:27], v[164:167], v[204:207], v[24:27]
	v_mfma_f32_16x16x32_bf16 v[12:15], v[146:149], v[212:215], v[12:15]
	v_mfma_f32_16x16x32_bf16 v[8:11], v[164:167], v[212:215], v[8:11]
	v_mfma_f32_16x16x32_bf16 v[60:63], v[150:153], v[192:195], v[60:63]
	v_mfma_f32_16x16x32_bf16 v[56:59], v[168:171], v[192:195], v[56:59]
	v_mfma_f32_16x16x32_bf16 v[44:47], v[150:153], v[200:203], v[44:47]
	v_mfma_f32_16x16x32_bf16 v[40:43], v[168:171], v[200:203], v[40:43]
	v_mfma_f32_16x16x32_bf16 v[28:31], v[150:153], v[208:211], v[28:31]
	v_mfma_f32_16x16x32_bf16 v[24:27], v[168:171], v[208:211], v[24:27]
	v_mfma_f32_16x16x32_bf16 v[12:15], v[150:153], v[216:219], v[12:15]
	v_mfma_f32_16x16x32_bf16 v[8:11], v[168:171], v[216:219], v[8:11]
	v_mfma_f32_16x16x32_bf16 v[52:55], v[172:175], v[188:191], v[52:55]
	v_mfma_f32_16x16x32_bf16 v[48:51], v[180:183], v[188:191], v[48:51]
	v_mfma_f32_16x16x32_bf16 v[36:39], v[172:175], v[196:199], v[36:39]
	v_mfma_f32_16x16x32_bf16 v[32:35], v[180:183], v[196:199], v[32:35]
	v_mfma_f32_16x16x32_bf16 v[20:23], v[172:175], v[204:207], v[20:23]
	v_mfma_f32_16x16x32_bf16 v[16:19], v[180:183], v[204:207], v[16:19]
	v_mfma_f32_16x16x32_bf16 v[4:7], v[172:175], v[212:215], v[4:7]
	v_mfma_f32_16x16x32_bf16 v[0:3], v[180:183], v[212:215], v[0:3]
	v_mfma_f32_16x16x32_bf16 v[52:55], v[176:179], v[192:195], v[52:55]
	v_mfma_f32_16x16x32_bf16 v[48:51], v[184:187], v[192:195], v[48:51]
	v_mfma_f32_16x16x32_bf16 v[36:39], v[176:179], v[200:203], v[36:39]
	v_mfma_f32_16x16x32_bf16 v[32:35], v[184:187], v[200:203], v[32:35]
	v_mfma_f32_16x16x32_bf16 v[20:23], v[176:179], v[208:211], v[20:23]
	v_mfma_f32_16x16x32_bf16 v[16:19], v[184:187], v[208:211], v[16:19]
	v_mfma_f32_16x16x32_bf16 v[4:7], v[176:179], v[216:219], v[4:7]
	v_mfma_f32_16x16x32_bf16 v[0:3], v[184:187], v[216:219], v[0:3]
	s_barrier
	s_setprio 0
	s_add_i32 s72, 0, 0x18000
	s_add_i32 s78, 0, 0x1c000
	v_add_u32_e32 v168, s72, v157
	v_add_u32_e32 v184, s78, v157
	ds_read_b128 v[146:149], v168
	ds_read_b128 v[150:153], v168 offset:1024
	ds_read_b128 v[164:167], v168 offset:2048
	ds_read_b128 v[168:171], v168 offset:3072
	ds_read_b128 v[172:175], v184
	ds_read_b128 v[176:179], v184 offset:1024
	ds_read_b128 v[180:183], v184 offset:2048
	ds_read_b128 v[184:187], v184 offset:3072
	s_add_u32 s60, s60, 0x80000
	s_addc_u32 s61, s61, 0
	s_mov_b32 m0, s49
	v_lshl_add_u64 v[226:227], s[60:61], 0, v[128:129]
	ds_read_b128 v[188:191], v161 offset:32768
	ds_read_b128 v[192:195], v161 offset:33792
	ds_read_b128 v[196:199], v161 offset:34816
	ds_read_b128 v[200:203], v161 offset:35840
	ds_read_b128 v[204:207], v161 offset:36864
	ds_read_b128 v[208:211], v161 offset:37888
	ds_read_b128 v[212:215], v161 offset:38912
	ds_read_b128 v[216:219], v161 offset:39936
	global_load_lds_dwordx4 v[226:227], off
	v_lshl_add_u64 v[226:227], s[60:61], 0, v[132:133]
	s_mov_b32 m0, s62
	s_nop 0
	global_load_lds_dwordx4 v[226:227], off
	s_waitcnt vmcnt(8)
	s_waitcnt lgkmcnt(0)
	s_setprio 1
	s_barrier
	v_mfma_f32_16x16x32_bf16 v[124:127], v[146:149], v[188:191], v[124:127]
	v_mfma_f32_16x16x32_bf16 v[120:123], v[164:167], v[188:191], v[120:123]
	v_mfma_f32_16x16x32_bf16 v[108:111], v[146:149], v[196:199], v[108:111]
	v_mfma_f32_16x16x32_bf16 v[104:107], v[164:167], v[196:199], v[104:107]
	v_mfma_f32_16x16x32_bf16 v[92:95], v[146:149], v[204:207], v[92:95]
	v_mfma_f32_16x16x32_bf16 v[88:91], v[164:167], v[204:207], v[88:91]
	v_mfma_f32_16x16x32_bf16 v[76:79], v[146:149], v[212:215], v[76:79]
	v_mfma_f32_16x16x32_bf16 v[72:75], v[164:167], v[212:215], v[72:75]
	v_mfma_f32_16x16x32_bf16 v[124:127], v[150:153], v[192:195], v[124:127]
	v_mfma_f32_16x16x32_bf16 v[120:123], v[168:171], v[192:195], v[120:123]
	v_mfma_f32_16x16x32_bf16 v[108:111], v[150:153], v[200:203], v[108:111]
	v_mfma_f32_16x16x32_bf16 v[104:107], v[168:171], v[200:203], v[104:107]
	v_mfma_f32_16x16x32_bf16 v[92:95], v[150:153], v[208:211], v[92:95]
	v_mfma_f32_16x16x32_bf16 v[88:91], v[168:171], v[208:211], v[88:91]
	v_mfma_f32_16x16x32_bf16 v[76:79], v[150:153], v[216:219], v[76:79]
	v_mfma_f32_16x16x32_bf16 v[72:75], v[168:171], v[216:219], v[72:75]
	v_mfma_f32_16x16x32_bf16 v[116:119], v[172:175], v[188:191], v[116:119]
	v_mfma_f32_16x16x32_bf16 v[112:115], v[180:183], v[188:191], v[112:115]
	v_mfma_f32_16x16x32_bf16 v[100:103], v[172:175], v[196:199], v[100:103]
	v_mfma_f32_16x16x32_bf16 v[96:99], v[180:183], v[196:199], v[96:99]
	v_mfma_f32_16x16x32_bf16 v[84:87], v[172:175], v[204:207], v[84:87]
	v_mfma_f32_16x16x32_bf16 v[80:83], v[180:183], v[204:207], v[80:83]
	v_mfma_f32_16x16x32_bf16 v[68:71], v[172:175], v[212:215], v[68:71]
	v_mfma_f32_16x16x32_bf16 v[64:67], v[180:183], v[212:215], v[64:67]
	v_mfma_f32_16x16x32_bf16 v[116:119], v[176:179], v[192:195], v[116:119]
	v_mfma_f32_16x16x32_bf16 v[112:115], v[184:187], v[192:195], v[112:115]
	v_mfma_f32_16x16x32_bf16 v[100:103], v[176:179], v[200:203], v[100:103]
	v_mfma_f32_16x16x32_bf16 v[96:99], v[184:187], v[200:203], v[96:99]
	v_mfma_f32_16x16x32_bf16 v[84:87], v[176:179], v[208:211], v[84:87]
	v_mfma_f32_16x16x32_bf16 v[80:83], v[184:187], v[208:211], v[80:83]
	v_mfma_f32_16x16x32_bf16 v[68:71], v[176:179], v[216:219], v[68:71]
	v_mfma_f32_16x16x32_bf16 v[64:67], v[184:187], v[216:219], v[64:67]
	s_barrier
	s_setprio 0
	s_add_i32 s60, s72, s44
	v_lshl_add_u64 v[154:155], v[154:155], 0, s[24:25]
	s_mov_b32 m0, s60
	ds_read_b128 v[188:191], v161 offset:49152
	ds_read_b128 v[192:195], v161 offset:50176
	ds_read_b128 v[196:199], v161 offset:51200
	ds_read_b128 v[200:203], v161 offset:52224
	ds_read_b128 v[204:207], v161 offset:53248
	ds_read_b128 v[208:211], v161 offset:54272
	ds_read_b128 v[212:215], v161 offset:55296
	ds_read_b128 v[216:219], v161 offset:56320
	global_load_lds_dwordx4 v[154:155], off
	s_add_i32 m0, s60, 0x2000
	s_add_u32 s58, s58, 0x80080
	v_lshl_add_u64 v[154:155], v[220:221], 0, s[24:25]
	s_addc_u32 s59, s59, 0
	s_add_i32 s60, s78, s44
	global_load_lds_dwordx4 v[154:155], off
	v_lshl_add_u64 v[154:155], s[58:59], 0, v[130:131]
	s_mov_b32 m0, s60
	s_nop 0
	global_load_lds_dwordx4 v[154:155], off
	v_lshl_add_u64 v[154:155], s[58:59], 0, v[134:135]
	s_add_i32 m0, s60, 0x2000
	s_nop 0
	global_load_lds_dwordx4 v[154:155], off
	v_lshl_add_u64 v[154:155], v[222:223], 0, s[24:25]
	s_mov_b32 m0, s64
	s_nop 0
	global_load_lds_dwordx4 v[154:155], off
	v_lshl_add_u64 v[154:155], v[224:225], 0, s[24:25]
	s_mov_b32 m0, s65
	s_nop 0
	global_load_lds_dwordx4 v[154:155], off
	s_waitcnt vmcnt(8)
	s_waitcnt lgkmcnt(0)
	s_setprio 1
	s_barrier
	v_mfma_f32_16x16x32_bf16 v[60:63], v[146:149], v[188:191], v[60:63]
	v_mfma_f32_16x16x32_bf16 v[56:59], v[164:167], v[188:191], v[56:59]
	v_mfma_f32_16x16x32_bf16 v[44:47], v[146:149], v[196:199], v[44:47]
	v_mfma_f32_16x16x32_bf16 v[40:43], v[164:167], v[196:199], v[40:43]
	v_mfma_f32_16x16x32_bf16 v[28:31], v[146:149], v[204:207], v[28:31]
	v_mfma_f32_16x16x32_bf16 v[24:27], v[164:167], v[204:207], v[24:27]
	v_mfma_f32_16x16x32_bf16 v[12:15], v[146:149], v[212:215], v[12:15]
	v_mfma_f32_16x16x32_bf16 v[8:11], v[164:167], v[212:215], v[8:11]
	v_mfma_f32_16x16x32_bf16 v[60:63], v[150:153], v[192:195], v[60:63]
	v_mfma_f32_16x16x32_bf16 v[56:59], v[168:171], v[192:195], v[56:59]
	v_mfma_f32_16x16x32_bf16 v[44:47], v[150:153], v[200:203], v[44:47]
	v_mfma_f32_16x16x32_bf16 v[40:43], v[168:171], v[200:203], v[40:43]
	v_mfma_f32_16x16x32_bf16 v[28:31], v[150:153], v[208:211], v[28:31]
	v_mfma_f32_16x16x32_bf16 v[24:27], v[168:171], v[208:211], v[24:27]
	v_mfma_f32_16x16x32_bf16 v[12:15], v[150:153], v[216:219], v[12:15]
	v_mfma_f32_16x16x32_bf16 v[8:11], v[168:171], v[216:219], v[8:11]
	v_mfma_f32_16x16x32_bf16 v[52:55], v[172:175], v[188:191], v[52:55]
	v_mfma_f32_16x16x32_bf16 v[48:51], v[180:183], v[188:191], v[48:51]
	v_mfma_f32_16x16x32_bf16 v[36:39], v[172:175], v[196:199], v[36:39]
	v_mfma_f32_16x16x32_bf16 v[32:35], v[180:183], v[196:199], v[32:35]
	v_mfma_f32_16x16x32_bf16 v[20:23], v[172:175], v[204:207], v[20:23]
	v_mfma_f32_16x16x32_bf16 v[16:19], v[180:183], v[204:207], v[16:19]
	v_mfma_f32_16x16x32_bf16 v[4:7], v[172:175], v[212:215], v[4:7]
	v_mfma_f32_16x16x32_bf16 v[0:3], v[180:183], v[212:215], v[0:3]
	v_mfma_f32_16x16x32_bf16 v[52:55], v[176:179], v[192:195], v[52:55]
	v_mfma_f32_16x16x32_bf16 v[48:51], v[184:187], v[192:195], v[48:51]
	v_mfma_f32_16x16x32_bf16 v[36:39], v[176:179], v[200:203], v[36:39]
	v_mfma_f32_16x16x32_bf16 v[32:35], v[184:187], v[200:203], v[32:35]
	v_mfma_f32_16x16x32_bf16 v[20:23], v[176:179], v[208:211], v[20:23]
	v_mfma_f32_16x16x32_bf16 v[16:19], v[184:187], v[208:211], v[16:19]
	v_mfma_f32_16x16x32_bf16 v[4:7], v[176:179], v[216:219], v[4:7]
	v_mfma_f32_16x16x32_bf16 v[0:3], v[184:187], v[216:219], v[0:3]
	s_barrier
	s_setprio 0
	s_add_i32 s55, s55, 2
	s_add_u32 s50, s50, 0x100
	s_addc_u32 s51, s51, 0
	s_add_u32 s56, s56, 0x100
	s_addc_u32 s57, s57, 0
	s_cmp_gt_u32 s55, 29
	s_cbranch_scc0 .LBB0_617
	s_and_b64 vcc, exec, s[26:27]
	s_cbranch_vccz .LBB0_620
	s_barrier

.LBB0_708:
	ds_read_b128 v[0:3], v145
	ds_read_b128 v[4:7], v145 offset:1024
	ds_read_b128 v[8:11], v145 offset:2048
	ds_read_b128 v[12:15], v145 offset:3072
	ds_read_b128 v[16:19], v146
	ds_read_b128 v[20:23], v146 offset:1024
	ds_read_b128 v[24:27], v146 offset:2048
	ds_read_b128 v[28:31], v146 offset:3072
	s_ashr_i32 s37, s36, 31
	s_lshl_b64 s[52:53], s[36:37], 17
	s_add_u32 s52, s6, s52
	s_addc_u32 s53, s7, s53
	s_and_b64 s[54:55], s[8:9], exec
	s_cselect_b32 s65, s53, s59
	s_cselect_b32 s64, s52, s58
	s_ashr_i32 s35, s34, 31
	s_lshl_b64 s[54:55], s[34:35], 17
	s_add_u32 s54, s44, s54
	s_addc_u32 s55, s45, s55
	s_and_b64 s[62:63], s[8:9], exec
	s_cselect_b32 s63, s55, s61
	s_cselect_b32 s62, s54, s60
	s_add_u32 s86, s58, 0x10080
	s_addc_u32 s87, s59, 0
	s_mov_b32 m0, s72
	v_lshl_add_u64 v[64:65], s[86:87], 0, v[128:129]
	ds_read_b128 v[32:35], v147
	ds_read_b128 v[36:39], v147 offset:1024
	ds_read_b128 v[40:43], v147 offset:2048
	ds_read_b128 v[44:47], v147 offset:3072
	ds_read_b128 v[48:51], v147 offset:4096
	ds_read_b128 v[52:55], v147 offset:5120
	ds_read_b128 v[56:59], v147 offset:6144
	ds_read_b128 v[60:63], v147 offset:7168
	global_load_lds_dwordx4 v[64:65], off
	v_lshl_add_u64 v[64:65], s[86:87], 0, v[132:133]
	s_mov_b32 m0, s80
	s_nop 0
	global_load_lds_dwordx4 v[64:65], off
	s_waitcnt vmcnt(8)
	s_waitcnt lgkmcnt(0)
	s_setprio 1
	s_barrier
	v_mfma_f32_16x16x32_bf16 v[64:67], v[0:3], v[32:35], 0
	v_mfma_f32_16x16x32_bf16 v[68:71], v[8:11], v[32:35], 0
	v_mfma_f32_16x16x32_bf16 v[72:75], v[0:3], v[40:43], 0
	v_mfma_f32_16x16x32_bf16 v[76:79], v[8:11], v[40:43], 0
	v_mfma_f32_16x16x32_bf16 v[80:83], v[0:3], v[48:51], 0
	v_mfma_f32_16x16x32_bf16 v[84:87], v[8:11], v[48:51], 0
	v_mfma_f32_16x16x32_bf16 v[88:91], v[0:3], v[56:59], 0
	v_mfma_f32_16x16x32_bf16 v[92:95], v[8:11], v[56:59], 0
	v_mfma_f32_16x16x32_bf16 v[64:67], v[4:7], v[36:39], v[64:67]
	v_mfma_f32_16x16x32_bf16 v[68:71], v[12:15], v[36:39], v[68:71]
	v_mfma_f32_16x16x32_bf16 v[72:75], v[4:7], v[44:47], v[72:75]
	v_mfma_f32_16x16x32_bf16 v[76:79], v[12:15], v[44:47], v[76:79]
	v_mfma_f32_16x16x32_bf16 v[80:83], v[4:7], v[52:55], v[80:83]
	v_mfma_f32_16x16x32_bf16 v[84:87], v[12:15], v[52:55], v[84:87]
	v_mfma_f32_16x16x32_bf16 v[88:91], v[4:7], v[60:63], v[88:91]
	v_mfma_f32_16x16x32_bf16 v[92:95], v[12:15], v[60:63], v[92:95]
	v_mfma_f32_16x16x32_bf16 v[96:99], v[16:19], v[32:35], 0
	v_mfma_f32_16x16x32_bf16 v[32:35], v[24:27], v[32:35], 0
	v_mfma_f32_16x16x32_bf16 v[96:99], v[20:23], v[36:39], v[96:99]
	v_mfma_f32_16x16x32_bf16 v[32:35], v[28:31], v[36:39], v[32:35]
	v_mfma_f32_16x16x32_bf16 v[36:39], v[16:19], v[40:43], 0
	v_mfma_f32_16x16x32_bf16 v[40:43], v[24:27], v[40:43], 0
	v_mfma_f32_16x16x32_bf16 v[36:39], v[20:23], v[44:47], v[36:39]
	v_mfma_f32_16x16x32_bf16 v[40:43], v[28:31], v[44:47], v[40:43]
	v_mfma_f32_16x16x32_bf16 v[44:47], v[16:19], v[48:51], 0
	v_mfma_f32_16x16x32_bf16 v[48:51], v[24:27], v[48:51], 0
	v_mfma_f32_16x16x32_bf16 v[44:47], v[20:23], v[52:55], v[44:47]
	v_mfma_f32_16x16x32_bf16 v[48:51], v[28:31], v[52:55], v[48:51]
	v_mfma_f32_16x16x32_bf16 v[52:55], v[16:19], v[56:59], 0
	v_mfma_f32_16x16x32_bf16 v[56:59], v[24:27], v[56:59], 0
	v_mfma_f32_16x16x32_bf16 v[52:55], v[20:23], v[60:63], v[52:55]
	v_mfma_f32_16x16x32_bf16 v[56:59], v[28:31], v[60:63], v[56:59]
	s_barrier
	s_setprio 0
	s_add_i32 s85, s70, s48
	v_lshl_add_u64 v[140:141], s[60:61], 0, v[130:131]
	s_add_i32 s35, s85, 0x2000
	v_lshl_add_u64 v[148:149], v[140:141], 0, s[20:21]
	s_mov_b32 m0, s85
	v_lshl_add_u64 v[212:213], s[60:61], 0, v[134:135]
	s_add_u32 s86, s60, 0x10100
	ds_read_b128 v[60:63], v147 offset:16384
	ds_read_b128 v[100:103], v147 offset:17408
	ds_read_b128 v[104:107], v147 offset:18432
	ds_read_b128 v[108:111], v147 offset:19456
	ds_read_b128 v[112:115], v147 offset:20480
	ds_read_b128 v[116:119], v147 offset:21504
	ds_read_b128 v[120:123], v147 offset:22528
	ds_read_b128 v[124:127], v147 offset:23552
	global_load_lds_dwordx4 v[148:149], off
	v_lshl_add_u64 v[148:149], v[212:213], 0, s[20:21]
	s_mov_b32 m0, s35
	s_addc_u32 s87, s61, 0
	s_add_i32 s37, s71, s48
	global_load_lds_dwordx4 v[148:149], off
	v_lshl_add_u64 v[148:149], s[86:87], 0, v[130:131]
	s_mov_b32 m0, s37
	s_add_i32 s47, s37, 0x2000
	global_load_lds_dwordx4 v[148:149], off
	v_lshl_add_u64 v[148:149], s[86:87], 0, v[134:135]
	s_mov_b32 m0, s47
	v_lshl_add_u64 v[214:215], s[58:59], 0, v[128:129]
	global_load_lds_dwordx4 v[148:149], off
	v_lshl_add_u64 v[148:149], v[214:215], 0, s[20:21]
	s_mov_b32 m0, s49
	v_lshl_add_u64 v[216:217], s[58:59], 0, v[132:133]
	global_load_lds_dwordx4 v[148:149], off
	v_lshl_add_u64 v[148:149], v[216:217], 0, s[20:21]
	s_mov_b32 m0, s50
	s_nop 0
	global_load_lds_dwordx4 v[148:149], off
	s_waitcnt vmcnt(8)
	s_waitcnt lgkmcnt(0)
	s_setprio 1
	s_barrier
	v_mfma_f32_16x16x32_bf16 v[148:151], v[0:3], v[60:63], 0
	v_mfma_f32_16x16x32_bf16 v[156:159], v[0:3], v[104:107], 0
	v_mfma_f32_16x16x32_bf16 v[164:167], v[0:3], v[112:115], 0
	v_mfma_f32_16x16x32_bf16 v[0:3], v[0:3], v[120:123], 0
	v_mfma_f32_16x16x32_bf16 v[148:151], v[4:7], v[100:103], v[148:151]
	v_mfma_f32_16x16x32_bf16 v[156:159], v[4:7], v[108:111], v[156:159]
	v_mfma_f32_16x16x32_bf16 v[164:167], v[4:7], v[116:119], v[164:167]
	v_mfma_f32_16x16x32_bf16 v[0:3], v[4:7], v[124:127], v[0:3]
	v_mfma_f32_16x16x32_bf16 v[4:7], v[8:11], v[120:123], 0
	v_mfma_f32_16x16x32_bf16 v[152:155], v[8:11], v[60:63], 0
	v_mfma_f32_16x16x32_bf16 v[160:163], v[8:11], v[104:107], 0
	v_mfma_f32_16x16x32_bf16 v[168:171], v[8:11], v[112:115], 0
	v_mfma_f32_16x16x32_bf16 v[4:7], v[12:15], v[124:127], v[4:7]
	v_mfma_f32_16x16x32_bf16 v[152:155], v[12:15], v[100:103], v[152:155]
	v_mfma_f32_16x16x32_bf16 v[160:163], v[12:15], v[108:111], v[160:163]
	v_mfma_f32_16x16x32_bf16 v[168:171], v[12:15], v[116:119], v[168:171]
	v_mfma_f32_16x16x32_bf16 v[8:11], v[16:19], v[60:63], 0
	v_mfma_f32_16x16x32_bf16 v[12:15], v[24:27], v[60:63], 0
	v_mfma_f32_16x16x32_bf16 v[8:11], v[20:23], v[100:103], v[8:11]
	v_mfma_f32_16x16x32_bf16 v[12:15], v[28:31], v[100:103], v[12:15]
	v_mfma_f32_16x16x32_bf16 v[60:63], v[16:19], v[104:107], 0
	v_mfma_f32_16x16x32_bf16 v[100:103], v[24:27], v[104:107], 0
	v_mfma_f32_16x16x32_bf16 v[104:107], v[16:19], v[112:115], 0
	v_mfma_f32_16x16x32_bf16 v[16:19], v[16:19], v[120:123], 0
	v_mfma_f32_16x16x32_bf16 v[60:63], v[20:23], v[108:111], v[60:63]
	v_mfma_f32_16x16x32_bf16 v[100:103], v[28:31], v[108:111], v[100:103]
	v_mfma_f32_16x16x32_bf16 v[104:107], v[20:23], v[116:119], v[104:107]
	v_mfma_f32_16x16x32_bf16 v[108:111], v[24:27], v[112:115], 0
	v_mfma_f32_16x16x32_bf16 v[16:19], v[20:23], v[124:127], v[16:19]
	v_mfma_f32_16x16x32_bf16 v[20:23], v[24:27], v[120:123], 0
	v_mfma_f32_16x16x32_bf16 v[108:111], v[28:31], v[116:119], v[108:111]
	v_mfma_f32_16x16x32_bf16 v[20:23], v[28:31], v[124:127], v[20:23]
	s_barrier
	s_setprio 0
	s_add_i32 s78, 0, 0x18000
	s_add_i32 s79, 0, 0x1c000
	v_add_u32_e32 v224, s78, v143
	v_add_u32_e32 v232, s79, v143
	ds_read_b128 v[24:27], v224
	ds_read_b128 v[28:31], v224 offset:1024
	ds_read_b128 v[112:115], v224 offset:2048
	ds_read_b128 v[116:119], v224 offset:3072
	ds_read_b128 v[120:123], v232
	ds_read_b128 v[124:127], v232 offset:1024
	ds_read_b128 v[172:175], v232 offset:2048
	ds_read_b128 v[176:179], v232 offset:3072
	s_add_u32 s86, s58, 0x10100
	s_addc_u32 s87, s59, 0
	s_mov_b32 m0, s51
	v_lshl_add_u64 v[218:219], s[86:87], 0, v[128:129]
	ds_read_b128 v[180:183], v147 offset:32768
	ds_read_b128 v[184:187], v147 offset:33792
	ds_read_b128 v[188:191], v147 offset:34816
	ds_read_b128 v[192:195], v147 offset:35840
	ds_read_b128 v[196:199], v147 offset:36864
	ds_read_b128 v[200:203], v147 offset:37888
	ds_read_b128 v[204:207], v147 offset:38912
	ds_read_b128 v[208:211], v147 offset:39936
	global_load_lds_dwordx4 v[218:219], off
	v_lshl_add_u64 v[218:219], s[86:87], 0, v[132:133]
	s_mov_b32 m0, s57
	s_nop 0
	global_load_lds_dwordx4 v[218:219], off
	s_waitcnt vmcnt(8)
	s_waitcnt lgkmcnt(0)
	s_setprio 1
	s_barrier
	v_mfma_f32_16x16x32_bf16 v[64:67], v[24:27], v[180:183], v[64:67]
	v_mfma_f32_16x16x32_bf16 v[68:71], v[112:115], v[180:183], v[68:71]
	v_mfma_f32_16x16x32_bf16 v[72:75], v[24:27], v[188:191], v[72:75]
	v_mfma_f32_16x16x32_bf16 v[76:79], v[112:115], v[188:191], v[76:79]
	v_mfma_f32_16x16x32_bf16 v[80:83], v[24:27], v[196:199], v[80:83]
	v_mfma_f32_16x16x32_bf16 v[84:87], v[112:115], v[196:199], v[84:87]
	v_mfma_f32_16x16x32_bf16 v[88:91], v[24:27], v[204:207], v[88:91]
	v_mfma_f32_16x16x32_bf16 v[92:95], v[112:115], v[204:207], v[92:95]
	v_mfma_f32_16x16x32_bf16 v[64:67], v[28:31], v[184:187], v[64:67]
	v_mfma_f32_16x16x32_bf16 v[68:71], v[116:119], v[184:187], v[68:71]
	v_mfma_f32_16x16x32_bf16 v[72:75], v[28:31], v[192:195], v[72:75]
	v_mfma_f32_16x16x32_bf16 v[76:79], v[116:119], v[192:195], v[76:79]
	v_mfma_f32_16x16x32_bf16 v[80:83], v[28:31], v[200:203], v[80:83]
	v_mfma_f32_16x16x32_bf16 v[84:87], v[116:119], v[200:203], v[84:87]
	v_mfma_f32_16x16x32_bf16 v[88:91], v[28:31], v[208:211], v[88:91]
	v_mfma_f32_16x16x32_bf16 v[92:95], v[116:119], v[208:211], v[92:95]
	v_mfma_f32_16x16x32_bf16 v[96:99], v[120:123], v[180:183], v[96:99]
	v_mfma_f32_16x16x32_bf16 v[32:35], v[172:175], v[180:183], v[32:35]
	v_mfma_f32_16x16x32_bf16 v[36:39], v[120:123], v[188:191], v[36:39]
	v_mfma_f32_16x16x32_bf16 v[40:43], v[172:175], v[188:191], v[40:43]
	v_mfma_f32_16x16x32_bf16 v[44:47], v[120:123], v[196:199], v[44:47]
	v_mfma_f32_16x16x32_bf16 v[48:51], v[172:175], v[196:199], v[48:51]
	v_mfma_f32_16x16x32_bf16 v[52:55], v[120:123], v[204:207], v[52:55]
	v_mfma_f32_16x16x32_bf16 v[56:59], v[172:175], v[204:207], v[56:59]
	v_mfma_f32_16x16x32_bf16 v[96:99], v[124:127], v[184:187], v[96:99]
	v_mfma_f32_16x16x32_bf16 v[32:35], v[176:179], v[184:187], v[32:35]
	v_mfma_f32_16x16x32_bf16 v[36:39], v[124:127], v[192:195], v[36:39]
	v_mfma_f32_16x16x32_bf16 v[40:43], v[176:179], v[192:195], v[40:43]
	v_mfma_f32_16x16x32_bf16 v[44:47], v[124:127], v[200:203], v[44:47]
	v_mfma_f32_16x16x32_bf16 v[48:51], v[176:179], v[200:203], v[48:51]
	v_mfma_f32_16x16x32_bf16 v[52:55], v[124:127], v[208:211], v[52:55]
	v_mfma_f32_16x16x32_bf16 v[56:59], v[176:179], v[208:211], v[56:59]
	s_barrier
	s_setprio 0
	s_add_i32 s87, s78, s48
	s_add_i32 s86, s87, 0x2000
	v_lshl_add_u64 v[140:141], v[140:141], 0, s[22:23]
	s_mov_b32 m0, s87
	s_add_u32 s88, s60, 0x10180
	ds_read_b128 v[180:183], v147 offset:49152
	ds_read_b128 v[184:187], v147 offset:50176
	ds_read_b128 v[188:191], v147 offset:51200
	ds_read_b128 v[192:195], v147 offset:52224
	ds_read_b128 v[196:199], v147 offset:53248
	ds_read_b128 v[200:203], v147 offset:54272
	ds_read_b128 v[204:207], v147 offset:55296
	ds_read_b128 v[208:211], v147 offset:56320
	global_load_lds_dwordx4 v[140:141], off
	v_lshl_add_u64 v[140:141], v[212:213], 0, s[22:23]
	s_mov_b32 m0, s86
	s_addc_u32 s89, s61, 0
	s_add_i32 s60, s79, s48
	global_load_lds_dwordx4 v[140:141], off
	v_lshl_add_u64 v[140:141], s[88:89], 0, v[130:131]
	s_mov_b32 m0, s60
	s_add_i32 s61, s60, 0x2000
	global_load_lds_dwordx4 v[140:141], off
	v_lshl_add_u64 v[140:141], s[88:89], 0, v[134:135]
	s_mov_b32 m0, s61
	s_nop 0
	global_load_lds_dwordx4 v[140:141], off
	v_lshl_add_u64 v[140:141], v[214:215], 0, s[22:23]
	s_mov_b32 m0, s66
	s_nop 0
	global_load_lds_dwordx4 v[140:141], off
	v_lshl_add_u64 v[140:141], v[216:217], 0, s[22:23]
	s_mov_b32 m0, s67
	s_nop 0
	global_load_lds_dwordx4 v[140:141], off
	s_waitcnt vmcnt(8)
	s_waitcnt lgkmcnt(0)
	s_setprio 1
	s_barrier
	v_mfma_f32_16x16x32_bf16 v[0:3], v[24:27], v[204:207], v[0:3]
	v_mfma_f32_16x16x32_bf16 v[4:7], v[112:115], v[204:207], v[4:7]
	v_mfma_f32_16x16x32_bf16 v[148:151], v[24:27], v[180:183], v[148:151]
	v_mfma_f32_16x16x32_bf16 v[152:155], v[112:115], v[180:183], v[152:155]
	v_mfma_f32_16x16x32_bf16 v[156:159], v[24:27], v[188:191], v[156:159]
	v_mfma_f32_16x16x32_bf16 v[160:163], v[112:115], v[188:191], v[160:163]
	v_mfma_f32_16x16x32_bf16 v[164:167], v[24:27], v[196:199], v[164:167]
	v_mfma_f32_16x16x32_bf16 v[168:171], v[112:115], v[196:199], v[168:171]
	v_mfma_f32_16x16x32_bf16 v[0:3], v[28:31], v[208:211], v[0:3]
	v_mfma_f32_16x16x32_bf16 v[4:7], v[116:119], v[208:211], v[4:7]
	v_mfma_f32_16x16x32_bf16 v[148:151], v[28:31], v[184:187], v[148:151]
	v_mfma_f32_16x16x32_bf16 v[152:155], v[116:119], v[184:187], v[152:155]
	v_mfma_f32_16x16x32_bf16 v[156:159], v[28:31], v[192:195], v[156:159]
	v_mfma_f32_16x16x32_bf16 v[160:163], v[116:119], v[192:195], v[160:163]
	v_mfma_f32_16x16x32_bf16 v[164:167], v[28:31], v[200:203], v[164:167]
	v_mfma_f32_16x16x32_bf16 v[168:171], v[116:119], v[200:203], v[168:171]
	v_mfma_f32_16x16x32_bf16 v[8:11], v[120:123], v[180:183], v[8:11]
	v_mfma_f32_16x16x32_bf16 v[12:15], v[172:175], v[180:183], v[12:15]
	v_mfma_f32_16x16x32_bf16 v[24:27], v[120:123], v[188:191], v[60:63]
	v_mfma_f32_16x16x32_bf16 v[28:31], v[172:175], v[188:191], v[100:103]
	v_mfma_f32_16x16x32_bf16 v[60:63], v[120:123], v[196:199], v[104:107]
	v_mfma_f32_16x16x32_bf16 v[100:103], v[172:175], v[196:199], v[108:111]
	v_mfma_f32_16x16x32_bf16 v[16:19], v[120:123], v[204:207], v[16:19]
	v_mfma_f32_16x16x32_bf16 v[20:23], v[172:175], v[204:207], v[20:23]
	v_mfma_f32_16x16x32_bf16 v[8:11], v[124:127], v[184:187], v[8:11]
	v_mfma_f32_16x16x32_bf16 v[12:15], v[176:179], v[184:187], v[12:15]
	v_mfma_f32_16x16x32_bf16 v[24:27], v[124:127], v[192:195], v[24:27]
	v_mfma_f32_16x16x32_bf16 v[28:31], v[176:179], v[192:195], v[28:31]
	v_mfma_f32_16x16x32_bf16 v[60:63], v[124:127], v[200:203], v[60:63]
	v_mfma_f32_16x16x32_bf16 v[100:103], v[176:179], v[200:203], v[100:103]
	v_mfma_f32_16x16x32_bf16 v[16:19], v[124:127], v[208:211], v[16:19]
	v_mfma_f32_16x16x32_bf16 v[20:23], v[176:179], v[208:211], v[20:23]
	s_barrier
	s_setprio 0
	ds_read_b128 v[104:107], v145
	ds_read_b128 v[108:111], v145 offset:1024
	ds_read_b128 v[112:115], v145 offset:2048
	ds_read_b128 v[116:119], v145 offset:3072
	ds_read_b128 v[120:123], v146
	ds_read_b128 v[124:127], v146 offset:1024
	ds_read_b128 v[172:175], v146 offset:2048
	ds_read_b128 v[176:179], v146 offset:3072
	s_add_u32 s58, s58, 0x10180
	s_addc_u32 s59, s59, 0
	s_mov_b32 m0, s72
	v_lshl_add_u64 v[140:141], s[58:59], 0, v[128:129]
	ds_read_b128 v[180:183], v147
	ds_read_b128 v[184:187], v147 offset:1024
	ds_read_b128 v[188:191], v147 offset:2048
	ds_read_b128 v[192:195], v147 offset:3072
	ds_read_b128 v[196:199], v147 offset:4096
	ds_read_b128 v[200:203], v147 offset:5120
	ds_read_b128 v[204:207], v147 offset:6144
	ds_read_b128 v[208:211], v147 offset:7168
	global_load_lds_dwordx4 v[140:141], off
	v_lshl_add_u64 v[140:141], s[58:59], 0, v[132:133]
	s_mov_b32 m0, s80
	s_nop 0
	global_load_lds_dwordx4 v[140:141], off
	s_waitcnt vmcnt(8)
	s_waitcnt lgkmcnt(0)
	s_setprio 1
	s_barrier
	v_mfma_f32_16x16x32_bf16 v[88:91], v[104:107], v[204:207], v[88:91]
	v_mfma_f32_16x16x32_bf16 v[64:67], v[104:107], v[180:183], v[64:67]
	v_mfma_f32_16x16x32_bf16 v[68:71], v[112:115], v[180:183], v[68:71]
	v_mfma_f32_16x16x32_bf16 v[72:75], v[104:107], v[188:191], v[72:75]
	v_mfma_f32_16x16x32_bf16 v[76:79], v[112:115], v[188:191], v[76:79]
	v_mfma_f32_16x16x32_bf16 v[80:83], v[104:107], v[196:199], v[80:83]
	v_mfma_f32_16x16x32_bf16 v[84:87], v[112:115], v[196:199], v[84:87]
	v_mfma_f32_16x16x32_bf16 v[212:215], v[108:111], v[208:211], v[88:91]
	v_mfma_f32_16x16x32_bf16 v[88:91], v[112:115], v[204:207], v[92:95]
	v_mfma_f32_16x16x32_bf16 v[64:67], v[108:111], v[184:187], v[64:67]
	v_mfma_f32_16x16x32_bf16 v[68:71], v[116:119], v[184:187], v[68:71]
	v_mfma_f32_16x16x32_bf16 v[72:75], v[108:111], v[192:195], v[72:75]
	v_mfma_f32_16x16x32_bf16 v[76:79], v[116:119], v[192:195], v[76:79]
	v_mfma_f32_16x16x32_bf16 v[80:83], v[108:111], v[200:203], v[80:83]
	v_mfma_f32_16x16x32_bf16 v[84:87], v[116:119], v[200:203], v[84:87]
	v_mfma_f32_16x16x32_bf16 v[92:95], v[116:119], v[208:211], v[88:91]
	v_mfma_f32_16x16x32_bf16 v[48:51], v[172:175], v[196:199], v[48:51]
	v_mfma_f32_16x16x32_bf16 v[88:91], v[120:123], v[180:183], v[96:99]
	v_mfma_f32_16x16x32_bf16 v[32:35], v[172:175], v[180:183], v[32:35]
	v_mfma_f32_16x16x32_bf16 v[36:39], v[120:123], v[188:191], v[36:39]
	v_mfma_f32_16x16x32_bf16 v[40:43], v[172:175], v[188:191], v[40:43]
	v_mfma_f32_16x16x32_bf16 v[44:47], v[120:123], v[196:199], v[44:47]
	v_mfma_f32_16x16x32_bf16 v[180:183], v[176:179], v[200:203], v[48:51]
	v_mfma_f32_16x16x32_bf16 v[48:51], v[120:123], v[204:207], v[52:55]
	v_mfma_f32_16x16x32_bf16 v[32:35], v[176:179], v[184:187], v[32:35]
	v_mfma_f32_16x16x32_bf16 v[36:39], v[124:127], v[192:195], v[36:39]
	v_mfma_f32_16x16x32_bf16 v[40:43], v[176:179], v[192:195], v[40:43]
	v_mfma_f32_16x16x32_bf16 v[44:47], v[124:127], v[200:203], v[44:47]
	v_mfma_f32_16x16x32_bf16 v[52:55], v[124:127], v[208:211], v[48:51]
	v_mfma_f32_16x16x32_bf16 v[48:51], v[172:175], v[204:207], v[56:59]
	v_mfma_f32_16x16x32_bf16 v[216:219], v[124:127], v[184:187], v[88:91]
	v_mfma_f32_16x16x32_bf16 v[184:187], v[176:179], v[208:211], v[48:51]
	s_barrier
	s_setprio 0
	s_mov_b32 m0, s85
	v_lshl_add_u64 v[140:141], s[62:63], 0, v[130:131]
	s_add_u32 s58, s62, 0x10000
	s_nop 0
	ds_read_b128 v[48:51], v147 offset:16384
	ds_read_b128 v[56:59], v147 offset:17408
	ds_read_b128 v[88:91], v147 offset:18432
	ds_read_b128 v[96:99], v147 offset:19456
	ds_read_b128 v[188:191], v147 offset:20480
	ds_read_b128 v[192:195], v147 offset:21504
	ds_read_b128 v[196:199], v147 offset:22528
	ds_read_b128 v[200:203], v147 offset:23552
	global_load_lds_dwordx4 v[140:141], off
	v_lshl_add_u64 v[252:253], s[62:63], 0, v[134:135]
	s_mov_b32 m0, s35
	s_addc_u32 s59, s63, 0
	global_load_lds_dwordx4 v[252:253], off
	v_lshl_add_u64 v[204:205], s[58:59], 0, v[130:131]
	s_mov_b32 m0, s37
	v_lshl_add_u64 v[136:137], s[64:65], 0, v[128:129]
	global_load_lds_dwordx4 v[204:205], off
	v_lshl_add_u64 v[204:205], s[58:59], 0, v[134:135]
	s_mov_b32 m0, s47
	v_lshl_add_u64 v[138:139], s[64:65], 0, v[132:133]
	global_load_lds_dwordx4 v[204:205], off
	s_mov_b32 m0, s49
	s_nop 0
	global_load_lds_dwordx4 v[136:137], off
	s_mov_b32 m0, s50
	s_nop 0
	global_load_lds_dwordx4 v[138:139], off
	s_waitcnt vmcnt(8)
	s_waitcnt lgkmcnt(0)
	s_setprio 1
	s_barrier
	v_mfma_f32_16x16x32_bf16 v[0:3], v[104:107], v[196:199], v[0:3]
	v_mfma_f32_16x16x32_bf16 v[4:7], v[112:115], v[196:199], v[4:7]
	v_mfma_f32_16x16x32_bf16 v[148:151], v[104:107], v[48:51], v[148:151]
	v_mfma_f32_16x16x32_bf16 v[152:155], v[112:115], v[48:51], v[152:155]
	v_mfma_f32_16x16x32_bf16 v[156:159], v[104:107], v[88:91], v[156:159]
	v_mfma_f32_16x16x32_bf16 v[160:163], v[112:115], v[88:91], v[160:163]
	v_mfma_f32_16x16x32_bf16 v[164:167], v[104:107], v[188:191], v[164:167]
	v_mfma_f32_16x16x32_bf16 v[168:171], v[112:115], v[188:191], v[168:171]
	v_mfma_f32_16x16x32_bf16 v[0:3], v[108:111], v[200:203], v[0:3]
	v_mfma_f32_16x16x32_bf16 v[4:7], v[116:119], v[200:203], v[4:7]
	v_mfma_f32_16x16x32_bf16 v[148:151], v[108:111], v[56:59], v[148:151]
	v_mfma_f32_16x16x32_bf16 v[152:155], v[116:119], v[56:59], v[152:155]
	v_mfma_f32_16x16x32_bf16 v[156:159], v[108:111], v[96:99], v[156:159]
	v_mfma_f32_16x16x32_bf16 v[160:163], v[116:119], v[96:99], v[160:163]
	v_mfma_f32_16x16x32_bf16 v[164:167], v[108:111], v[192:195], v[164:167]
	v_mfma_f32_16x16x32_bf16 v[168:171], v[116:119], v[192:195], v[168:171]
	v_mfma_f32_16x16x32_bf16 v[12:15], v[172:175], v[48:51], v[12:15]
	v_mfma_f32_16x16x32_bf16 v[204:207], v[176:179], v[56:59], v[12:15]
	v_mfma_f32_16x16x32_bf16 v[12:15], v[120:123], v[88:91], v[24:27]
	v_mfma_f32_16x16x32_bf16 v[24:27], v[124:127], v[96:99], v[12:15]
	v_mfma_f32_16x16x32_bf16 v[12:15], v[172:175], v[88:91], v[28:31]
	v_mfma_f32_16x16x32_bf16 v[208:211], v[176:179], v[96:99], v[12:15]
	v_mfma_f32_16x16x32_bf16 v[12:15], v[120:123], v[188:191], v[60:63]
	v_mfma_f32_16x16x32_bf16 v[220:223], v[124:127], v[192:195], v[12:15]
	v_mfma_f32_16x16x32_bf16 v[12:15], v[172:175], v[188:191], v[100:103]
	v_mfma_f32_16x16x32_bf16 v[8:11], v[120:123], v[48:51], v[8:11]
	v_mfma_f32_16x16x32_bf16 v[188:191], v[176:179], v[192:195], v[12:15]
	v_mfma_f32_16x16x32_bf16 v[12:15], v[120:123], v[196:199], v[16:19]
	v_mfma_f32_16x16x32_bf16 v[8:11], v[124:127], v[56:59], v[8:11]
	v_mfma_f32_16x16x32_bf16 v[192:195], v[124:127], v[200:203], v[12:15]
	v_mfma_f32_16x16x32_bf16 v[12:15], v[172:175], v[196:199], v[20:23]
	v_mfma_f32_16x16x32_bf16 v[172:175], v[176:179], v[200:203], v[12:15]
	s_barrier
	s_setprio 0
	s_nop 4
	ds_read_b128 v[12:15], v224
	ds_read_b128 v[16:19], v224 offset:1024
	ds_read_b128 v[176:179], v224 offset:2048
	ds_read_b128 v[196:199], v224 offset:3072
	ds_read_b128 v[200:203], v232
	ds_read_b128 v[224:227], v232 offset:1024
	ds_read_b128 v[228:231], v232 offset:2048
	ds_read_b128 v[232:235], v232 offset:3072
	s_add_u32 s58, s64, 0x10000
	s_addc_u32 s59, s65, 0
	s_mov_b32 m0, s51
	v_lshl_add_u64 v[48:49], s[58:59], 0, v[128:129]
	ds_read_b128 v[20:23], v147 offset:32768
	ds_read_b128 v[28:31], v147 offset:33792
	ds_read_b128 v[60:63], v147 offset:34816
	ds_read_b128 v[100:103], v147 offset:35840
	ds_read_b128 v[236:239], v147 offset:36864
	ds_read_b128 v[240:243], v147 offset:37888
	ds_read_b128 v[244:247], v147 offset:38912
	ds_read_b128 v[248:251], v147 offset:39936
	global_load_lds_dwordx4 v[48:49], off
	v_lshl_add_u64 v[48:49], s[58:59], 0, v[132:133]
	s_mov_b32 m0, s57
	s_nop 0
	global_load_lds_dwordx4 v[48:49], off
	s_waitcnt vmcnt(8)
	s_waitcnt lgkmcnt(0)
	s_setprio 1
	s_barrier
	v_mfma_f32_16x16x32_bf16 v[48:51], v[12:15], v[20:23], v[64:67]
	v_mfma_f32_16x16x32_bf16 v[120:123], v[16:19], v[28:31], v[48:51]
	v_mfma_f32_16x16x32_bf16 v[48:51], v[176:179], v[20:23], v[68:71]
	v_mfma_f32_16x16x32_bf16 v[112:115], v[196:199], v[28:31], v[48:51]
	v_mfma_f32_16x16x32_bf16 v[48:51], v[12:15], v[60:63], v[72:75]
	v_mfma_f32_16x16x32_bf16 v[104:107], v[16:19], v[100:103], v[48:51]
	v_mfma_f32_16x16x32_bf16 v[48:51], v[176:179], v[60:63], v[76:79]
	v_mfma_f32_16x16x32_bf16 v[96:99], v[196:199], v[100:103], v[48:51]
	v_mfma_f32_16x16x32_bf16 v[48:51], v[12:15], v[236:239], v[80:83]
	v_mfma_f32_16x16x32_bf16 v[88:91], v[16:19], v[240:243], v[48:51]
	v_mfma_f32_16x16x32_bf16 v[48:51], v[176:179], v[236:239], v[84:87]
	v_mfma_f32_16x16x32_bf16 v[80:83], v[196:199], v[240:243], v[48:51]
	v_mfma_f32_16x16x32_bf16 v[48:51], v[12:15], v[244:247], v[212:215]
	v_mfma_f32_16x16x32_bf16 v[56:59], v[16:19], v[248:251], v[48:51]
	v_mfma_f32_16x16x32_bf16 v[48:51], v[176:179], v[244:247], v[92:95]
	v_mfma_f32_16x16x32_bf16 v[48:51], v[196:199], v[248:251], v[48:51]
	v_mfma_f32_16x16x32_bf16 v[64:67], v[200:203], v[20:23], v[216:219]
	v_mfma_f32_16x16x32_bf16 v[20:23], v[228:231], v[20:23], v[32:35]
	v_mfma_f32_16x16x32_bf16 v[116:119], v[232:235], v[28:31], v[20:23]
	v_mfma_f32_16x16x32_bf16 v[20:23], v[200:203], v[60:63], v[36:39]
	v_mfma_f32_16x16x32_bf16 v[108:111], v[224:227], v[100:103], v[20:23]
	v_mfma_f32_16x16x32_bf16 v[20:23], v[228:231], v[60:63], v[40:43]
	v_mfma_f32_16x16x32_bf16 v[100:103], v[232:235], v[100:103], v[20:23]
	v_mfma_f32_16x16x32_bf16 v[20:23], v[200:203], v[236:239], v[44:47]
	v_mfma_f32_16x16x32_bf16 v[92:95], v[224:227], v[240:243], v[20:23]
	v_mfma_f32_16x16x32_bf16 v[20:23], v[228:231], v[236:239], v[180:183]
	v_mfma_f32_16x16x32_bf16 v[84:87], v[232:235], v[240:243], v[20:23]
	v_mfma_f32_16x16x32_bf16 v[20:23], v[200:203], v[244:247], v[52:55]
	v_mfma_f32_16x16x32_bf16 v[60:63], v[224:227], v[248:251], v[20:23]
	v_mfma_f32_16x16x32_bf16 v[20:23], v[228:231], v[244:247], v[184:187]
	v_mfma_f32_16x16x32_bf16 v[124:127], v[224:227], v[28:31], v[64:67]
	v_mfma_f32_16x16x32_bf16 v[52:55], v[232:235], v[248:251], v[20:23]
	s_barrier
	s_setprio 0
	s_mov_b32 m0, s87
	s_nop 2
	v_lshl_add_u64 v[20:21], v[140:141], 0, s[14:15]
	s_add_u32 s58, s62, 0x10080
	ds_read_b128 v[32:35], v147 offset:49152
	ds_read_b128 v[40:43], v147 offset:50176
	ds_read_b128 v[180:183], v147 offset:51200
	ds_read_b128 v[184:187], v147 offset:52224
	ds_read_b128 v[212:215], v147 offset:53248
	ds_read_b128 v[216:219], v147 offset:54272
	ds_read_b128 v[236:239], v147 offset:55296
	ds_read_b128 v[240:243], v147 offset:56320
	global_load_lds_dwordx4 v[20:21], off
	v_lshl_add_u64 v[20:21], v[252:253], 0, s[14:15]
	s_mov_b32 m0, s86
	s_addc_u32 s59, s63, 0
	global_load_lds_dwordx4 v[20:21], off
	v_lshl_add_u64 v[20:21], s[58:59], 0, v[130:131]
	s_mov_b32 m0, s60
	s_nop 0
	global_load_lds_dwordx4 v[20:21], off
	v_lshl_add_u64 v[20:21], s[58:59], 0, v[134:135]
	s_mov_b32 m0, s61
	s_nop 0
	global_load_lds_dwordx4 v[20:21], off
	v_lshl_add_u64 v[20:21], v[136:137], 0, s[14:15]
	s_mov_b32 m0, s66
	s_nop 0
	global_load_lds_dwordx4 v[20:21], off
	v_lshl_add_u64 v[20:21], v[138:139], 0, s[14:15]
	s_mov_b32 m0, s67
	s_nop 0
	global_load_lds_dwordx4 v[20:21], off
	s_waitcnt vmcnt(8)
	s_waitcnt lgkmcnt(0)
	s_setprio 1
	s_barrier
	v_mfma_f32_16x16x32_bf16 v[20:23], v[12:15], v[32:35], v[148:151]
	v_mfma_f32_16x16x32_bf16 v[76:79], v[16:19], v[40:43], v[20:23]
	v_mfma_f32_16x16x32_bf16 v[20:23], v[176:179], v[32:35], v[152:155]
	v_mfma_f32_16x16x32_bf16 v[68:71], v[196:199], v[40:43], v[20:23]
	v_mfma_f32_16x16x32_bf16 v[20:23], v[12:15], v[180:183], v[156:159]
	v_mfma_f32_16x16x32_bf16 v[44:47], v[16:19], v[184:187], v[20:23]
	v_mfma_f32_16x16x32_bf16 v[20:23], v[176:179], v[180:183], v[160:163]
	v_mfma_f32_16x16x32_bf16 v[36:39], v[196:199], v[184:187], v[20:23]
	v_mfma_f32_16x16x32_bf16 v[20:23], v[12:15], v[212:215], v[164:167]
	v_mfma_f32_16x16x32_bf16 v[0:3], v[12:15], v[236:239], v[0:3]
	v_mfma_f32_16x16x32_bf16 v[28:31], v[16:19], v[216:219], v[20:23]
	v_mfma_f32_16x16x32_bf16 v[20:23], v[176:179], v[212:215], v[168:171]
	v_mfma_f32_16x16x32_bf16 v[12:15], v[16:19], v[240:243], v[0:3]
	v_mfma_f32_16x16x32_bf16 v[0:3], v[176:179], v[236:239], v[4:7]
	v_mfma_f32_16x16x32_bf16 v[20:23], v[196:199], v[216:219], v[20:23]
	v_mfma_f32_16x16x32_bf16 v[4:7], v[196:199], v[240:243], v[0:3]
	v_mfma_f32_16x16x32_bf16 v[0:3], v[200:203], v[32:35], v[8:11]
	v_mfma_f32_16x16x32_bf16 v[72:75], v[224:227], v[40:43], v[0:3]
	v_mfma_f32_16x16x32_bf16 v[0:3], v[228:231], v[32:35], v[204:207]
	v_mfma_f32_16x16x32_bf16 v[64:67], v[232:235], v[40:43], v[0:3]
	v_mfma_f32_16x16x32_bf16 v[0:3], v[200:203], v[180:183], v[24:27]
	v_mfma_f32_16x16x32_bf16 v[40:43], v[224:227], v[184:187], v[0:3]
	v_mfma_f32_16x16x32_bf16 v[0:3], v[228:231], v[180:183], v[208:211]
	v_mfma_f32_16x16x32_bf16 v[32:35], v[232:235], v[184:187], v[0:3]
	v_mfma_f32_16x16x32_bf16 v[0:3], v[200:203], v[212:215], v[220:223]
	v_mfma_f32_16x16x32_bf16 v[24:27], v[224:227], v[216:219], v[0:3]
	v_mfma_f32_16x16x32_bf16 v[0:3], v[228:231], v[212:215], v[188:191]
	v_mfma_f32_16x16x32_bf16 v[16:19], v[232:235], v[216:219], v[0:3]
	v_mfma_f32_16x16x32_bf16 v[0:3], v[200:203], v[236:239], v[192:195]
	v_mfma_f32_16x16x32_bf16 v[8:11], v[224:227], v[240:243], v[0:3]
	v_mfma_f32_16x16x32_bf16 v[0:3], v[228:231], v[236:239], v[172:175]
	v_mfma_f32_16x16x32_bf16 v[0:3], v[232:235], v[240:243], v[0:3]
	s_barrier
	s_setprio 0
	s_andn2_b64 vcc, exec, s[16:17]
	s_cbranch_vccnz .LBB0_710
	s_barrier

.LBB0_731:
	ds_read_b128 v[146:149], v153
	ds_read_b128 v[158:161], v153 offset:1024
	ds_read_b128 v[162:165], v153 offset:2048
	ds_read_b128 v[166:169], v153 offset:3072
	ds_read_b128 v[170:173], v154
	ds_read_b128 v[174:177], v154 offset:1024
	ds_read_b128 v[178:181], v154 offset:2048
	ds_read_b128 v[182:185], v154 offset:3072
	s_add_u32 s34, s30, 0xfff80080
	s_addc_u32 s35, s31, -1
	s_cmp_eq_u32 s61, 28
	s_cselect_b32 s37, s21, s35
	s_cselect_b32 s36, s46, s34
	s_cselect_b32 s35, s19, s60
	s_cselect_b32 s34, s47, s59
	v_lshl_add_u64 v[218:219], s[30:31], 0, v[140:141]
	s_add_i32 m0, s27, 0xc000
	ds_read_b128 v[186:189], v155
	ds_read_b128 v[190:193], v155 offset:1024
	ds_read_b128 v[194:197], v155 offset:2048
	ds_read_b128 v[198:201], v155 offset:3072
	ds_read_b128 v[202:205], v155 offset:4096
	ds_read_b128 v[206:209], v155 offset:5120
	ds_read_b128 v[210:213], v155 offset:6144
	ds_read_b128 v[214:217], v155 offset:7168
	global_load_lds_dwordx4 v[218:219], off
	v_lshl_add_u64 v[218:219], s[30:31], 0, v[138:139]
	s_add_i32 m0, s27, 0xe000
	s_nop 0
	global_load_lds_dwordx4 v[218:219], off
	s_waitcnt vmcnt(8)
	s_waitcnt lgkmcnt(0)
	s_setprio 1
	s_barrier
	v_mfma_f32_16x16x32_bf16 v[124:127], v[146:149], v[186:189], v[124:127]
	v_mfma_f32_16x16x32_bf16 v[120:123], v[162:165], v[186:189], v[120:123]
	v_mfma_f32_16x16x32_bf16 v[108:111], v[146:149], v[194:197], v[108:111]
	v_mfma_f32_16x16x32_bf16 v[104:107], v[162:165], v[194:197], v[104:107]
	v_mfma_f32_16x16x32_bf16 v[92:95], v[146:149], v[202:205], v[92:95]
	v_mfma_f32_16x16x32_bf16 v[88:91], v[162:165], v[202:205], v[88:91]
	v_mfma_f32_16x16x32_bf16 v[76:79], v[146:149], v[210:213], v[76:79]
	v_mfma_f32_16x16x32_bf16 v[72:75], v[162:165], v[210:213], v[72:75]
	v_mfma_f32_16x16x32_bf16 v[124:127], v[158:161], v[190:193], v[124:127]
	v_mfma_f32_16x16x32_bf16 v[120:123], v[166:169], v[190:193], v[120:123]
	v_mfma_f32_16x16x32_bf16 v[108:111], v[158:161], v[198:201], v[108:111]
	v_mfma_f32_16x16x32_bf16 v[104:107], v[166:169], v[198:201], v[104:107]
	v_mfma_f32_16x16x32_bf16 v[92:95], v[158:161], v[206:209], v[92:95]
	v_mfma_f32_16x16x32_bf16 v[88:91], v[166:169], v[206:209], v[88:91]
	v_mfma_f32_16x16x32_bf16 v[76:79], v[158:161], v[214:217], v[76:79]
	v_mfma_f32_16x16x32_bf16 v[72:75], v[166:169], v[214:217], v[72:75]
	v_mfma_f32_16x16x32_bf16 v[116:119], v[170:173], v[186:189], v[116:119]
	v_mfma_f32_16x16x32_bf16 v[112:115], v[178:181], v[186:189], v[112:115]
	v_mfma_f32_16x16x32_bf16 v[100:103], v[170:173], v[194:197], v[100:103]
	v_mfma_f32_16x16x32_bf16 v[96:99], v[178:181], v[194:197], v[96:99]
	v_mfma_f32_16x16x32_bf16 v[84:87], v[170:173], v[202:205], v[84:87]
	v_mfma_f32_16x16x32_bf16 v[80:83], v[178:181], v[202:205], v[80:83]
	v_mfma_f32_16x16x32_bf16 v[68:71], v[170:173], v[210:213], v[68:71]
	v_mfma_f32_16x16x32_bf16 v[64:67], v[178:181], v[210:213], v[64:67]
	v_mfma_f32_16x16x32_bf16 v[116:119], v[174:177], v[190:193], v[116:119]
	v_mfma_f32_16x16x32_bf16 v[112:115], v[182:185], v[190:193], v[112:115]
	v_mfma_f32_16x16x32_bf16 v[100:103], v[174:177], v[198:201], v[100:103]
	v_mfma_f32_16x16x32_bf16 v[96:99], v[182:185], v[198:201], v[96:99]
	v_mfma_f32_16x16x32_bf16 v[84:87], v[174:177], v[206:209], v[84:87]
	v_mfma_f32_16x16x32_bf16 v[80:83], v[182:185], v[206:209], v[80:83]
	v_mfma_f32_16x16x32_bf16 v[68:71], v[174:177], v[214:217], v[68:71]
	v_mfma_f32_16x16x32_bf16 v[64:67], v[182:185], v[214:217], v[64:67]
	s_barrier
	s_setprio 0
	s_add_i32 s62, s55, s48
	v_lshl_add_u64 v[218:219], s[34:35], 0, v[130:131]
	s_mov_b32 m0, s62
	ds_read_b128 v[186:189], v155 offset:16384
	ds_read_b128 v[190:193], v155 offset:17408
	ds_read_b128 v[194:197], v155 offset:18432
	ds_read_b128 v[198:201], v155 offset:19456
	ds_read_b128 v[202:205], v155 offset:20480
	ds_read_b128 v[206:209], v155 offset:21504
	ds_read_b128 v[210:213], v155 offset:22528
	ds_read_b128 v[214:217], v155 offset:23552
	global_load_lds_dwordx4 v[218:219], off
	s_add_i32 m0, s62, 0x2000
	s_add_u32 s62, s34, 0x80000
	v_lshl_add_u64 v[220:221], s[34:35], 0, v[134:135]
	s_addc_u32 s63, s35, 0
	s_add_i32 s64, s56, s48
	global_load_lds_dwordx4 v[220:221], off
	v_lshl_add_u64 v[222:223], s[62:63], 0, v[130:131]
	s_mov_b32 m0, s64
	v_lshl_add_u64 v[224:225], s[36:37], 0, v[132:133]
	global_load_lds_dwordx4 v[222:223], off
	v_lshl_add_u64 v[222:223], s[62:63], 0, v[134:135]
	s_add_i32 m0, s64, 0x2000
	s_nop 0
	global_load_lds_dwordx4 v[222:223], off
	v_lshl_add_u64 v[222:223], s[36:37], 0, v[128:129]
	s_mov_b32 m0, s27
	s_nop 0
	global_load_lds_dwordx4 v[222:223], off
	s_mov_b32 m0, s49
	s_nop 0
	global_load_lds_dwordx4 v[224:225], off
	s_waitcnt vmcnt(8)
	s_waitcnt lgkmcnt(0)
	s_setprio 1
	s_barrier
	v_mfma_f32_16x16x32_bf16 v[60:63], v[146:149], v[186:189], v[60:63]
	v_mfma_f32_16x16x32_bf16 v[56:59], v[162:165], v[186:189], v[56:59]
	v_mfma_f32_16x16x32_bf16 v[44:47], v[146:149], v[194:197], v[44:47]
	v_mfma_f32_16x16x32_bf16 v[40:43], v[162:165], v[194:197], v[40:43]
	v_mfma_f32_16x16x32_bf16 v[28:31], v[146:149], v[202:205], v[28:31]
	v_mfma_f32_16x16x32_bf16 v[24:27], v[162:165], v[202:205], v[24:27]
	v_mfma_f32_16x16x32_bf16 v[12:15], v[146:149], v[210:213], v[12:15]
	v_mfma_f32_16x16x32_bf16 v[8:11], v[162:165], v[210:213], v[8:11]
	v_mfma_f32_16x16x32_bf16 v[60:63], v[158:161], v[190:193], v[60:63]
	v_mfma_f32_16x16x32_bf16 v[56:59], v[166:169], v[190:193], v[56:59]
	v_mfma_f32_16x16x32_bf16 v[44:47], v[158:161], v[198:201], v[44:47]
	v_mfma_f32_16x16x32_bf16 v[40:43], v[166:169], v[198:201], v[40:43]
	v_mfma_f32_16x16x32_bf16 v[28:31], v[158:161], v[206:209], v[28:31]
	v_mfma_f32_16x16x32_bf16 v[24:27], v[166:169], v[206:209], v[24:27]
	v_mfma_f32_16x16x32_bf16 v[12:15], v[158:161], v[214:217], v[12:15]
	v_mfma_f32_16x16x32_bf16 v[8:11], v[166:169], v[214:217], v[8:11]
	v_mfma_f32_16x16x32_bf16 v[52:55], v[170:173], v[186:189], v[52:55]
	v_mfma_f32_16x16x32_bf16 v[48:51], v[178:181], v[186:189], v[48:51]
	v_mfma_f32_16x16x32_bf16 v[36:39], v[170:173], v[194:197], v[36:39]
	v_mfma_f32_16x16x32_bf16 v[32:35], v[178:181], v[194:197], v[32:35]
	v_mfma_f32_16x16x32_bf16 v[20:23], v[170:173], v[202:205], v[20:23]
	v_mfma_f32_16x16x32_bf16 v[16:19], v[178:181], v[202:205], v[16:19]
	v_mfma_f32_16x16x32_bf16 v[4:7], v[170:173], v[210:213], v[4:7]
	v_mfma_f32_16x16x32_bf16 v[0:3], v[178:181], v[210:213], v[0:3]
	v_mfma_f32_16x16x32_bf16 v[52:55], v[174:177], v[190:193], v[52:55]
	v_mfma_f32_16x16x32_bf16 v[48:51], v[182:185], v[190:193], v[48:51]
	v_mfma_f32_16x16x32_bf16 v[36:39], v[174:177], v[198:201], v[36:39]
	v_mfma_f32_16x16x32_bf16 v[32:35], v[182:185], v[198:201], v[32:35]
	v_mfma_f32_16x16x32_bf16 v[20:23], v[174:177], v[206:209], v[20:23]
	v_mfma_f32_16x16x32_bf16 v[16:19], v[182:185], v[206:209], v[16:19]
	v_mfma_f32_16x16x32_bf16 v[4:7], v[174:177], v[214:217], v[4:7]
	v_mfma_f32_16x16x32_bf16 v[0:3], v[182:185], v[214:217], v[0:3]
	s_barrier
	s_setprio 0
	s_add_i32 s62, 0, 0x18000
	s_add_i32 s63, 0, 0x1c000
	v_add_u32_e32 v166, s62, v151
	v_add_u32_e32 v182, s63, v151
	ds_read_b128 v[146:149], v166
	ds_read_b128 v[158:161], v166 offset:1024
	ds_read_b128 v[162:165], v166 offset:2048
	ds_read_b128 v[166:169], v166 offset:3072
	ds_read_b128 v[170:173], v182
	ds_read_b128 v[174:177], v182 offset:1024
	ds_read_b128 v[178:181], v182 offset:2048
	ds_read_b128 v[182:185], v182 offset:3072
	s_add_u32 s36, s36, 0x80000
	s_addc_u32 s37, s37, 0
	s_mov_b32 m0, s50
	v_lshl_add_u64 v[226:227], s[36:37], 0, v[128:129]
	ds_read_b128 v[186:189], v155 offset:32768
	ds_read_b128 v[190:193], v155 offset:33792
	ds_read_b128 v[194:197], v155 offset:34816
	ds_read_b128 v[198:201], v155 offset:35840
	ds_read_b128 v[202:205], v155 offset:36864
	ds_read_b128 v[206:209], v155 offset:37888
	ds_read_b128 v[210:213], v155 offset:38912
	ds_read_b128 v[214:217], v155 offset:39936
	global_load_lds_dwordx4 v[226:227], off
	v_lshl_add_u64 v[226:227], s[36:37], 0, v[132:133]
	s_mov_b32 m0, s51
	s_nop 0
	global_load_lds_dwordx4 v[226:227], off
	s_waitcnt vmcnt(8)
	s_waitcnt lgkmcnt(0)
	s_setprio 1
	s_barrier
	v_mfma_f32_16x16x32_bf16 v[124:127], v[146:149], v[186:189], v[124:127]
	v_mfma_f32_16x16x32_bf16 v[120:123], v[162:165], v[186:189], v[120:123]
	v_mfma_f32_16x16x32_bf16 v[108:111], v[146:149], v[194:197], v[108:111]
	v_mfma_f32_16x16x32_bf16 v[104:107], v[162:165], v[194:197], v[104:107]
	v_mfma_f32_16x16x32_bf16 v[92:95], v[146:149], v[202:205], v[92:95]
	v_mfma_f32_16x16x32_bf16 v[88:91], v[162:165], v[202:205], v[88:91]
	v_mfma_f32_16x16x32_bf16 v[76:79], v[146:149], v[210:213], v[76:79]
	v_mfma_f32_16x16x32_bf16 v[72:75], v[162:165], v[210:213], v[72:75]
	v_mfma_f32_16x16x32_bf16 v[124:127], v[158:161], v[190:193], v[124:127]
	v_mfma_f32_16x16x32_bf16 v[120:123], v[166:169], v[190:193], v[120:123]
	v_mfma_f32_16x16x32_bf16 v[108:111], v[158:161], v[198:201], v[108:111]
	v_mfma_f32_16x16x32_bf16 v[104:107], v[166:169], v[198:201], v[104:107]
	v_mfma_f32_16x16x32_bf16 v[92:95], v[158:161], v[206:209], v[92:95]
	v_mfma_f32_16x16x32_bf16 v[88:91], v[166:169], v[206:209], v[88:91]
	v_mfma_f32_16x16x32_bf16 v[76:79], v[158:161], v[214:217], v[76:79]
	v_mfma_f32_16x16x32_bf16 v[72:75], v[166:169], v[214:217], v[72:75]
	v_mfma_f32_16x16x32_bf16 v[116:119], v[170:173], v[186:189], v[116:119]
	v_mfma_f32_16x16x32_bf16 v[112:115], v[178:181], v[186:189], v[112:115]
	v_mfma_f32_16x16x32_bf16 v[100:103], v[170:173], v[194:197], v[100:103]
	v_mfma_f32_16x16x32_bf16 v[96:99], v[178:181], v[194:197], v[96:99]
	v_mfma_f32_16x16x32_bf16 v[84:87], v[170:173], v[202:205], v[84:87]
	v_mfma_f32_16x16x32_bf16 v[80:83], v[178:181], v[202:205], v[80:83]
	v_mfma_f32_16x16x32_bf16 v[68:71], v[170:173], v[210:213], v[68:71]
	v_mfma_f32_16x16x32_bf16 v[64:67], v[178:181], v[210:213], v[64:67]
	v_mfma_f32_16x16x32_bf16 v[116:119], v[174:177], v[190:193], v[116:119]
	v_mfma_f32_16x16x32_bf16 v[112:115], v[182:185], v[190:193], v[112:115]
	v_mfma_f32_16x16x32_bf16 v[100:103], v[174:177], v[198:201], v[100:103]
	v_mfma_f32_16x16x32_bf16 v[96:99], v[182:185], v[198:201], v[96:99]
	v_mfma_f32_16x16x32_bf16 v[84:87], v[174:177], v[206:209], v[84:87]
	v_mfma_f32_16x16x32_bf16 v[80:83], v[182:185], v[206:209], v[80:83]
	v_mfma_f32_16x16x32_bf16 v[68:71], v[174:177], v[214:217], v[68:71]
	v_mfma_f32_16x16x32_bf16 v[64:67], v[182:185], v[214:217], v[64:67]
	s_barrier
	s_setprio 0
	s_add_i32 s36, s62, s48
	v_lshl_add_u64 v[218:219], v[218:219], 0, s[14:15]
	s_mov_b32 m0, s36
	ds_read_b128 v[186:189], v155 offset:49152
	ds_read_b128 v[190:193], v155 offset:50176
	ds_read_b128 v[194:197], v155 offset:51200
	ds_read_b128 v[198:201], v155 offset:52224
	ds_read_b128 v[202:205], v155 offset:53248
	ds_read_b128 v[206:209], v155 offset:54272
	ds_read_b128 v[210:213], v155 offset:55296
	ds_read_b128 v[214:217], v155 offset:56320
	global_load_lds_dwordx4 v[218:219], off
	s_add_i32 m0, s36, 0x2000
	s_add_u32 s34, s34, 0x80080
	v_lshl_add_u64 v[218:219], v[220:221], 0, s[14:15]
	s_addc_u32 s35, s35, 0
	s_add_i32 s36, s63, s48
	global_load_lds_dwordx4 v[218:219], off
	v_lshl_add_u64 v[218:219], s[34:35], 0, v[130:131]
	s_mov_b32 m0, s36
	s_nop 0
	global_load_lds_dwordx4 v[218:219], off
	v_lshl_add_u64 v[218:219], s[34:35], 0, v[134:135]
	s_add_i32 m0, s36, 0x2000
	s_nop 0
	global_load_lds_dwordx4 v[218:219], off
	v_lshl_add_u64 v[218:219], v[222:223], 0, s[14:15]
	s_mov_b32 m0, s53
	s_nop 0
	global_load_lds_dwordx4 v[218:219], off
	v_lshl_add_u64 v[218:219], v[224:225], 0, s[14:15]
	s_mov_b32 m0, s54
	s_nop 0
	global_load_lds_dwordx4 v[218:219], off
	s_waitcnt vmcnt(8)
	s_waitcnt lgkmcnt(0)
	s_setprio 1
	s_barrier
	v_mfma_f32_16x16x32_bf16 v[60:63], v[146:149], v[186:189], v[60:63]
	v_mfma_f32_16x16x32_bf16 v[56:59], v[162:165], v[186:189], v[56:59]
	v_mfma_f32_16x16x32_bf16 v[44:47], v[146:149], v[194:197], v[44:47]
	v_mfma_f32_16x16x32_bf16 v[40:43], v[162:165], v[194:197], v[40:43]
	v_mfma_f32_16x16x32_bf16 v[28:31], v[146:149], v[202:205], v[28:31]
	v_mfma_f32_16x16x32_bf16 v[24:27], v[162:165], v[202:205], v[24:27]
	v_mfma_f32_16x16x32_bf16 v[12:15], v[146:149], v[210:213], v[12:15]
	v_mfma_f32_16x16x32_bf16 v[8:11], v[162:165], v[210:213], v[8:11]
	v_mfma_f32_16x16x32_bf16 v[60:63], v[158:161], v[190:193], v[60:63]
	v_mfma_f32_16x16x32_bf16 v[56:59], v[166:169], v[190:193], v[56:59]
	v_mfma_f32_16x16x32_bf16 v[44:47], v[158:161], v[198:201], v[44:47]
	v_mfma_f32_16x16x32_bf16 v[40:43], v[166:169], v[198:201], v[40:43]
	v_mfma_f32_16x16x32_bf16 v[28:31], v[158:161], v[206:209], v[28:31]
	v_mfma_f32_16x16x32_bf16 v[24:27], v[166:169], v[206:209], v[24:27]
	v_mfma_f32_16x16x32_bf16 v[12:15], v[158:161], v[214:217], v[12:15]
	v_mfma_f32_16x16x32_bf16 v[8:11], v[166:169], v[214:217], v[8:11]
	v_mfma_f32_16x16x32_bf16 v[52:55], v[170:173], v[186:189], v[52:55]
	v_mfma_f32_16x16x32_bf16 v[48:51], v[178:181], v[186:189], v[48:51]
	v_mfma_f32_16x16x32_bf16 v[36:39], v[170:173], v[194:197], v[36:39]
	v_mfma_f32_16x16x32_bf16 v[32:35], v[178:181], v[194:197], v[32:35]
	v_mfma_f32_16x16x32_bf16 v[20:23], v[170:173], v[202:205], v[20:23]
	v_mfma_f32_16x16x32_bf16 v[16:19], v[178:181], v[202:205], v[16:19]
	v_mfma_f32_16x16x32_bf16 v[4:7], v[170:173], v[210:213], v[4:7]
	v_mfma_f32_16x16x32_bf16 v[0:3], v[178:181], v[210:213], v[0:3]
	v_mfma_f32_16x16x32_bf16 v[52:55], v[174:177], v[190:193], v[52:55]
	v_mfma_f32_16x16x32_bf16 v[48:51], v[182:185], v[190:193], v[48:51]
	v_mfma_f32_16x16x32_bf16 v[36:39], v[174:177], v[198:201], v[36:39]
	v_mfma_f32_16x16x32_bf16 v[32:35], v[182:185], v[198:201], v[32:35]
	v_mfma_f32_16x16x32_bf16 v[20:23], v[174:177], v[206:209], v[20:23]
	v_mfma_f32_16x16x32_bf16 v[16:19], v[182:185], v[206:209], v[16:19]
	v_mfma_f32_16x16x32_bf16 v[4:7], v[174:177], v[214:217], v[4:7]
	v_mfma_f32_16x16x32_bf16 v[0:3], v[182:185], v[214:217], v[0:3]
	s_barrier
	s_setprio 0
	s_add_i32 s61, s61, 2
	s_add_u32 s59, s59, 0x100
	s_addc_u32 s60, s60, 0
	s_add_u32 s30, s30, 0x100
	s_addc_u32 s31, s31, 0
	s_cmp_gt_u32 s61, 29
	s_cbranch_scc0 .LBB0_731
	s_and_b64 vcc, exec, s[16:17]
	s_cbranch_vccz .LBB0_734
	s_barrier

.LBB0_952:
	ds_read_b128 v[144:147], v151
	ds_read_b128 v[156:159], v151 offset:1024
	ds_read_b128 v[160:163], v151 offset:2048
	ds_read_b128 v[164:167], v151 offset:3072
	ds_read_b128 v[168:171], v152
	ds_read_b128 v[172:175], v152 offset:1024
	ds_read_b128 v[176:179], v152 offset:2048
	ds_read_b128 v[180:183], v152 offset:3072
	s_add_u32 s54, s52, 0xfff80080
	s_addc_u32 s55, s53, -1
	s_cmp_eq_u32 s68, 28
	s_cselect_b32 s57, s27, s55
	s_cselect_b32 s56, s37, s54
	s_cselect_b32 s55, s25, s67
	s_cselect_b32 s54, s46, s47
	v_lshl_add_u64 v[216:217], s[52:53], 0, v[138:139]
	s_add_i32 m0, s59, 0xc000
	ds_read_b128 v[184:187], v153
	ds_read_b128 v[188:191], v153 offset:1024
	ds_read_b128 v[192:195], v153 offset:2048
	ds_read_b128 v[196:199], v153 offset:3072
	ds_read_b128 v[200:203], v153 offset:4096
	ds_read_b128 v[204:207], v153 offset:5120
	ds_read_b128 v[208:211], v153 offset:6144
	ds_read_b128 v[212:215], v153 offset:7168
	global_load_lds_dwordx4 v[216:217], off
	v_lshl_add_u64 v[216:217], s[52:53], 0, v[136:137]
	s_add_i32 m0, s59, 0xe000
	s_nop 0
	global_load_lds_dwordx4 v[216:217], off
	s_waitcnt vmcnt(8)
	s_waitcnt lgkmcnt(0)
	s_setprio 1
	s_barrier
	v_mfma_f32_16x16x32_bf16 v[116:119], v[144:147], v[184:187], v[116:119]
	v_mfma_f32_16x16x32_bf16 v[112:115], v[160:163], v[184:187], v[112:115]
	v_mfma_f32_16x16x32_bf16 v[104:107], v[144:147], v[192:195], v[104:107]
	v_mfma_f32_16x16x32_bf16 v[96:99], v[160:163], v[192:195], v[96:99]
	v_mfma_f32_16x16x32_bf16 v[88:91], v[144:147], v[200:203], v[88:91]
	v_mfma_f32_16x16x32_bf16 v[80:83], v[160:163], v[200:203], v[80:83]
	v_mfma_f32_16x16x32_bf16 v[72:75], v[144:147], v[208:211], v[72:75]
	v_mfma_f32_16x16x32_bf16 v[64:67], v[160:163], v[208:211], v[64:67]
	v_mfma_f32_16x16x32_bf16 v[116:119], v[156:159], v[188:191], v[116:119]
	v_mfma_f32_16x16x32_bf16 v[112:115], v[164:167], v[188:191], v[112:115]
	v_mfma_f32_16x16x32_bf16 v[104:107], v[156:159], v[196:199], v[104:107]
	v_mfma_f32_16x16x32_bf16 v[96:99], v[164:167], v[196:199], v[96:99]
	v_mfma_f32_16x16x32_bf16 v[88:91], v[156:159], v[204:207], v[88:91]
	v_mfma_f32_16x16x32_bf16 v[80:83], v[164:167], v[204:207], v[80:83]
	v_mfma_f32_16x16x32_bf16 v[72:75], v[156:159], v[212:215], v[72:75]
	v_mfma_f32_16x16x32_bf16 v[64:67], v[164:167], v[212:215], v[64:67]
	v_mfma_f32_16x16x32_bf16 v[124:127], v[168:171], v[184:187], v[124:127]
	v_mfma_f32_16x16x32_bf16 v[120:123], v[176:179], v[184:187], v[120:123]
	v_mfma_f32_16x16x32_bf16 v[108:111], v[168:171], v[192:195], v[108:111]
	v_mfma_f32_16x16x32_bf16 v[100:103], v[176:179], v[192:195], v[100:103]
	v_mfma_f32_16x16x32_bf16 v[92:95], v[168:171], v[200:203], v[92:95]
	v_mfma_f32_16x16x32_bf16 v[84:87], v[176:179], v[200:203], v[84:87]
	v_mfma_f32_16x16x32_bf16 v[76:79], v[168:171], v[208:211], v[76:79]
	v_mfma_f32_16x16x32_bf16 v[68:71], v[176:179], v[208:211], v[68:71]
	v_mfma_f32_16x16x32_bf16 v[124:127], v[172:175], v[188:191], v[124:127]
	v_mfma_f32_16x16x32_bf16 v[120:123], v[180:183], v[188:191], v[120:123]
	v_mfma_f32_16x16x32_bf16 v[108:111], v[172:175], v[196:199], v[108:111]
	v_mfma_f32_16x16x32_bf16 v[100:103], v[180:183], v[196:199], v[100:103]
	v_mfma_f32_16x16x32_bf16 v[92:95], v[172:175], v[204:207], v[92:95]
	v_mfma_f32_16x16x32_bf16 v[84:87], v[180:183], v[204:207], v[84:87]
	v_mfma_f32_16x16x32_bf16 v[76:79], v[172:175], v[212:215], v[76:79]
	v_mfma_f32_16x16x32_bf16 v[68:71], v[180:183], v[212:215], v[68:71]
	s_barrier
	s_setprio 0
	s_add_i32 s69, s64, s58
	v_lshl_add_u64 v[216:217], s[54:55], 0, v[130:131]
	s_mov_b32 m0, s69
	ds_read_b128 v[184:187], v153 offset:16384
	ds_read_b128 v[188:191], v153 offset:17408
	ds_read_b128 v[192:195], v153 offset:18432
	ds_read_b128 v[196:199], v153 offset:19456
	ds_read_b128 v[200:203], v153 offset:20480
	ds_read_b128 v[204:207], v153 offset:21504
	ds_read_b128 v[208:211], v153 offset:22528
	ds_read_b128 v[212:215], v153 offset:23552
	global_load_lds_dwordx4 v[216:217], off
	s_add_i32 m0, s69, 0x2000
	s_add_u32 s70, s54, 0x80000
	v_lshl_add_u64 v[218:219], s[54:55], 0, v[134:135]
	s_addc_u32 s71, s55, 0
	s_add_i32 s69, s65, s58
	global_load_lds_dwordx4 v[218:219], off
	v_lshl_add_u64 v[220:221], s[70:71], 0, v[130:131]
	s_mov_b32 m0, s69
	v_lshl_add_u64 v[222:223], s[56:57], 0, v[132:133]
	global_load_lds_dwordx4 v[220:221], off
	v_lshl_add_u64 v[220:221], s[70:71], 0, v[134:135]
	s_add_i32 m0, s69, 0x2000
	s_nop 0
	global_load_lds_dwordx4 v[220:221], off
	v_lshl_add_u64 v[220:221], s[56:57], 0, v[128:129]
	s_mov_b32 m0, s59
	s_nop 0
	global_load_lds_dwordx4 v[220:221], off
	s_mov_b32 m0, s50
	s_nop 0
	global_load_lds_dwordx4 v[222:223], off
	s_waitcnt vmcnt(8)
	s_waitcnt lgkmcnt(0)
	s_setprio 1
	s_barrier
	v_mfma_f32_16x16x32_bf16 v[56:59], v[144:147], v[184:187], v[56:59]
	v_mfma_f32_16x16x32_bf16 v[48:51], v[160:163], v[184:187], v[48:51]
	v_mfma_f32_16x16x32_bf16 v[40:43], v[144:147], v[192:195], v[40:43]
	v_mfma_f32_16x16x32_bf16 v[32:35], v[160:163], v[192:195], v[32:35]
	v_mfma_f32_16x16x32_bf16 v[24:27], v[144:147], v[200:203], v[24:27]
	v_mfma_f32_16x16x32_bf16 v[16:19], v[160:163], v[200:203], v[16:19]
	v_mfma_f32_16x16x32_bf16 v[8:11], v[144:147], v[208:211], v[8:11]
	v_mfma_f32_16x16x32_bf16 v[0:3], v[160:163], v[208:211], v[0:3]
	v_mfma_f32_16x16x32_bf16 v[56:59], v[156:159], v[188:191], v[56:59]
	v_mfma_f32_16x16x32_bf16 v[48:51], v[164:167], v[188:191], v[48:51]
	v_mfma_f32_16x16x32_bf16 v[40:43], v[156:159], v[196:199], v[40:43]
	v_mfma_f32_16x16x32_bf16 v[32:35], v[164:167], v[196:199], v[32:35]
	v_mfma_f32_16x16x32_bf16 v[24:27], v[156:159], v[204:207], v[24:27]
	v_mfma_f32_16x16x32_bf16 v[16:19], v[164:167], v[204:207], v[16:19]
	v_mfma_f32_16x16x32_bf16 v[8:11], v[156:159], v[212:215], v[8:11]
	v_mfma_f32_16x16x32_bf16 v[0:3], v[164:167], v[212:215], v[0:3]
	v_mfma_f32_16x16x32_bf16 v[60:63], v[168:171], v[184:187], v[60:63]
	v_mfma_f32_16x16x32_bf16 v[52:55], v[176:179], v[184:187], v[52:55]
	v_mfma_f32_16x16x32_bf16 v[44:47], v[168:171], v[192:195], v[44:47]
	v_mfma_f32_16x16x32_bf16 v[36:39], v[176:179], v[192:195], v[36:39]
	v_mfma_f32_16x16x32_bf16 v[28:31], v[168:171], v[200:203], v[28:31]
	v_mfma_f32_16x16x32_bf16 v[20:23], v[176:179], v[200:203], v[20:23]
	v_mfma_f32_16x16x32_bf16 v[12:15], v[168:171], v[208:211], v[12:15]
	v_mfma_f32_16x16x32_bf16 v[4:7], v[176:179], v[208:211], v[4:7]
	v_mfma_f32_16x16x32_bf16 v[60:63], v[172:175], v[188:191], v[60:63]
	v_mfma_f32_16x16x32_bf16 v[52:55], v[180:183], v[188:191], v[52:55]
	v_mfma_f32_16x16x32_bf16 v[44:47], v[172:175], v[196:199], v[44:47]
	v_mfma_f32_16x16x32_bf16 v[36:39], v[180:183], v[196:199], v[36:39]
	v_mfma_f32_16x16x32_bf16 v[28:31], v[172:175], v[204:207], v[28:31]
	v_mfma_f32_16x16x32_bf16 v[20:23], v[180:183], v[204:207], v[20:23]
	v_mfma_f32_16x16x32_bf16 v[12:15], v[172:175], v[212:215], v[12:15]
	v_mfma_f32_16x16x32_bf16 v[4:7], v[180:183], v[212:215], v[4:7]
	s_barrier
	s_setprio 0
	s_add_i32 s69, 0, 0x18000
	v_add_u32_e32 v155, s69, v149
	s_add_i32 s70, 0, 0x1c000
	ds_read_b128 v[144:147], v155
	ds_read_b128 v[156:159], v155 offset:1024
	ds_read_b128 v[160:163], v155 offset:2048
	ds_read_b128 v[164:167], v155 offset:3072
	v_add_u32_e32 v155, s70, v149
	ds_read_b128 v[168:171], v155
	ds_read_b128 v[172:175], v155 offset:1024
	ds_read_b128 v[176:179], v155 offset:2048
	ds_read_b128 v[180:183], v155 offset:3072
	s_add_u32 s56, s56, 0x80000
	s_addc_u32 s57, s57, 0
	s_mov_b32 m0, s51
	v_lshl_add_u64 v[224:225], s[56:57], 0, v[128:129]
	ds_read_b128 v[184:187], v153 offset:32768
	ds_read_b128 v[188:191], v153 offset:33792
	ds_read_b128 v[192:195], v153 offset:34816
	ds_read_b128 v[196:199], v153 offset:35840
	ds_read_b128 v[200:203], v153 offset:36864
	ds_read_b128 v[204:207], v153 offset:37888
	ds_read_b128 v[208:211], v153 offset:38912
	ds_read_b128 v[212:215], v153 offset:39936
	global_load_lds_dwordx4 v[224:225], off
	v_lshl_add_u64 v[224:225], s[56:57], 0, v[132:133]
	s_mov_b32 m0, s60
	s_nop 0
	global_load_lds_dwordx4 v[224:225], off
	s_waitcnt vmcnt(8)
	s_waitcnt lgkmcnt(0)
	s_setprio 1
	s_barrier
	v_mfma_f32_16x16x32_bf16 v[116:119], v[144:147], v[184:187], v[116:119]
	v_mfma_f32_16x16x32_bf16 v[112:115], v[160:163], v[184:187], v[112:115]
	v_mfma_f32_16x16x32_bf16 v[104:107], v[144:147], v[192:195], v[104:107]
	v_mfma_f32_16x16x32_bf16 v[96:99], v[160:163], v[192:195], v[96:99]
	v_mfma_f32_16x16x32_bf16 v[88:91], v[144:147], v[200:203], v[88:91]
	v_mfma_f32_16x16x32_bf16 v[80:83], v[160:163], v[200:203], v[80:83]
	v_mfma_f32_16x16x32_bf16 v[72:75], v[144:147], v[208:211], v[72:75]
	v_mfma_f32_16x16x32_bf16 v[64:67], v[160:163], v[208:211], v[64:67]
	v_mfma_f32_16x16x32_bf16 v[116:119], v[156:159], v[188:191], v[116:119]
	v_mfma_f32_16x16x32_bf16 v[112:115], v[164:167], v[188:191], v[112:115]
	v_mfma_f32_16x16x32_bf16 v[104:107], v[156:159], v[196:199], v[104:107]
	v_mfma_f32_16x16x32_bf16 v[96:99], v[164:167], v[196:199], v[96:99]
	v_mfma_f32_16x16x32_bf16 v[88:91], v[156:159], v[204:207], v[88:91]
	v_mfma_f32_16x16x32_bf16 v[80:83], v[164:167], v[204:207], v[80:83]
	v_mfma_f32_16x16x32_bf16 v[72:75], v[156:159], v[212:215], v[72:75]
	v_mfma_f32_16x16x32_bf16 v[64:67], v[164:167], v[212:215], v[64:67]
	v_mfma_f32_16x16x32_bf16 v[124:127], v[168:171], v[184:187], v[124:127]
	v_mfma_f32_16x16x32_bf16 v[120:123], v[176:179], v[184:187], v[120:123]
	v_mfma_f32_16x16x32_bf16 v[108:111], v[168:171], v[192:195], v[108:111]
	v_mfma_f32_16x16x32_bf16 v[100:103], v[176:179], v[192:195], v[100:103]
	v_mfma_f32_16x16x32_bf16 v[92:95], v[168:171], v[200:203], v[92:95]
	v_mfma_f32_16x16x32_bf16 v[84:87], v[176:179], v[200:203], v[84:87]
	v_mfma_f32_16x16x32_bf16 v[76:79], v[168:171], v[208:211], v[76:79]
	v_mfma_f32_16x16x32_bf16 v[68:71], v[176:179], v[208:211], v[68:71]
	v_mfma_f32_16x16x32_bf16 v[124:127], v[172:175], v[188:191], v[124:127]
	v_mfma_f32_16x16x32_bf16 v[120:123], v[180:183], v[188:191], v[120:123]
	v_mfma_f32_16x16x32_bf16 v[108:111], v[172:175], v[196:199], v[108:111]
	v_mfma_f32_16x16x32_bf16 v[100:103], v[180:183], v[196:199], v[100:103]
	v_mfma_f32_16x16x32_bf16 v[92:95], v[172:175], v[204:207], v[92:95]
	v_mfma_f32_16x16x32_bf16 v[84:87], v[180:183], v[204:207], v[84:87]
	v_mfma_f32_16x16x32_bf16 v[76:79], v[172:175], v[212:215], v[76:79]
	v_mfma_f32_16x16x32_bf16 v[68:71], v[180:183], v[212:215], v[68:71]
	s_barrier
	s_setprio 0
	s_add_i32 s56, s69, s58
	v_lshl_add_u64 v[216:217], v[216:217], 0, s[20:21]
	s_mov_b32 m0, s56
	ds_read_b128 v[184:187], v153 offset:49152
	ds_read_b128 v[188:191], v153 offset:50176
	ds_read_b128 v[192:195], v153 offset:51200
	ds_read_b128 v[196:199], v153 offset:52224
	ds_read_b128 v[200:203], v153 offset:53248
	ds_read_b128 v[204:207], v153 offset:54272
	ds_read_b128 v[208:211], v153 offset:55296
	ds_read_b128 v[212:215], v153 offset:56320
	global_load_lds_dwordx4 v[216:217], off
	s_add_i32 m0, s56, 0x2000
	s_add_u32 s54, s54, 0x80080
	v_lshl_add_u64 v[216:217], v[218:219], 0, s[20:21]
	s_addc_u32 s55, s55, 0
	s_add_i32 s56, s70, s58
	global_load_lds_dwordx4 v[216:217], off
	v_lshl_add_u64 v[216:217], s[54:55], 0, v[130:131]
	s_mov_b32 m0, s56
	s_nop 0
	global_load_lds_dwordx4 v[216:217], off
	v_lshl_add_u64 v[216:217], s[54:55], 0, v[134:135]
	s_add_i32 m0, s56, 0x2000
	s_nop 0
	global_load_lds_dwordx4 v[216:217], off
	v_lshl_add_u64 v[216:217], v[220:221], 0, s[20:21]
	s_mov_b32 m0, s62
	s_nop 0
	global_load_lds_dwordx4 v[216:217], off
	v_lshl_add_u64 v[216:217], v[222:223], 0, s[20:21]
	s_mov_b32 m0, s63
	s_nop 0
	global_load_lds_dwordx4 v[216:217], off
	s_waitcnt vmcnt(8)
	s_waitcnt lgkmcnt(0)
	s_setprio 1
	s_barrier
	v_mfma_f32_16x16x32_bf16 v[56:59], v[144:147], v[184:187], v[56:59]
	v_mfma_f32_16x16x32_bf16 v[48:51], v[160:163], v[184:187], v[48:51]
	v_mfma_f32_16x16x32_bf16 v[40:43], v[144:147], v[192:195], v[40:43]
	v_mfma_f32_16x16x32_bf16 v[32:35], v[160:163], v[192:195], v[32:35]
	v_mfma_f32_16x16x32_bf16 v[24:27], v[144:147], v[200:203], v[24:27]
	v_mfma_f32_16x16x32_bf16 v[16:19], v[160:163], v[200:203], v[16:19]
	v_mfma_f32_16x16x32_bf16 v[8:11], v[144:147], v[208:211], v[8:11]
	v_mfma_f32_16x16x32_bf16 v[0:3], v[160:163], v[208:211], v[0:3]
	v_mfma_f32_16x16x32_bf16 v[56:59], v[156:159], v[188:191], v[56:59]
	v_mfma_f32_16x16x32_bf16 v[48:51], v[164:167], v[188:191], v[48:51]
	v_mfma_f32_16x16x32_bf16 v[40:43], v[156:159], v[196:199], v[40:43]
	v_mfma_f32_16x16x32_bf16 v[32:35], v[164:167], v[196:199], v[32:35]
	v_mfma_f32_16x16x32_bf16 v[24:27], v[156:159], v[204:207], v[24:27]
	v_mfma_f32_16x16x32_bf16 v[16:19], v[164:167], v[204:207], v[16:19]
	v_mfma_f32_16x16x32_bf16 v[8:11], v[156:159], v[212:215], v[8:11]
	v_mfma_f32_16x16x32_bf16 v[0:3], v[164:167], v[212:215], v[0:3]
	v_mfma_f32_16x16x32_bf16 v[60:63], v[168:171], v[184:187], v[60:63]
	v_mfma_f32_16x16x32_bf16 v[52:55], v[176:179], v[184:187], v[52:55]
	v_mfma_f32_16x16x32_bf16 v[44:47], v[168:171], v[192:195], v[44:47]
	v_mfma_f32_16x16x32_bf16 v[36:39], v[176:179], v[192:195], v[36:39]
	v_mfma_f32_16x16x32_bf16 v[28:31], v[168:171], v[200:203], v[28:31]
	v_mfma_f32_16x16x32_bf16 v[20:23], v[176:179], v[200:203], v[20:23]
	v_mfma_f32_16x16x32_bf16 v[12:15], v[168:171], v[208:211], v[12:15]
	v_mfma_f32_16x16x32_bf16 v[4:7], v[176:179], v[208:211], v[4:7]
	v_mfma_f32_16x16x32_bf16 v[60:63], v[172:175], v[188:191], v[60:63]
	v_mfma_f32_16x16x32_bf16 v[52:55], v[180:183], v[188:191], v[52:55]
	v_mfma_f32_16x16x32_bf16 v[44:47], v[172:175], v[196:199], v[44:47]
	v_mfma_f32_16x16x32_bf16 v[36:39], v[180:183], v[196:199], v[36:39]
	v_mfma_f32_16x16x32_bf16 v[28:31], v[172:175], v[204:207], v[28:31]
	v_mfma_f32_16x16x32_bf16 v[20:23], v[180:183], v[204:207], v[20:23]
	v_mfma_f32_16x16x32_bf16 v[12:15], v[172:175], v[212:215], v[12:15]
	v_mfma_f32_16x16x32_bf16 v[4:7], v[180:183], v[212:215], v[4:7]
	s_barrier
	s_setprio 0
	s_add_i32 s68, s68, 2
	s_add_u32 s47, s47, 0x100
	s_addc_u32 s67, s67, 0
	s_add_u32 s52, s52, 0x100
	s_addc_u32 s53, s53, 0
	s_cmp_gt_u32 s68, 29
	s_cbranch_scc0 .LBB0_952
	s_and_b64 vcc, exec, s[22:23]
	s_cbranch_vccz .LBB0_955
	s_barrier

.Lsegback_3:
	s_add_i32 s81, s81, 2
	s_add_u32 s79, s79, 0x100
	s_addc_u32 s80, s80, 0
	s_add_u32 s48, s48, 0x100
	s_addc_u32 s49, s49, 0
	s_cmp_gt_u32 s81, 29
	s_cbranch_scc1 .LBB0_1053
.LBB0_1049:
	ds_read_b128 v[148:151], v222
	ds_read_b128 v[152:155], v222 offset:1024
	ds_read_b128 v[156:159], v222 offset:2048
	ds_read_b128 v[160:163], v222 offset:3072
	ds_read_b128 v[132:135], v223
	ds_read_b128 v[136:139], v223 offset:1024
	ds_read_b128 v[140:143], v223 offset:2048
	ds_read_b128 v[144:147], v223 offset:3072
	s_add_u32 s8, s48, 0xfff80080
	s_addc_u32 s9, s49, -1
	s_cmp_eq_u32 s81, 28
	s_cselect_b32 s53, s23, s9
	s_cselect_b32 s52, s46, s8
	s_cselect_b32 s51, s21, s80
	s_cselect_b32 s50, s47, s79
	v_lshl_add_u64 v[2:3], s[48:49], 0, v[208:209]
	s_add_i32 m0, s35, 0xc000
	s_waitcnt lgkmcnt(0)
	ds_read_b128 v[164:167], v224
	ds_read_b128 v[168:171], v224 offset:1024
	ds_read_b128 v[172:175], v224 offset:2048
	ds_read_b128 v[176:179], v224 offset:3072
	ds_read_b128 v[180:183], v224 offset:4096
	ds_read_b128 v[184:187], v224 offset:5120
	ds_read_b128 v[188:191], v224 offset:6144
	ds_read_b128 v[192:195], v224 offset:7168
	global_load_lds_dwordx4 v[2:3], off
	v_lshl_add_u64 v[2:3], s[48:49], 0, v[206:207]
	s_add_i32 m0, s35, 0xe000
	s_nop 0
	global_load_lds_dwordx4 v[2:3], off
	s_waitcnt vmcnt(8)
	s_waitcnt lgkmcnt(0)
	s_setprio 1
	s_barrier
	v_mfma_f32_16x16x32_bf16 v[124:127], v[148:151], v[164:167], v[124:127]
	v_mfma_f32_16x16x32_bf16 v[120:123], v[156:159], v[164:167], v[120:123]
	v_mfma_f32_16x16x32_bf16 v[104:107], v[148:151], v[172:175], v[104:107]
	v_mfma_f32_16x16x32_bf16 v[100:103], v[156:159], v[172:175], v[100:103]
	v_mfma_f32_16x16x32_bf16 v[88:91], v[148:151], v[180:183], v[88:91]
	v_mfma_f32_16x16x32_bf16 v[84:87], v[156:159], v[180:183], v[84:87]
	v_mfma_f32_16x16x32_bf16 v[76:79], v[148:151], v[188:191], v[76:79]
	v_mfma_f32_16x16x32_bf16 v[72:75], v[156:159], v[188:191], v[72:75]
	v_mfma_f32_16x16x32_bf16 v[124:127], v[152:155], v[168:171], v[124:127]
	v_mfma_f32_16x16x32_bf16 v[120:123], v[160:163], v[168:171], v[120:123]
	v_mfma_f32_16x16x32_bf16 v[104:107], v[152:155], v[176:179], v[104:107]
	v_mfma_f32_16x16x32_bf16 v[100:103], v[160:163], v[176:179], v[100:103]
	v_mfma_f32_16x16x32_bf16 v[88:91], v[152:155], v[184:187], v[88:91]
	v_mfma_f32_16x16x32_bf16 v[84:87], v[160:163], v[184:187], v[84:87]
	v_mfma_f32_16x16x32_bf16 v[76:79], v[152:155], v[192:195], v[76:79]
	v_mfma_f32_16x16x32_bf16 v[72:75], v[160:163], v[192:195], v[72:75]
	v_mfma_f32_16x16x32_bf16 v[128:131], v[132:135], v[164:167], v[128:131]
	v_mfma_f32_16x16x32_bf16 v[116:119], v[140:143], v[164:167], v[116:119]
	v_mfma_f32_16x16x32_bf16 v[112:115], v[132:135], v[172:175], v[112:115]
	v_mfma_f32_16x16x32_bf16 v[108:111], v[140:143], v[172:175], v[108:111]
	v_mfma_f32_16x16x32_bf16 v[96:99], v[132:135], v[180:183], v[96:99]
	v_mfma_f32_16x16x32_bf16 v[92:95], v[140:143], v[180:183], v[92:95]
	v_mfma_f32_16x16x32_bf16 v[80:83], v[132:135], v[188:191], v[80:83]
	v_mfma_f32_16x16x32_bf16 v[68:71], v[140:143], v[188:191], v[68:71]
	v_mfma_f32_16x16x32_bf16 v[128:131], v[136:139], v[168:171], v[128:131]
	v_mfma_f32_16x16x32_bf16 v[116:119], v[144:147], v[168:171], v[116:119]
	v_mfma_f32_16x16x32_bf16 v[112:115], v[136:139], v[176:179], v[112:115]
	v_mfma_f32_16x16x32_bf16 v[108:111], v[144:147], v[176:179], v[108:111]
	v_mfma_f32_16x16x32_bf16 v[96:99], v[136:139], v[184:187], v[96:99]
	v_mfma_f32_16x16x32_bf16 v[92:95], v[144:147], v[184:187], v[92:95]
	v_mfma_f32_16x16x32_bf16 v[80:83], v[136:139], v[192:195], v[80:83]
	v_mfma_f32_16x16x32_bf16 v[68:71], v[144:147], v[192:195], v[68:71]
	s_barrier
	s_setprio 0
	s_add_i32 s8, s65, s56
	v_lshl_add_u64 v[2:3], s[50:51], 0, v[198:199]
	s_mov_b32 m0, s8
	ds_read_b128 v[188:191], v224 offset:16384
	ds_read_b128 v[192:195], v224 offset:17408
	ds_read_b128 v[180:183], v224 offset:18432
	ds_read_b128 v[184:187], v224 offset:19456
	ds_read_b128 v[172:175], v224 offset:20480
	ds_read_b128 v[176:179], v224 offset:21504
	ds_read_b128 v[164:167], v224 offset:22528
	ds_read_b128 v[168:171], v224 offset:23552
	global_load_lds_dwordx4 v[2:3], off
	s_add_i32 m0, s8, 0x2000
	s_add_u32 s8, s50, 0x80000
	v_lshl_add_u64 v[212:213], s[50:51], 0, v[202:203]
	s_addc_u32 s9, s51, 0
	s_add_i32 s78, s66, s56
	global_load_lds_dwordx4 v[212:213], off
	v_lshl_add_u64 v[214:215], s[8:9], 0, v[198:199]
	s_mov_b32 m0, s78
	v_lshl_add_u64 v[216:217], s[52:53], 0, v[200:201]
	global_load_lds_dwordx4 v[214:215], off
	v_lshl_add_u64 v[214:215], s[8:9], 0, v[202:203]
	s_add_i32 m0, s78, 0x2000
	v_cmp_ne_u32_e64 s[8:9], 1, v227
	global_load_lds_dwordx4 v[214:215], off
	v_lshl_add_u64 v[214:215], s[52:53], 0, v[196:197]
	s_mov_b32 m0, s35
	s_andn2_b64 vcc, exec, s[36:37]
	global_load_lds_dwordx4 v[214:215], off
	s_mov_b32 m0, s58
	s_nop 0
	global_load_lds_dwordx4 v[216:217], off
	s_waitcnt vmcnt(8)
	s_waitcnt lgkmcnt(0)
	s_cbranch_vccnz .Lsegskip_2
	s_setprio 1
	s_barrier
	v_mfma_f32_16x16x32_bf16 v[56:59], v[148:151], v[188:191], v[56:59]
	v_mfma_f32_16x16x32_bf16 v[52:55], v[156:159], v[188:191], v[52:55]
	v_mfma_f32_16x16x32_bf16 v[40:43], v[148:151], v[180:183], v[40:43]
	v_mfma_f32_16x16x32_bf16 v[36:39], v[156:159], v[180:183], v[36:39]
	v_mfma_f32_16x16x32_bf16 v[24:27], v[148:151], v[172:175], v[24:27]
	v_mfma_f32_16x16x32_bf16 v[20:23], v[156:159], v[172:175], v[20:23]
	v_mfma_f32_16x16x32_bf16 v[8:11], v[148:151], v[164:167], v[8:11]
	v_mfma_f32_16x16x32_bf16 v[4:7], v[156:159], v[164:167], v[4:7]
	v_mfma_f32_16x16x32_bf16 v[56:59], v[152:155], v[192:195], v[56:59]
	v_mfma_f32_16x16x32_bf16 v[52:55], v[160:163], v[192:195], v[52:55]
	v_mfma_f32_16x16x32_bf16 v[40:43], v[152:155], v[184:187], v[40:43]
	v_mfma_f32_16x16x32_bf16 v[36:39], v[160:163], v[184:187], v[36:39]
	v_mfma_f32_16x16x32_bf16 v[24:27], v[152:155], v[176:179], v[24:27]
	v_mfma_f32_16x16x32_bf16 v[20:23], v[160:163], v[176:179], v[20:23]
	v_mfma_f32_16x16x32_bf16 v[8:11], v[152:155], v[168:171], v[8:11]
	v_mfma_f32_16x16x32_bf16 v[4:7], v[160:163], v[168:171], v[4:7]
	v_mfma_f32_16x16x32_bf16 v[64:67], v[132:135], v[188:191], v[64:67]
	v_mfma_f32_16x16x32_bf16 v[60:63], v[140:143], v[188:191], v[60:63]
	v_mfma_f32_16x16x32_bf16 v[48:51], v[132:135], v[180:183], v[48:51]
	v_mfma_f32_16x16x32_bf16 v[44:47], v[140:143], v[180:183], v[44:47]
	v_mfma_f32_16x16x32_bf16 v[32:35], v[132:135], v[172:175], v[32:35]
	v_mfma_f32_16x16x32_bf16 v[28:31], v[140:143], v[172:175], v[28:31]
	v_mfma_f32_16x16x32_bf16 v[16:19], v[132:135], v[164:167], v[16:19]
	v_mfma_f32_16x16x32_bf16 v[12:15], v[140:143], v[164:167], v[12:15]
	v_mfma_f32_16x16x32_bf16 v[64:67], v[136:139], v[192:195], v[64:67]
	v_mfma_f32_16x16x32_bf16 v[60:63], v[144:147], v[192:195], v[60:63]
	v_mfma_f32_16x16x32_bf16 v[48:51], v[136:139], v[184:187], v[48:51]
	v_mfma_f32_16x16x32_bf16 v[44:47], v[144:147], v[184:187], v[44:47]
	v_mfma_f32_16x16x32_bf16 v[32:35], v[136:139], v[176:179], v[32:35]
	v_mfma_f32_16x16x32_bf16 v[28:31], v[144:147], v[176:179], v[28:31]
	v_mfma_f32_16x16x32_bf16 v[16:19], v[136:139], v[168:171], v[16:19]
	v_mfma_f32_16x16x32_bf16 v[12:15], v[144:147], v[168:171], v[12:15]
.LBB0_1051:
	s_barrier
	s_setprio 0
	s_add_i32 s78, 0, 0x18000
	v_add_u32_e32 v1, s78, v220
	s_add_i32 s82, 0, 0x1c000
	ds_read_b128 v[148:151], v1
	ds_read_b128 v[152:155], v1 offset:1024
	ds_read_b128 v[156:159], v1 offset:2048
	ds_read_b128 v[160:163], v1 offset:3072
	v_add_u32_e32 v1, s82, v220
	ds_read_b128 v[132:135], v1
	ds_read_b128 v[136:139], v1 offset:1024
	ds_read_b128 v[140:143], v1 offset:2048
	ds_read_b128 v[144:147], v1 offset:3072
	s_add_u32 s52, s52, 0x80000
	s_addc_u32 s53, s53, 0
	s_mov_b32 m0, s59
	v_lshl_add_u64 v[228:229], s[52:53], 0, v[196:197]
	s_waitcnt lgkmcnt(0)
	ds_read_b128 v[164:167], v224 offset:32768
	ds_read_b128 v[168:171], v224 offset:33792
	ds_read_b128 v[172:175], v224 offset:34816
	ds_read_b128 v[176:179], v224 offset:35840
	ds_read_b128 v[180:183], v224 offset:36864
	ds_read_b128 v[184:187], v224 offset:37888
	ds_read_b128 v[188:191], v224 offset:38912
	ds_read_b128 v[192:195], v224 offset:39936
	global_load_lds_dwordx4 v[228:229], off
	v_lshl_add_u64 v[228:229], s[52:53], 0, v[200:201]
	s_mov_b32 m0, s60
	s_nop 0
	global_load_lds_dwordx4 v[228:229], off
	s_waitcnt vmcnt(8)
	s_waitcnt lgkmcnt(0)
	s_setprio 1
	s_barrier
	v_mfma_f32_16x16x32_bf16 v[124:127], v[148:151], v[164:167], v[124:127]
	v_mfma_f32_16x16x32_bf16 v[120:123], v[156:159], v[164:167], v[120:123]
	v_mfma_f32_16x16x32_bf16 v[104:107], v[148:151], v[172:175], v[104:107]
	v_mfma_f32_16x16x32_bf16 v[100:103], v[156:159], v[172:175], v[100:103]
	v_mfma_f32_16x16x32_bf16 v[88:91], v[148:151], v[180:183], v[88:91]
	v_mfma_f32_16x16x32_bf16 v[84:87], v[156:159], v[180:183], v[84:87]
	v_mfma_f32_16x16x32_bf16 v[76:79], v[148:151], v[188:191], v[76:79]
	v_mfma_f32_16x16x32_bf16 v[72:75], v[156:159], v[188:191], v[72:75]
	v_mfma_f32_16x16x32_bf16 v[124:127], v[152:155], v[168:171], v[124:127]
	v_mfma_f32_16x16x32_bf16 v[120:123], v[160:163], v[168:171], v[120:123]
	v_mfma_f32_16x16x32_bf16 v[104:107], v[152:155], v[176:179], v[104:107]
	v_mfma_f32_16x16x32_bf16 v[100:103], v[160:163], v[176:179], v[100:103]
	v_mfma_f32_16x16x32_bf16 v[88:91], v[152:155], v[184:187], v[88:91]
	v_mfma_f32_16x16x32_bf16 v[84:87], v[160:163], v[184:187], v[84:87]
	v_mfma_f32_16x16x32_bf16 v[76:79], v[152:155], v[192:195], v[76:79]
	v_mfma_f32_16x16x32_bf16 v[72:75], v[160:163], v[192:195], v[72:75]
	v_mfma_f32_16x16x32_bf16 v[128:131], v[132:135], v[164:167], v[128:131]
	v_mfma_f32_16x16x32_bf16 v[116:119], v[140:143], v[164:167], v[116:119]
	v_mfma_f32_16x16x32_bf16 v[112:115], v[132:135], v[172:175], v[112:115]
	v_mfma_f32_16x16x32_bf16 v[108:111], v[140:143], v[172:175], v[108:111]
	v_mfma_f32_16x16x32_bf16 v[96:99], v[132:135], v[180:183], v[96:99]
	v_mfma_f32_16x16x32_bf16 v[92:95], v[140:143], v[180:183], v[92:95]
	v_mfma_f32_16x16x32_bf16 v[80:83], v[132:135], v[188:191], v[80:83]
	v_mfma_f32_16x16x32_bf16 v[68:71], v[140:143], v[188:191], v[68:71]
	v_mfma_f32_16x16x32_bf16 v[128:131], v[136:139], v[168:171], v[128:131]
	v_mfma_f32_16x16x32_bf16 v[116:119], v[144:147], v[168:171], v[116:119]
	v_mfma_f32_16x16x32_bf16 v[112:115], v[136:139], v[176:179], v[112:115]
	v_mfma_f32_16x16x32_bf16 v[108:111], v[144:147], v[176:179], v[108:111]
	v_mfma_f32_16x16x32_bf16 v[96:99], v[136:139], v[184:187], v[96:99]
	v_mfma_f32_16x16x32_bf16 v[92:95], v[144:147], v[184:187], v[92:95]
	v_mfma_f32_16x16x32_bf16 v[80:83], v[136:139], v[192:195], v[80:83]
	v_mfma_f32_16x16x32_bf16 v[68:71], v[144:147], v[192:195], v[68:71]
	s_barrier
	s_setprio 0
	s_add_i32 s52, s78, s56
	v_lshl_add_u64 v[2:3], v[2:3], 0, s[14:15]
	s_mov_b32 m0, s52
	ds_read_b128 v[188:191], v224 offset:49152
	ds_read_b128 v[192:195], v224 offset:50176
	ds_read_b128 v[180:183], v224 offset:51200
	ds_read_b128 v[184:187], v224 offset:52224
	ds_read_b128 v[172:175], v224 offset:53248
	ds_read_b128 v[176:179], v224 offset:54272
	ds_read_b128 v[164:167], v224 offset:55296
	ds_read_b128 v[168:171], v224 offset:56320
	global_load_lds_dwordx4 v[2:3], off
	s_add_i32 m0, s52, 0x2000
	s_add_u32 s50, s50, 0x80080
	v_lshl_add_u64 v[2:3], v[212:213], 0, s[14:15]
	s_addc_u32 s51, s51, 0
	s_add_i32 s52, s82, s56
	global_load_lds_dwordx4 v[2:3], off
	v_lshl_add_u64 v[2:3], s[50:51], 0, v[198:199]
	s_mov_b32 m0, s52
	s_and_b64 vcc, exec, s[8:9]
	global_load_lds_dwordx4 v[2:3], off
	v_lshl_add_u64 v[2:3], s[50:51], 0, v[202:203]
	s_add_i32 m0, s52, 0x2000
	s_nop 0
	global_load_lds_dwordx4 v[2:3], off
	v_lshl_add_u64 v[2:3], v[214:215], 0, s[14:15]
	s_mov_b32 m0, s61
	s_nop 0
	global_load_lds_dwordx4 v[2:3], off
	v_lshl_add_u64 v[2:3], v[216:217], 0, s[14:15]
	s_mov_b32 m0, s62
	s_nop 0
	global_load_lds_dwordx4 v[2:3], off
	s_waitcnt vmcnt(8)
	s_waitcnt lgkmcnt(0)
	s_cbranch_vccnz .Lsegskip_3
	s_setprio 1
	s_barrier
	v_mfma_f32_16x16x32_bf16 v[56:59], v[148:151], v[188:191], v[56:59]
	v_mfma_f32_16x16x32_bf16 v[52:55], v[156:159], v[188:191], v[52:55]
	v_mfma_f32_16x16x32_bf16 v[40:43], v[148:151], v[180:183], v[40:43]
	v_mfma_f32_16x16x32_bf16 v[36:39], v[156:159], v[180:183], v[36:39]
	v_mfma_f32_16x16x32_bf16 v[24:27], v[148:151], v[172:175], v[24:27]
	v_mfma_f32_16x16x32_bf16 v[20:23], v[156:159], v[172:175], v[20:23]
	v_mfma_f32_16x16x32_bf16 v[8:11], v[148:151], v[164:167], v[8:11]
	v_mfma_f32_16x16x32_bf16 v[2:5], v[156:159], v[164:167], v[4:7]
	v_mfma_f32_16x16x32_bf16 v[56:59], v[152:155], v[192:195], v[56:59]
	v_mfma_f32_16x16x32_bf16 v[52:55], v[160:163], v[192:195], v[52:55]
	v_mfma_f32_16x16x32_bf16 v[40:43], v[152:155], v[184:187], v[40:43]
	v_mfma_f32_16x16x32_bf16 v[36:39], v[160:163], v[184:187], v[36:39]
	v_mfma_f32_16x16x32_bf16 v[24:27], v[152:155], v[176:179], v[24:27]
	v_mfma_f32_16x16x32_bf16 v[20:23], v[160:163], v[176:179], v[20:23]
	v_mfma_f32_16x16x32_bf16 v[8:11], v[152:155], v[168:171], v[8:11]
	v_mfma_f32_16x16x32_bf16 v[4:7], v[160:163], v[168:171], v[2:5]
	v_mfma_f32_16x16x32_bf16 v[64:67], v[132:135], v[188:191], v[64:67]
	v_mfma_f32_16x16x32_bf16 v[60:63], v[140:143], v[188:191], v[60:63]
	v_mfma_f32_16x16x32_bf16 v[48:51], v[132:135], v[180:183], v[48:51]
	v_mfma_f32_16x16x32_bf16 v[44:47], v[140:143], v[180:183], v[44:47]
	v_mfma_f32_16x16x32_bf16 v[32:35], v[132:135], v[172:175], v[32:35]
	v_mfma_f32_16x16x32_bf16 v[28:31], v[140:143], v[172:175], v[28:31]
	v_mfma_f32_16x16x32_bf16 v[16:19], v[132:135], v[164:167], v[16:19]
	v_mfma_f32_16x16x32_bf16 v[12:15], v[140:143], v[164:167], v[12:15]
	v_mfma_f32_16x16x32_bf16 v[64:67], v[136:139], v[192:195], v[64:67]
	v_mfma_f32_16x16x32_bf16 v[60:63], v[144:147], v[192:195], v[60:63]
	v_mfma_f32_16x16x32_bf16 v[48:51], v[136:139], v[184:187], v[48:51]
	v_mfma_f32_16x16x32_bf16 v[44:47], v[144:147], v[184:187], v[44:47]
	v_mfma_f32_16x16x32_bf16 v[32:35], v[136:139], v[176:179], v[32:35]
	v_mfma_f32_16x16x32_bf16 v[28:31], v[144:147], v[176:179], v[28:31]
	v_mfma_f32_16x16x32_bf16 v[16:19], v[136:139], v[168:171], v[16:19]
	v_mfma_f32_16x16x32_bf16 v[12:15], v[144:147], v[168:171], v[12:15]
	s_barrier
	s_setprio 0
	s_branch .Lsegback_3

.LBB0_1137:
	ds_read_b128 v[144:147], v151
	ds_read_b128 v[156:159], v151 offset:1024
	ds_read_b128 v[160:163], v151 offset:2048
	ds_read_b128 v[164:167], v151 offset:3072
	ds_read_b128 v[168:171], v152
	ds_read_b128 v[172:175], v152 offset:1024
	ds_read_b128 v[176:179], v152 offset:2048
	ds_read_b128 v[180:183], v152 offset:3072
	s_add_u32 s34, s30, 0x100
	s_addc_u32 s35, s31, 0
	s_cmpk_eq_i32 s66, 0x54
	s_cselect_b32 s49, s11, s35
	s_cselect_b32 s48, s10, s34
	s_cselect_b32 s37, s27, s47
	s_cselect_b32 s36, s26, s46
	v_lshl_add_u64 v[216:217], s[30:31], 0, v[138:139]
	s_add_i32 m0, s53, 0xc000
	ds_read_b128 v[184:187], v153
	ds_read_b128 v[188:191], v153 offset:1024
	ds_read_b128 v[192:195], v153 offset:2048
	ds_read_b128 v[196:199], v153 offset:3072
	ds_read_b128 v[200:203], v153 offset:4096
	ds_read_b128 v[204:207], v153 offset:5120
	ds_read_b128 v[208:211], v153 offset:6144
	ds_read_b128 v[212:215], v153 offset:7168
	global_load_lds_dwordx4 v[216:217], off
	v_lshl_add_u64 v[216:217], s[30:31], 0, v[136:137]
	s_add_i32 m0, s53, 0xe000
	s_nop 0
	global_load_lds_dwordx4 v[216:217], off
	s_waitcnt vmcnt(8)
	s_waitcnt lgkmcnt(0)
	s_setprio 1
	s_barrier
	v_mfma_f32_16x16x32_bf16 v[124:127], v[144:147], v[184:187], v[124:127]
	v_mfma_f32_16x16x32_bf16 v[120:123], v[160:163], v[184:187], v[120:123]
	v_mfma_f32_16x16x32_bf16 v[108:111], v[144:147], v[192:195], v[108:111]
	v_mfma_f32_16x16x32_bf16 v[104:107], v[160:163], v[192:195], v[104:107]
	v_mfma_f32_16x16x32_bf16 v[92:95], v[144:147], v[200:203], v[92:95]
	v_mfma_f32_16x16x32_bf16 v[88:91], v[160:163], v[200:203], v[88:91]
	v_mfma_f32_16x16x32_bf16 v[76:79], v[144:147], v[208:211], v[76:79]
	v_mfma_f32_16x16x32_bf16 v[72:75], v[160:163], v[208:211], v[72:75]
	v_mfma_f32_16x16x32_bf16 v[124:127], v[156:159], v[188:191], v[124:127]
	v_mfma_f32_16x16x32_bf16 v[120:123], v[164:167], v[188:191], v[120:123]
	v_mfma_f32_16x16x32_bf16 v[108:111], v[156:159], v[196:199], v[108:111]
	v_mfma_f32_16x16x32_bf16 v[104:107], v[164:167], v[196:199], v[104:107]
	v_mfma_f32_16x16x32_bf16 v[92:95], v[156:159], v[204:207], v[92:95]
	v_mfma_f32_16x16x32_bf16 v[88:91], v[164:167], v[204:207], v[88:91]
	v_mfma_f32_16x16x32_bf16 v[76:79], v[156:159], v[212:215], v[76:79]
	v_mfma_f32_16x16x32_bf16 v[72:75], v[164:167], v[212:215], v[72:75]
	v_mfma_f32_16x16x32_bf16 v[116:119], v[168:171], v[184:187], v[116:119]
	v_mfma_f32_16x16x32_bf16 v[112:115], v[176:179], v[184:187], v[112:115]
	v_mfma_f32_16x16x32_bf16 v[100:103], v[168:171], v[192:195], v[100:103]
	v_mfma_f32_16x16x32_bf16 v[96:99], v[176:179], v[192:195], v[96:99]
	v_mfma_f32_16x16x32_bf16 v[84:87], v[168:171], v[200:203], v[84:87]
	v_mfma_f32_16x16x32_bf16 v[80:83], v[176:179], v[200:203], v[80:83]
	v_mfma_f32_16x16x32_bf16 v[68:71], v[168:171], v[208:211], v[68:71]
	v_mfma_f32_16x16x32_bf16 v[64:67], v[176:179], v[208:211], v[64:67]
	v_mfma_f32_16x16x32_bf16 v[116:119], v[172:175], v[188:191], v[116:119]
	v_mfma_f32_16x16x32_bf16 v[112:115], v[180:183], v[188:191], v[112:115]
	v_mfma_f32_16x16x32_bf16 v[100:103], v[172:175], v[196:199], v[100:103]
	v_mfma_f32_16x16x32_bf16 v[96:99], v[180:183], v[196:199], v[96:99]
	v_mfma_f32_16x16x32_bf16 v[84:87], v[172:175], v[204:207], v[84:87]
	v_mfma_f32_16x16x32_bf16 v[80:83], v[180:183], v[204:207], v[80:83]
	v_mfma_f32_16x16x32_bf16 v[68:71], v[172:175], v[212:215], v[68:71]
	v_mfma_f32_16x16x32_bf16 v[64:67], v[180:183], v[212:215], v[64:67]
	s_barrier
	s_setprio 0
	s_add_i32 s30, s60, s52
	v_lshl_add_u64 v[216:217], s[36:37], 0, v[130:131]
	s_mov_b32 m0, s30
	ds_read_b128 v[184:187], v153 offset:16384
	ds_read_b128 v[188:191], v153 offset:17408
	ds_read_b128 v[192:195], v153 offset:18432
	ds_read_b128 v[196:199], v153 offset:19456
	ds_read_b128 v[200:203], v153 offset:20480
	ds_read_b128 v[204:207], v153 offset:21504
	ds_read_b128 v[208:211], v153 offset:22528
	ds_read_b128 v[212:215], v153 offset:23552
	global_load_lds_dwordx4 v[216:217], off
	s_add_i32 m0, s30, 0x2000
	s_add_u32 s30, s36, 0x160000
	v_lshl_add_u64 v[218:219], s[36:37], 0, v[134:135]
	s_addc_u32 s31, s37, 0
	s_add_i32 s67, s61, s52
	global_load_lds_dwordx4 v[218:219], off
	v_lshl_add_u64 v[220:221], s[30:31], 0, v[130:131]
	s_mov_b32 m0, s67
	v_lshl_add_u64 v[222:223], s[48:49], 0, v[132:133]
	global_load_lds_dwordx4 v[220:221], off
	v_lshl_add_u64 v[220:221], s[30:31], 0, v[134:135]
	s_add_i32 m0, s67, 0x2000
	s_nop 0
	global_load_lds_dwordx4 v[220:221], off
	v_lshl_add_u64 v[220:221], s[48:49], 0, v[128:129]
	s_mov_b32 m0, s53
	s_nop 0
	global_load_lds_dwordx4 v[220:221], off
	s_mov_b32 m0, s54
	s_nop 0
	global_load_lds_dwordx4 v[222:223], off
	s_waitcnt vmcnt(8)
	s_waitcnt lgkmcnt(0)
	s_setprio 1
	s_barrier
	v_mfma_f32_16x16x32_bf16 v[60:63], v[144:147], v[184:187], v[60:63]
	v_mfma_f32_16x16x32_bf16 v[56:59], v[160:163], v[184:187], v[56:59]
	v_mfma_f32_16x16x32_bf16 v[44:47], v[144:147], v[192:195], v[44:47]
	v_mfma_f32_16x16x32_bf16 v[40:43], v[160:163], v[192:195], v[40:43]
	v_mfma_f32_16x16x32_bf16 v[28:31], v[144:147], v[200:203], v[28:31]
	v_mfma_f32_16x16x32_bf16 v[24:27], v[160:163], v[200:203], v[24:27]
	v_mfma_f32_16x16x32_bf16 v[12:15], v[144:147], v[208:211], v[12:15]
	v_mfma_f32_16x16x32_bf16 v[8:11], v[160:163], v[208:211], v[8:11]
	v_mfma_f32_16x16x32_bf16 v[60:63], v[156:159], v[188:191], v[60:63]
	v_mfma_f32_16x16x32_bf16 v[56:59], v[164:167], v[188:191], v[56:59]
	v_mfma_f32_16x16x32_bf16 v[44:47], v[156:159], v[196:199], v[44:47]
	v_mfma_f32_16x16x32_bf16 v[40:43], v[164:167], v[196:199], v[40:43]
	v_mfma_f32_16x16x32_bf16 v[28:31], v[156:159], v[204:207], v[28:31]
	v_mfma_f32_16x16x32_bf16 v[24:27], v[164:167], v[204:207], v[24:27]
	v_mfma_f32_16x16x32_bf16 v[12:15], v[156:159], v[212:215], v[12:15]
	v_mfma_f32_16x16x32_bf16 v[8:11], v[164:167], v[212:215], v[8:11]
	v_mfma_f32_16x16x32_bf16 v[52:55], v[168:171], v[184:187], v[52:55]
	v_mfma_f32_16x16x32_bf16 v[48:51], v[176:179], v[184:187], v[48:51]
	v_mfma_f32_16x16x32_bf16 v[36:39], v[168:171], v[192:195], v[36:39]
	v_mfma_f32_16x16x32_bf16 v[32:35], v[176:179], v[192:195], v[32:35]
	v_mfma_f32_16x16x32_bf16 v[20:23], v[168:171], v[200:203], v[20:23]
	v_mfma_f32_16x16x32_bf16 v[16:19], v[176:179], v[200:203], v[16:19]
	v_mfma_f32_16x16x32_bf16 v[4:7], v[168:171], v[208:211], v[4:7]
	v_mfma_f32_16x16x32_bf16 v[0:3], v[176:179], v[208:211], v[0:3]
	v_mfma_f32_16x16x32_bf16 v[52:55], v[172:175], v[188:191], v[52:55]
	v_mfma_f32_16x16x32_bf16 v[48:51], v[180:183], v[188:191], v[48:51]
	v_mfma_f32_16x16x32_bf16 v[36:39], v[172:175], v[196:199], v[36:39]
	v_mfma_f32_16x16x32_bf16 v[32:35], v[180:183], v[196:199], v[32:35]
	v_mfma_f32_16x16x32_bf16 v[20:23], v[172:175], v[204:207], v[20:23]
	v_mfma_f32_16x16x32_bf16 v[16:19], v[180:183], v[204:207], v[16:19]
	v_mfma_f32_16x16x32_bf16 v[4:7], v[172:175], v[212:215], v[4:7]
	v_mfma_f32_16x16x32_bf16 v[0:3], v[180:183], v[212:215], v[0:3]
	s_barrier
	s_setprio 0
	s_add_i32 s67, 0, 0x18000
	v_add_u32_e32 v155, s67, v149
	s_add_i32 s68, 0, 0x1c000
	ds_read_b128 v[144:147], v155
	ds_read_b128 v[156:159], v155 offset:1024
	ds_read_b128 v[160:163], v155 offset:2048
	ds_read_b128 v[164:167], v155 offset:3072
	v_add_u32_e32 v155, s68, v149
	ds_read_b128 v[168:171], v155
	ds_read_b128 v[172:175], v155 offset:1024
	ds_read_b128 v[176:179], v155 offset:2048
	ds_read_b128 v[180:183], v155 offset:3072
	s_add_u32 s30, s48, 0x160000
	s_addc_u32 s31, s49, 0
	s_mov_b32 m0, s55
	v_lshl_add_u64 v[224:225], s[30:31], 0, v[128:129]
	ds_read_b128 v[184:187], v153 offset:32768
	ds_read_b128 v[188:191], v153 offset:33792
	ds_read_b128 v[192:195], v153 offset:34816
	ds_read_b128 v[196:199], v153 offset:35840
	ds_read_b128 v[200:203], v153 offset:36864
	ds_read_b128 v[204:207], v153 offset:37888
	ds_read_b128 v[208:211], v153 offset:38912
	ds_read_b128 v[212:215], v153 offset:39936
	global_load_lds_dwordx4 v[224:225], off
	v_lshl_add_u64 v[224:225], s[30:31], 0, v[132:133]
	s_mov_b32 m0, s56
	s_nop 0
	global_load_lds_dwordx4 v[224:225], off
	s_waitcnt vmcnt(8)
	s_waitcnt lgkmcnt(0)
	s_setprio 1
	s_barrier
	v_mfma_f32_16x16x32_bf16 v[124:127], v[144:147], v[184:187], v[124:127]
	v_mfma_f32_16x16x32_bf16 v[120:123], v[160:163], v[184:187], v[120:123]
	v_mfma_f32_16x16x32_bf16 v[108:111], v[144:147], v[192:195], v[108:111]
	v_mfma_f32_16x16x32_bf16 v[104:107], v[160:163], v[192:195], v[104:107]
	v_mfma_f32_16x16x32_bf16 v[92:95], v[144:147], v[200:203], v[92:95]
	v_mfma_f32_16x16x32_bf16 v[88:91], v[160:163], v[200:203], v[88:91]
	v_mfma_f32_16x16x32_bf16 v[76:79], v[144:147], v[208:211], v[76:79]
	v_mfma_f32_16x16x32_bf16 v[72:75], v[160:163], v[208:211], v[72:75]
	v_mfma_f32_16x16x32_bf16 v[124:127], v[156:159], v[188:191], v[124:127]
	v_mfma_f32_16x16x32_bf16 v[120:123], v[164:167], v[188:191], v[120:123]
	v_mfma_f32_16x16x32_bf16 v[108:111], v[156:159], v[196:199], v[108:111]
	v_mfma_f32_16x16x32_bf16 v[104:107], v[164:167], v[196:199], v[104:107]
	v_mfma_f32_16x16x32_bf16 v[92:95], v[156:159], v[204:207], v[92:95]
	v_mfma_f32_16x16x32_bf16 v[88:91], v[164:167], v[204:207], v[88:91]
	v_mfma_f32_16x16x32_bf16 v[76:79], v[156:159], v[212:215], v[76:79]
	v_mfma_f32_16x16x32_bf16 v[72:75], v[164:167], v[212:215], v[72:75]
	v_mfma_f32_16x16x32_bf16 v[116:119], v[168:171], v[184:187], v[116:119]
	v_mfma_f32_16x16x32_bf16 v[112:115], v[176:179], v[184:187], v[112:115]
	v_mfma_f32_16x16x32_bf16 v[100:103], v[168:171], v[192:195], v[100:103]
	v_mfma_f32_16x16x32_bf16 v[96:99], v[176:179], v[192:195], v[96:99]
	v_mfma_f32_16x16x32_bf16 v[84:87], v[168:171], v[200:203], v[84:87]
	v_mfma_f32_16x16x32_bf16 v[80:83], v[176:179], v[200:203], v[80:83]
	v_mfma_f32_16x16x32_bf16 v[68:71], v[168:171], v[208:211], v[68:71]
	v_mfma_f32_16x16x32_bf16 v[64:67], v[176:179], v[208:211], v[64:67]
	v_mfma_f32_16x16x32_bf16 v[116:119], v[172:175], v[188:191], v[116:119]
	v_mfma_f32_16x16x32_bf16 v[112:115], v[180:183], v[188:191], v[112:115]
	v_mfma_f32_16x16x32_bf16 v[100:103], v[172:175], v[196:199], v[100:103]
	v_mfma_f32_16x16x32_bf16 v[96:99], v[180:183], v[196:199], v[96:99]
	v_mfma_f32_16x16x32_bf16 v[84:87], v[172:175], v[204:207], v[84:87]
	v_mfma_f32_16x16x32_bf16 v[80:83], v[180:183], v[204:207], v[80:83]
	v_mfma_f32_16x16x32_bf16 v[68:71], v[172:175], v[212:215], v[68:71]
	v_mfma_f32_16x16x32_bf16 v[64:67], v[180:183], v[212:215], v[64:67]
	s_barrier
	s_setprio 0
	s_add_i32 s30, s67, s52
	v_lshl_add_u64 v[216:217], v[216:217], 0, s[22:23]
	s_mov_b32 m0, s30
	ds_read_b128 v[184:187], v153 offset:49152
	ds_read_b128 v[188:191], v153 offset:50176
	ds_read_b128 v[192:195], v153 offset:51200
	ds_read_b128 v[196:199], v153 offset:52224
	ds_read_b128 v[200:203], v153 offset:53248
	ds_read_b128 v[204:207], v153 offset:54272
	ds_read_b128 v[208:211], v153 offset:55296
	ds_read_b128 v[212:215], v153 offset:56320
	global_load_lds_dwordx4 v[216:217], off
	s_add_i32 m0, s30, 0x2000
	s_add_u32 s30, s36, 0x160080
	v_lshl_add_u64 v[216:217], v[218:219], 0, s[22:23]
	s_addc_u32 s31, s37, 0
	s_add_i32 s36, s68, s52
	global_load_lds_dwordx4 v[216:217], off
	v_lshl_add_u64 v[216:217], s[30:31], 0, v[130:131]
	s_mov_b32 m0, s36
	s_nop 0
	global_load_lds_dwordx4 v[216:217], off
	v_lshl_add_u64 v[216:217], s[30:31], 0, v[134:135]
	s_add_i32 m0, s36, 0x2000
	s_nop 0
	global_load_lds_dwordx4 v[216:217], off
	v_lshl_add_u64 v[216:217], v[220:221], 0, s[22:23]
	s_mov_b32 m0, s58
	s_nop 0
	global_load_lds_dwordx4 v[216:217], off
	v_lshl_add_u64 v[216:217], v[222:223], 0, s[22:23]
	s_mov_b32 m0, s59
	s_nop 0
	global_load_lds_dwordx4 v[216:217], off
	s_waitcnt vmcnt(8)
	s_waitcnt lgkmcnt(0)
	s_setprio 1
	s_barrier
	v_mfma_f32_16x16x32_bf16 v[60:63], v[144:147], v[184:187], v[60:63]
	v_mfma_f32_16x16x32_bf16 v[56:59], v[160:163], v[184:187], v[56:59]
	v_mfma_f32_16x16x32_bf16 v[44:47], v[144:147], v[192:195], v[44:47]
	v_mfma_f32_16x16x32_bf16 v[40:43], v[160:163], v[192:195], v[40:43]
	v_mfma_f32_16x16x32_bf16 v[28:31], v[144:147], v[200:203], v[28:31]
	v_mfma_f32_16x16x32_bf16 v[24:27], v[160:163], v[200:203], v[24:27]
	v_mfma_f32_16x16x32_bf16 v[12:15], v[144:147], v[208:211], v[12:15]
	v_mfma_f32_16x16x32_bf16 v[8:11], v[160:163], v[208:211], v[8:11]
	v_mfma_f32_16x16x32_bf16 v[60:63], v[156:159], v[188:191], v[60:63]
	v_mfma_f32_16x16x32_bf16 v[56:59], v[164:167], v[188:191], v[56:59]
	v_mfma_f32_16x16x32_bf16 v[44:47], v[156:159], v[196:199], v[44:47]
	v_mfma_f32_16x16x32_bf16 v[40:43], v[164:167], v[196:199], v[40:43]
	v_mfma_f32_16x16x32_bf16 v[28:31], v[156:159], v[204:207], v[28:31]
	v_mfma_f32_16x16x32_bf16 v[24:27], v[164:167], v[204:207], v[24:27]
	v_mfma_f32_16x16x32_bf16 v[12:15], v[156:159], v[212:215], v[12:15]
	v_mfma_f32_16x16x32_bf16 v[8:11], v[164:167], v[212:215], v[8:11]
	v_mfma_f32_16x16x32_bf16 v[52:55], v[168:171], v[184:187], v[52:55]
	v_mfma_f32_16x16x32_bf16 v[48:51], v[176:179], v[184:187], v[48:51]
	v_mfma_f32_16x16x32_bf16 v[36:39], v[168:171], v[192:195], v[36:39]
	v_mfma_f32_16x16x32_bf16 v[32:35], v[176:179], v[192:195], v[32:35]
	v_mfma_f32_16x16x32_bf16 v[20:23], v[168:171], v[200:203], v[20:23]
	v_mfma_f32_16x16x32_bf16 v[16:19], v[176:179], v[200:203], v[16:19]
	v_mfma_f32_16x16x32_bf16 v[4:7], v[168:171], v[208:211], v[4:7]
	v_mfma_f32_16x16x32_bf16 v[0:3], v[176:179], v[208:211], v[0:3]
	v_mfma_f32_16x16x32_bf16 v[52:55], v[172:175], v[188:191], v[52:55]
	v_mfma_f32_16x16x32_bf16 v[48:51], v[180:183], v[188:191], v[48:51]
	v_mfma_f32_16x16x32_bf16 v[36:39], v[172:175], v[196:199], v[36:39]
	v_mfma_f32_16x16x32_bf16 v[32:35], v[180:183], v[196:199], v[32:35]
	v_mfma_f32_16x16x32_bf16 v[20:23], v[172:175], v[204:207], v[20:23]
	v_mfma_f32_16x16x32_bf16 v[16:19], v[180:183], v[204:207], v[16:19]
	v_mfma_f32_16x16x32_bf16 v[4:7], v[172:175], v[212:215], v[4:7]
	v_mfma_f32_16x16x32_bf16 v[0:3], v[180:183], v[212:215], v[0:3]
	s_barrier
	s_setprio 0
	s_add_i32 s66, s66, 2
	s_add_u32 s46, s46, 0x100
	s_addc_u32 s47, s47, 0
	s_cmpk_gt_u32 s66, 0x55
	s_mov_b64 s[30:31], s[34:35]
	s_cbranch_scc0 .LBB0_1137
	s_and_b64 vcc, exec, s[24:25]
	s_cbranch_vccz .LBB0_1140
	s_barrier

.LBB0_1227:
	v_add_u32_e32 v164, s56, v150
	v_add_u32_e32 v180, s57, v150
	s_add_u32 s34, s16, s30
	ds_read_b128 v[152:155], v164
	ds_read_b128 v[156:159], v164 offset:1024
	ds_read_b128 v[160:163], v164 offset:2048
	ds_read_b128 v[164:167], v164 offset:3072
	ds_read_b128 v[168:171], v180
	ds_read_b128 v[172:175], v180 offset:1024
	ds_read_b128 v[176:179], v180 offset:2048
	ds_read_b128 v[180:183], v180 offset:3072
	s_addc_u32 s35, s17, s31
	s_add_u32 s34, s34, 0x100
	s_addc_u32 s35, s35, 0
	s_add_u32 s64, s59, s30
	s_addc_u32 s65, s60, s31
	s_cmpk_eq_i32 s30, 0xf00
	s_cselect_b32 s37, s23, s35
	s_cselect_b32 s36, s61, s34
	s_cselect_b32 s35, s21, s65
	s_cselect_b32 s34, s62, s64
	v_lshl_add_u64 v[216:217], v[146:147], 0, s[30:31]
	s_add_i32 m0, s48, 0xc000
	ds_read_b128 v[184:187], v151
	ds_read_b128 v[188:191], v151 offset:1024
	ds_read_b128 v[192:195], v151 offset:2048
	ds_read_b128 v[196:199], v151 offset:3072
	ds_read_b128 v[200:203], v151 offset:4096
	ds_read_b128 v[204:207], v151 offset:5120
	ds_read_b128 v[208:211], v151 offset:6144
	ds_read_b128 v[212:215], v151 offset:7168
	global_load_lds_dwordx4 v[216:217], off
	v_lshl_add_u64 v[216:217], v[144:145], 0, s[30:31]
	s_add_i32 m0, s48, 0xe000
	s_nop 0
	global_load_lds_dwordx4 v[216:217], off
	s_waitcnt vmcnt(8)
	s_waitcnt lgkmcnt(0)
	s_setprio 1
	s_barrier
	v_mfma_f32_16x16x32_bf16 v[124:127], v[152:155], v[184:187], v[124:127]
	v_mfma_f32_16x16x32_bf16 v[120:123], v[160:163], v[184:187], v[120:123]
	v_mfma_f32_16x16x32_bf16 v[108:111], v[152:155], v[192:195], v[108:111]
	v_mfma_f32_16x16x32_bf16 v[104:107], v[160:163], v[192:195], v[104:107]
	v_mfma_f32_16x16x32_bf16 v[92:95], v[152:155], v[200:203], v[92:95]
	v_mfma_f32_16x16x32_bf16 v[88:91], v[160:163], v[200:203], v[88:91]
	v_mfma_f32_16x16x32_bf16 v[76:79], v[152:155], v[208:211], v[76:79]
	v_mfma_f32_16x16x32_bf16 v[72:75], v[160:163], v[208:211], v[72:75]
	v_mfma_f32_16x16x32_bf16 v[124:127], v[156:159], v[188:191], v[124:127]
	v_mfma_f32_16x16x32_bf16 v[120:123], v[164:167], v[188:191], v[120:123]
	v_mfma_f32_16x16x32_bf16 v[108:111], v[156:159], v[196:199], v[108:111]
	v_mfma_f32_16x16x32_bf16 v[104:107], v[164:167], v[196:199], v[104:107]
	v_mfma_f32_16x16x32_bf16 v[92:95], v[156:159], v[204:207], v[92:95]
	v_mfma_f32_16x16x32_bf16 v[88:91], v[164:167], v[204:207], v[88:91]
	v_mfma_f32_16x16x32_bf16 v[76:79], v[156:159], v[212:215], v[76:79]
	v_mfma_f32_16x16x32_bf16 v[72:75], v[164:167], v[212:215], v[72:75]
	v_mfma_f32_16x16x32_bf16 v[116:119], v[168:171], v[184:187], v[116:119]
	v_mfma_f32_16x16x32_bf16 v[112:115], v[176:179], v[184:187], v[112:115]
	v_mfma_f32_16x16x32_bf16 v[100:103], v[168:171], v[192:195], v[100:103]
	v_mfma_f32_16x16x32_bf16 v[96:99], v[176:179], v[192:195], v[96:99]
	v_mfma_f32_16x16x32_bf16 v[84:87], v[168:171], v[200:203], v[84:87]
	v_mfma_f32_16x16x32_bf16 v[80:83], v[176:179], v[200:203], v[80:83]
	v_mfma_f32_16x16x32_bf16 v[68:71], v[168:171], v[208:211], v[68:71]
	v_mfma_f32_16x16x32_bf16 v[64:67], v[176:179], v[208:211], v[64:67]
	v_mfma_f32_16x16x32_bf16 v[116:119], v[172:175], v[188:191], v[116:119]
	v_mfma_f32_16x16x32_bf16 v[112:115], v[180:183], v[188:191], v[112:115]
	v_mfma_f32_16x16x32_bf16 v[100:103], v[172:175], v[196:199], v[100:103]
	v_mfma_f32_16x16x32_bf16 v[96:99], v[180:183], v[196:199], v[96:99]
	v_mfma_f32_16x16x32_bf16 v[84:87], v[172:175], v[204:207], v[84:87]
	v_mfma_f32_16x16x32_bf16 v[80:83], v[180:183], v[204:207], v[80:83]
	v_mfma_f32_16x16x32_bf16 v[68:71], v[172:175], v[212:215], v[68:71]
	v_mfma_f32_16x16x32_bf16 v[64:67], v[180:183], v[212:215], v[64:67]
	s_barrier
	s_setprio 0
	s_add_i32 s64, s56, s47
	v_lshl_add_u64 v[216:217], s[34:35], 0, v[130:131]
	s_mov_b32 m0, s64
	ds_read_b128 v[184:187], v151 offset:16384
	ds_read_b128 v[188:191], v151 offset:17408
	ds_read_b128 v[192:195], v151 offset:18432
	ds_read_b128 v[196:199], v151 offset:19456
	ds_read_b128 v[200:203], v151 offset:20480
	ds_read_b128 v[204:207], v151 offset:21504
	ds_read_b128 v[208:211], v151 offset:22528
	ds_read_b128 v[212:215], v151 offset:23552
	global_load_lds_dwordx4 v[216:217], off
	s_add_i32 m0, s64, 0x2000
	s_add_u32 s64, s34, 0x80000
	v_lshl_add_u64 v[218:219], s[34:35], 0, v[134:135]
	s_addc_u32 s65, s35, 0
	s_add_i32 s66, s57, s47
	global_load_lds_dwordx4 v[218:219], off
	v_lshl_add_u64 v[220:221], s[64:65], 0, v[130:131]
	s_mov_b32 m0, s66
	v_lshl_add_u64 v[222:223], s[36:37], 0, v[132:133]
	global_load_lds_dwordx4 v[220:221], off
	v_lshl_add_u64 v[220:221], s[64:65], 0, v[134:135]
	s_add_i32 m0, s66, 0x2000
	s_nop 0
	global_load_lds_dwordx4 v[220:221], off
	v_lshl_add_u64 v[220:221], s[36:37], 0, v[128:129]
	s_mov_b32 m0, s48
	s_nop 0
	global_load_lds_dwordx4 v[220:221], off
	s_mov_b32 m0, s49
	s_nop 0
	global_load_lds_dwordx4 v[222:223], off
	s_waitcnt vmcnt(8)
	s_waitcnt lgkmcnt(0)
	s_setprio 1
	s_barrier
	v_mfma_f32_16x16x32_bf16 v[60:63], v[152:155], v[184:187], v[60:63]
	v_mfma_f32_16x16x32_bf16 v[56:59], v[160:163], v[184:187], v[56:59]
	v_mfma_f32_16x16x32_bf16 v[44:47], v[152:155], v[192:195], v[44:47]
	v_mfma_f32_16x16x32_bf16 v[40:43], v[160:163], v[192:195], v[40:43]
	v_mfma_f32_16x16x32_bf16 v[28:31], v[152:155], v[200:203], v[28:31]
	v_mfma_f32_16x16x32_bf16 v[24:27], v[160:163], v[200:203], v[24:27]
	v_mfma_f32_16x16x32_bf16 v[12:15], v[152:155], v[208:211], v[12:15]
	v_mfma_f32_16x16x32_bf16 v[8:11], v[160:163], v[208:211], v[8:11]
	v_mfma_f32_16x16x32_bf16 v[60:63], v[156:159], v[188:191], v[60:63]
	v_mfma_f32_16x16x32_bf16 v[56:59], v[164:167], v[188:191], v[56:59]
	v_mfma_f32_16x16x32_bf16 v[44:47], v[156:159], v[196:199], v[44:47]
	v_mfma_f32_16x16x32_bf16 v[40:43], v[164:167], v[196:199], v[40:43]
	v_mfma_f32_16x16x32_bf16 v[28:31], v[156:159], v[204:207], v[28:31]
	v_mfma_f32_16x16x32_bf16 v[24:27], v[164:167], v[204:207], v[24:27]
	v_mfma_f32_16x16x32_bf16 v[12:15], v[156:159], v[212:215], v[12:15]
	v_mfma_f32_16x16x32_bf16 v[8:11], v[164:167], v[212:215], v[8:11]
	v_mfma_f32_16x16x32_bf16 v[52:55], v[168:171], v[184:187], v[52:55]
	v_mfma_f32_16x16x32_bf16 v[48:51], v[176:179], v[184:187], v[48:51]
	v_mfma_f32_16x16x32_bf16 v[36:39], v[168:171], v[192:195], v[36:39]
	v_mfma_f32_16x16x32_bf16 v[32:35], v[176:179], v[192:195], v[32:35]
	v_mfma_f32_16x16x32_bf16 v[20:23], v[168:171], v[200:203], v[20:23]
	v_mfma_f32_16x16x32_bf16 v[16:19], v[176:179], v[200:203], v[16:19]
	v_mfma_f32_16x16x32_bf16 v[4:7], v[168:171], v[208:211], v[4:7]
	v_mfma_f32_16x16x32_bf16 v[0:3], v[176:179], v[208:211], v[0:3]
	v_mfma_f32_16x16x32_bf16 v[52:55], v[172:175], v[188:191], v[52:55]
	v_mfma_f32_16x16x32_bf16 v[48:51], v[180:183], v[188:191], v[48:51]
	v_mfma_f32_16x16x32_bf16 v[36:39], v[172:175], v[196:199], v[36:39]
	v_mfma_f32_16x16x32_bf16 v[32:35], v[180:183], v[196:199], v[32:35]
	v_mfma_f32_16x16x32_bf16 v[20:23], v[172:175], v[204:207], v[20:23]
	v_mfma_f32_16x16x32_bf16 v[16:19], v[180:183], v[204:207], v[16:19]
	v_mfma_f32_16x16x32_bf16 v[4:7], v[172:175], v[212:215], v[4:7]
	v_mfma_f32_16x16x32_bf16 v[0:3], v[180:183], v[212:215], v[0:3]
	s_barrier
	s_setprio 0
	s_add_i32 s64, 0, 0x18000
	s_add_i32 s65, 0, 0x1c000
	v_add_u32_e32 v164, s64, v150
	v_add_u32_e32 v180, s65, v150
	ds_read_b128 v[152:155], v164
	ds_read_b128 v[156:159], v164 offset:1024
	ds_read_b128 v[160:163], v164 offset:2048
	ds_read_b128 v[164:167], v164 offset:3072
	ds_read_b128 v[168:171], v180
	ds_read_b128 v[172:175], v180 offset:1024
	ds_read_b128 v[176:179], v180 offset:2048
	ds_read_b128 v[180:183], v180 offset:3072
	s_add_u32 s36, s36, 0x80000
	s_addc_u32 s37, s37, 0
	s_mov_b32 m0, s50
	v_lshl_add_u64 v[224:225], s[36:37], 0, v[128:129]
	ds_read_b128 v[184:187], v151 offset:32768
	ds_read_b128 v[188:191], v151 offset:33792
	ds_read_b128 v[192:195], v151 offset:34816
	ds_read_b128 v[196:199], v151 offset:35840
	ds_read_b128 v[200:203], v151 offset:36864
	ds_read_b128 v[204:207], v151 offset:37888
	ds_read_b128 v[208:211], v151 offset:38912
	ds_read_b128 v[212:215], v151 offset:39936
	global_load_lds_dwordx4 v[224:225], off
	v_lshl_add_u64 v[224:225], s[36:37], 0, v[132:133]
	s_mov_b32 m0, s51
	s_nop 0
	global_load_lds_dwordx4 v[224:225], off
	s_waitcnt vmcnt(8)
	s_waitcnt lgkmcnt(0)
	s_setprio 1
	s_barrier
	v_mfma_f32_16x16x32_bf16 v[124:127], v[152:155], v[184:187], v[124:127]
	v_mfma_f32_16x16x32_bf16 v[120:123], v[160:163], v[184:187], v[120:123]
	v_mfma_f32_16x16x32_bf16 v[108:111], v[152:155], v[192:195], v[108:111]
	v_mfma_f32_16x16x32_bf16 v[104:107], v[160:163], v[192:195], v[104:107]
	v_mfma_f32_16x16x32_bf16 v[92:95], v[152:155], v[200:203], v[92:95]
	v_mfma_f32_16x16x32_bf16 v[88:91], v[160:163], v[200:203], v[88:91]
	v_mfma_f32_16x16x32_bf16 v[76:79], v[152:155], v[208:211], v[76:79]
	v_mfma_f32_16x16x32_bf16 v[72:75], v[160:163], v[208:211], v[72:75]
	v_mfma_f32_16x16x32_bf16 v[124:127], v[156:159], v[188:191], v[124:127]
	v_mfma_f32_16x16x32_bf16 v[120:123], v[164:167], v[188:191], v[120:123]
	v_mfma_f32_16x16x32_bf16 v[108:111], v[156:159], v[196:199], v[108:111]
	v_mfma_f32_16x16x32_bf16 v[104:107], v[164:167], v[196:199], v[104:107]
	v_mfma_f32_16x16x32_bf16 v[92:95], v[156:159], v[204:207], v[92:95]
	v_mfma_f32_16x16x32_bf16 v[88:91], v[164:167], v[204:207], v[88:91]
	v_mfma_f32_16x16x32_bf16 v[76:79], v[156:159], v[212:215], v[76:79]
	v_mfma_f32_16x16x32_bf16 v[72:75], v[164:167], v[212:215], v[72:75]
	v_mfma_f32_16x16x32_bf16 v[116:119], v[168:171], v[184:187], v[116:119]
	v_mfma_f32_16x16x32_bf16 v[112:115], v[176:179], v[184:187], v[112:115]
	v_mfma_f32_16x16x32_bf16 v[100:103], v[168:171], v[192:195], v[100:103]
	v_mfma_f32_16x16x32_bf16 v[96:99], v[176:179], v[192:195], v[96:99]
	v_mfma_f32_16x16x32_bf16 v[84:87], v[168:171], v[200:203], v[84:87]
	v_mfma_f32_16x16x32_bf16 v[80:83], v[176:179], v[200:203], v[80:83]
	v_mfma_f32_16x16x32_bf16 v[68:71], v[168:171], v[208:211], v[68:71]
	v_mfma_f32_16x16x32_bf16 v[64:67], v[176:179], v[208:211], v[64:67]
	v_mfma_f32_16x16x32_bf16 v[116:119], v[172:175], v[188:191], v[116:119]
	v_mfma_f32_16x16x32_bf16 v[112:115], v[180:183], v[188:191], v[112:115]
	v_mfma_f32_16x16x32_bf16 v[100:103], v[172:175], v[196:199], v[100:103]
	v_mfma_f32_16x16x32_bf16 v[96:99], v[180:183], v[196:199], v[96:99]
	v_mfma_f32_16x16x32_bf16 v[84:87], v[172:175], v[204:207], v[84:87]
	v_mfma_f32_16x16x32_bf16 v[80:83], v[180:183], v[204:207], v[80:83]
	v_mfma_f32_16x16x32_bf16 v[68:71], v[172:175], v[212:215], v[68:71]
	v_mfma_f32_16x16x32_bf16 v[64:67], v[180:183], v[212:215], v[64:67]
	s_barrier
	s_setprio 0
	s_add_i32 s36, s64, s47
	v_lshl_add_u64 v[216:217], v[216:217], 0, s[18:19]
	s_mov_b32 m0, s36
	ds_read_b128 v[184:187], v151 offset:49152
	ds_read_b128 v[188:191], v151 offset:50176
	ds_read_b128 v[192:195], v151 offset:51200
	ds_read_b128 v[196:199], v151 offset:52224
	ds_read_b128 v[200:203], v151 offset:53248
	ds_read_b128 v[204:207], v151 offset:54272
	ds_read_b128 v[208:211], v151 offset:55296
	ds_read_b128 v[212:215], v151 offset:56320
	global_load_lds_dwordx4 v[216:217], off
	s_add_i32 m0, s36, 0x2000
	s_add_u32 s34, s34, 0x80080
	v_lshl_add_u64 v[216:217], v[218:219], 0, s[18:19]
	s_addc_u32 s35, s35, 0
	s_add_i32 s36, s65, s47
	global_load_lds_dwordx4 v[216:217], off
	v_lshl_add_u64 v[216:217], s[34:35], 0, v[130:131]
	s_mov_b32 m0, s36
	s_nop 0
	global_load_lds_dwordx4 v[216:217], off
	v_lshl_add_u64 v[216:217], s[34:35], 0, v[134:135]
	s_add_i32 m0, s36, 0x2000
	s_nop 0
	global_load_lds_dwordx4 v[216:217], off
	v_lshl_add_u64 v[216:217], v[220:221], 0, s[18:19]
	s_mov_b32 m0, s54
	s_nop 0
	global_load_lds_dwordx4 v[216:217], off
	v_lshl_add_u64 v[216:217], v[222:223], 0, s[18:19]
	s_mov_b32 m0, s55
	s_nop 0
	global_load_lds_dwordx4 v[216:217], off
	s_waitcnt vmcnt(8)
	s_waitcnt lgkmcnt(0)
	s_setprio 1
	s_barrier
	v_mfma_f32_16x16x32_bf16 v[60:63], v[152:155], v[184:187], v[60:63]
	v_mfma_f32_16x16x32_bf16 v[56:59], v[160:163], v[184:187], v[56:59]
	v_mfma_f32_16x16x32_bf16 v[44:47], v[152:155], v[192:195], v[44:47]
	v_mfma_f32_16x16x32_bf16 v[40:43], v[160:163], v[192:195], v[40:43]
	v_mfma_f32_16x16x32_bf16 v[28:31], v[152:155], v[200:203], v[28:31]
	v_mfma_f32_16x16x32_bf16 v[24:27], v[160:163], v[200:203], v[24:27]
	v_mfma_f32_16x16x32_bf16 v[12:15], v[152:155], v[208:211], v[12:15]
	v_mfma_f32_16x16x32_bf16 v[8:11], v[160:163], v[208:211], v[8:11]
	v_mfma_f32_16x16x32_bf16 v[60:63], v[156:159], v[188:191], v[60:63]
	v_mfma_f32_16x16x32_bf16 v[56:59], v[164:167], v[188:191], v[56:59]
	v_mfma_f32_16x16x32_bf16 v[44:47], v[156:159], v[196:199], v[44:47]
	v_mfma_f32_16x16x32_bf16 v[40:43], v[164:167], v[196:199], v[40:43]
	v_mfma_f32_16x16x32_bf16 v[28:31], v[156:159], v[204:207], v[28:31]
	v_mfma_f32_16x16x32_bf16 v[24:27], v[164:167], v[204:207], v[24:27]
	v_mfma_f32_16x16x32_bf16 v[12:15], v[156:159], v[212:215], v[12:15]
	v_mfma_f32_16x16x32_bf16 v[8:11], v[164:167], v[212:215], v[8:11]
	v_mfma_f32_16x16x32_bf16 v[52:55], v[168:171], v[184:187], v[52:55]
	v_mfma_f32_16x16x32_bf16 v[48:51], v[176:179], v[184:187], v[48:51]
	v_mfma_f32_16x16x32_bf16 v[36:39], v[168:171], v[192:195], v[36:39]
	v_mfma_f32_16x16x32_bf16 v[32:35], v[176:179], v[192:195], v[32:35]
	v_mfma_f32_16x16x32_bf16 v[20:23], v[168:171], v[200:203], v[20:23]
	v_mfma_f32_16x16x32_bf16 v[16:19], v[176:179], v[200:203], v[16:19]
	v_mfma_f32_16x16x32_bf16 v[4:7], v[168:171], v[208:211], v[4:7]
	v_mfma_f32_16x16x32_bf16 v[0:3], v[176:179], v[208:211], v[0:3]
	v_mfma_f32_16x16x32_bf16 v[52:55], v[172:175], v[188:191], v[52:55]
	v_mfma_f32_16x16x32_bf16 v[48:51], v[180:183], v[188:191], v[48:51]
	v_mfma_f32_16x16x32_bf16 v[36:39], v[172:175], v[196:199], v[36:39]
	v_mfma_f32_16x16x32_bf16 v[32:35], v[180:183], v[196:199], v[32:35]
	v_mfma_f32_16x16x32_bf16 v[20:23], v[172:175], v[204:207], v[20:23]
	v_mfma_f32_16x16x32_bf16 v[16:19], v[180:183], v[204:207], v[16:19]
	v_mfma_f32_16x16x32_bf16 v[4:7], v[172:175], v[212:215], v[4:7]
	v_mfma_f32_16x16x32_bf16 v[0:3], v[180:183], v[212:215], v[0:3]
	s_barrier
	s_setprio 0
	s_add_i32 s63, s63, 2
	s_add_u32 s30, s30, 0x100
	s_addc_u32 s31, s31, 0
	s_cmp_gt_u32 s63, 29
	s_cbranch_scc0 .LBB0_1227
	s_add_u32 s30, s59, 0xffffff00
	s_addc_u32 s31, s60, -1
	s_andn2_b64 vcc, exec, s[4:5]
	s_cbranch_vccnz .LBB0_1230
	v_mov_b32_e32 v0, 0
	s_mov_b32 s15, s20
	s_mov_b32 s14, s22
	s_mov_b64 s[16:17], s[26:27]
	s_mov_b32 s53, s58
	v_mov_b32_e32 v1, v0
	v_pk_mov_b32 v[2:3], 0, 0
	v_pk_mov_b32 v[4:5], 0, 0
	v_pk_mov_b32 v[6:7], 0, 0
	v_pk_mov_b32 v[16:17], 0, 0
	v_pk_mov_b32 v[18:19], 0, 0
	v_pk_mov_b32 v[20:21], 0, 0
	v_pk_mov_b32 v[22:23], 0, 0
	v_pk_mov_b32 v[32:33], 0, 0
	v_pk_mov_b32 v[34:35], 0, 0
	v_pk_mov_b32 v[36:37], 0, 0
	v_pk_mov_b32 v[38:39], 0, 0
	v_pk_mov_b32 v[48:49], 0, 0
	v_pk_mov_b32 v[50:51], 0, 0
	v_pk_mov_b32 v[52:53], 0, 0
	v_pk_mov_b32 v[54:55], 0, 0
	v_pk_mov_b32 v[8:9], 0, 0
	v_pk_mov_b32 v[10:11], 0, 0
	v_pk_mov_b32 v[12:13], 0, 0
	v_pk_mov_b32 v[14:15], 0, 0
	v_pk_mov_b32 v[24:25], 0, 0
	v_pk_mov_b32 v[26:27], 0, 0
	v_pk_mov_b32 v[28:29], 0, 0
	v_pk_mov_b32 v[30:31], 0, 0
	v_pk_mov_b32 v[40:41], 0, 0
	v_pk_mov_b32 v[42:43], 0, 0
	v_pk_mov_b32 v[44:45], 0, 0
	v_pk_mov_b32 v[46:47], 0, 0
	v_pk_mov_b32 v[56:57], 0, 0
	v_pk_mov_b32 v[58:59], 0, 0
	v_pk_mov_b32 v[60:61], 0, 0
	v_pk_mov_b32 v[62:63], 0, 0
	v_pk_mov_b32 v[64:65], 0, 0
	v_pk_mov_b32 v[66:67], 0, 0
	v_pk_mov_b32 v[68:69], 0, 0
	v_pk_mov_b32 v[70:71], 0, 0
	v_pk_mov_b32 v[80:81], 0, 0
	v_pk_mov_b32 v[82:83], 0, 0
	v_pk_mov_b32 v[84:85], 0, 0
	v_pk_mov_b32 v[86:87], 0, 0
	v_pk_mov_b32 v[96:97], 0, 0
	v_pk_mov_b32 v[98:99], 0, 0
	v_pk_mov_b32 v[100:101], 0, 0
	v_pk_mov_b32 v[102:103], 0, 0
	v_pk_mov_b32 v[112:113], 0, 0
	v_pk_mov_b32 v[114:115], 0, 0
	v_pk_mov_b32 v[116:117], 0, 0
	v_pk_mov_b32 v[118:119], 0, 0
	v_pk_mov_b32 v[72:73], 0, 0
	v_pk_mov_b32 v[74:75], 0, 0
	v_pk_mov_b32 v[76:77], 0, 0
	v_pk_mov_b32 v[78:79], 0, 0
	v_pk_mov_b32 v[88:89], 0, 0
	v_pk_mov_b32 v[90:91], 0, 0
	v_pk_mov_b32 v[92:93], 0, 0
	v_pk_mov_b32 v[94:95], 0, 0
	v_pk_mov_b32 v[104:105], 0, 0
	v_pk_mov_b32 v[106:107], 0, 0
	v_pk_mov_b32 v[108:109], 0, 0
	v_pk_mov_b32 v[110:111], 0, 0
	v_pk_mov_b32 v[120:121], 0, 0
	v_pk_mov_b32 v[122:123], 0, 0
	v_pk_mov_b32 v[124:125], 0, 0
	v_pk_mov_b32 v[126:127], 0, 0
	s_andn2_b64 vcc, exec, s[0:1]
	s_cbranch_vccnz .LBB0_1231
	s_branch .LBB0_1232
